# v12: v11s + one more saddr LDS-DMA load per loop, and the MFMA order / saddr form also in the two P8 K-loops
# speedup vs baseline: 1.0126x; 1.0020x over previous
; #define PG8_STAGE(bufoff, gbase, voff) do { _Pragma("unroll") for (int _i = 0; _i < 2; ++_i) \
;         __builtin_amdgcn_global_load_lds((const unsigned*)((const char*)(gbase) + (voff)[_i]), (PG8_LAS unsigned*)(lds + (bufoff) + ldsw + _i * 8192), 16, 0, 0); } while (0)
; #define PG8_LDA(dst, b, h) do { _Pragma("unroll") for (int m = 0; m < 4; ++m) _Pragma("unroll") for (int k = 0; k < 2; ++k) dst[m][k] = *(const PG8_LAS bf16x8*)(lds + PG8_SA(b, h) + aoff + m * 2048 + k * 1024); } while (0)
; #define PG8_LDB(dst, b, h) do { _Pragma("unroll") for (int n = 0; n < 2; ++n) _Pragma("unroll") for (int k = 0; k < 2; ++k) dst[n][k] = *(const PG8_LAS bf16x8*)(lds + PG8_SB(b, h) + boff + n * 2048 + k * 1024); } while (0)
; #define PG8_MMA(ai, bj, At, Bt) do { __builtin_amdgcn_s_setprio(1); _Pragma("unroll") for (int m = 0; m < 4; ++m) _Pragma("unroll") for (int n = 0; n < 2; ++n) _Pragma("unroll") for (int k = 0; k < 2; ++k) \
;         acc[ai][bj][m][n] = __builtin_amdgcn_mfma_f32_16x16x32_bf16(Bt[n][k], At[m][k], acc[ai][bj][m][n], 0, 0, 0); __builtin_amdgcn_s_setprio(0); } while (0)
; #define PG8_WAIT_V(n) asm volatile("s_waitcnt vmcnt(" #n ")" ::: "memory")
; #define PG8_WAIT_L(n) asm volatile("s_waitcnt lgkmcnt(" #n ")" ::: "memory")
; template <class Epi, class Sched, bool ALIGN_EPI = false, bool SP2 = false>
; __device__ __forceinline__ void gemm_phase(PG8_LAS unsigned char* lds, const Gemm g, const Sched& S, const Epi& E) {
;     ...
;         for (; t < tend; t += 2) {
;             const bool last = (t == nt - 2);
;             const char* a1 = cA + (size_t)(t + 1) * kstep;
;             const char* a2 = last ? nA : cA + (size_t)(t + 2) * kstep; const char* b2 = last ? nB : cB + (size_t)(t + 2) * kstep;
;             const char* a3 = a2 + kstep; const char* b3 = b2 + kstep;
;             if (last && has_next) S.a_ready(nxt);
;             if constexpr (SP2) {
;             PG8_LDB(B0, 0, 0); PG8_LDB(B1, 0, 1); PG8_SCHED; PG8_LDA(At, 0, 0); PG8_STAGE(PG8_SA(1, 1), a1 + hstep, voffA);
;             PG8_WAIT_V(8); PG8_WAIT_L(0); PG8_BAR; PG8_MMA(0, 0, At, B0); PG8_MMA(0, 1, At, B1); PG8_BAR; PG8_SCHED;
;             PG8_LDA(At, 0, 1); PG8_STAGE(PG8_SB(0, 0), b2, voffB); PG8_STAGE(PG8_SB(0, 1), b2 + hstep, voffB); PG8_STAGE(PG8_SA(0, 0), a2, voffA);
;             PG8_WAIT_V(8); PG8_WAIT_L(0); PG8_BAR; PG8_MMA(1, 0, At, B0); PG8_MMA(1, 1, At, B1); PG8_BAR; PG8_SCHED;
.LBB0_115:
	ds_read_b128 v[154:157], v150
	ds_read_b128 v[158:161], v150 offset:1024
	ds_read_b128 v[162:165], v150 offset:2048
	ds_read_b128 v[166:169], v150 offset:3072
	ds_read_b128 v[170:173], v151
	ds_read_b128 v[174:177], v151 offset:1024
	ds_read_b128 v[180:183], v151 offset:2048
	ds_read_b128 v[184:187], v151 offset:3072
	s_add_u32 s50, s48, 0x4000
	s_addc_u32 s51, s49, 0
	s_cmp_eq_u32 s76, 60
	s_cselect_b32 s74, s64, s50
	s_cselect_b32 s75, s25, s51
	s_cselect_b32 s72, s65, s68
	s_cselect_b32 s73, s19, s69
	s_add_u32 s50, s74, 0x8000
	s_addc_u32 s51, s75, 0
	s_sub_u32 s50, s48, 0x4000
	s_subb_u32 s51, s49, 0
	s_mov_b32 m0, s58
	s_nop 0
	global_load_lds_dwordx4 v130, s[50:51]
	s_mov_b32 m0, s59
	s_nop 0
	global_load_lds_dwordx4 v134, s[50:51]
	s_add_i32 m0, s28, 0xc000
	ds_read_b128 v[188:191], v152
	ds_read_b128 v[196:199], v152 offset:1024
	ds_read_b128 v[200:203], v152 offset:2048
	ds_read_b128 v[204:207], v152 offset:3072
	ds_read_b128 v[208:211], v152 offset:4096
	ds_read_b128 v[212:215], v152 offset:5120
	ds_read_b128 v[216:219], v152 offset:6144
	ds_read_b128 v[220:223], v152 offset:7168
	global_load_lds_dwordx4 v140, s[48:49]
	s_add_i32 m0, s28, 0xe000
	s_nop 0
	global_load_lds_dwordx4 v142, s[48:49]
	s_waitcnt vmcnt(8)
	s_waitcnt lgkmcnt(0)
	s_barrier
	s_setprio 1
	s_waitcnt lgkmcnt(0)
	v_mfma_f32_16x16x32_bf16 v[126:129], v[154:157], v[188:191], v[126:129]
	v_mfma_f32_16x16x32_bf16 v[126:129], v[158:161], v[196:199], v[126:129]
	v_mfma_f32_16x16x32_bf16 v[110:113], v[154:157], v[200:203], v[110:113]
	v_mfma_f32_16x16x32_bf16 v[110:113], v[158:161], v[204:207], v[110:113]
	v_mfma_f32_16x16x32_bf16 v[94:97], v[154:157], v[208:211], v[94:97]
	v_mfma_f32_16x16x32_bf16 v[94:97], v[158:161], v[212:215], v[94:97]
	v_mfma_f32_16x16x32_bf16 v[78:81], v[154:157], v[216:219], v[78:81]
	v_mfma_f32_16x16x32_bf16 v[78:81], v[158:161], v[220:223], v[78:81]
	v_mfma_f32_16x16x32_bf16 v[70:73], v[162:165], v[216:219], v[70:73]
	v_mfma_f32_16x16x32_bf16 v[70:73], v[166:169], v[220:223], v[70:73]
	v_mfma_f32_16x16x32_bf16 v[86:89], v[162:165], v[208:211], v[86:89]
	v_mfma_f32_16x16x32_bf16 v[86:89], v[166:169], v[212:215], v[86:89]
	v_mfma_f32_16x16x32_bf16 v[102:105], v[162:165], v[200:203], v[102:105]
	v_mfma_f32_16x16x32_bf16 v[102:105], v[166:169], v[204:207], v[102:105]
	v_mfma_f32_16x16x32_bf16 v[118:121], v[162:165], v[188:191], v[118:121]
	v_mfma_f32_16x16x32_bf16 v[118:121], v[166:169], v[196:199], v[118:121]
	s_setprio 0
	s_setprio 1
	v_mfma_f32_16x16x32_bf16 v[122:125], v[170:173], v[188:191], v[122:125]
	v_mfma_f32_16x16x32_bf16 v[122:125], v[174:177], v[196:199], v[122:125]
	v_mfma_f32_16x16x32_bf16 v[106:109], v[170:173], v[200:203], v[106:109]
	v_mfma_f32_16x16x32_bf16 v[106:109], v[174:177], v[204:207], v[106:109]
	v_mfma_f32_16x16x32_bf16 v[90:93], v[170:173], v[208:211], v[90:93]
	v_mfma_f32_16x16x32_bf16 v[90:93], v[174:177], v[212:215], v[90:93]
	v_mfma_f32_16x16x32_bf16 v[74:77], v[170:173], v[216:219], v[74:77]
	v_mfma_f32_16x16x32_bf16 v[74:77], v[174:177], v[220:223], v[74:77]
	v_mfma_f32_16x16x32_bf16 v[66:69], v[180:183], v[216:219], v[66:69]
	v_mfma_f32_16x16x32_bf16 v[66:69], v[184:187], v[220:223], v[66:69]
	v_mfma_f32_16x16x32_bf16 v[82:85], v[180:183], v[208:211], v[82:85]
	v_mfma_f32_16x16x32_bf16 v[82:85], v[184:187], v[212:215], v[82:85]
	v_mfma_f32_16x16x32_bf16 v[98:101], v[180:183], v[200:203], v[98:101]
	v_mfma_f32_16x16x32_bf16 v[98:101], v[184:187], v[204:207], v[98:101]
	v_mfma_f32_16x16x32_bf16 v[114:117], v[180:183], v[188:191], v[114:117]
	v_mfma_f32_16x16x32_bf16 v[114:117], v[184:187], v[196:199], v[114:117]
	s_setprio 0
	s_barrier
	s_add_i32 s77, s61, s3
	s_mov_b32 m0, s77
	ds_read_b128 v[188:191], v152 offset:16384
	ds_read_b128 v[196:199], v152 offset:17408
	ds_read_b128 v[200:203], v152 offset:18432
	ds_read_b128 v[204:207], v152 offset:19456
	ds_read_b128 v[208:211], v152 offset:20480
	ds_read_b128 v[212:215], v152 offset:21504
	ds_read_b128 v[216:219], v152 offset:22528
	ds_read_b128 v[220:223], v152 offset:23552
	global_load_lds_dwordx4 v132, s[72:73]
	s_add_i32 m0, s77, 0x2000
	s_add_u32 s78, s72, 0x4000
	s_addc_u32 s79, s73, 0
	s_add_i32 s77, s62, s3
	global_load_lds_dwordx4 v136, s[72:73]
	s_mov_b32 m0, s77
	s_nop 0
	global_load_lds_dwordx4 v132, s[78:79]
	s_add_i32 m0, s77, 0x2000
	s_nop 0
	global_load_lds_dwordx4 v136, s[78:79]
	s_waitcnt vmcnt(6)
	s_waitcnt lgkmcnt(0)
	s_barrier
	s_setprio 1
	s_waitcnt lgkmcnt(0)
	v_mfma_f32_16x16x32_bf16 v[62:65], v[154:157], v[188:191], v[62:65]
	v_mfma_f32_16x16x32_bf16 v[62:65], v[158:161], v[196:199], v[62:65]
	v_mfma_f32_16x16x32_bf16 v[46:49], v[154:157], v[200:203], v[46:49]
	v_mfma_f32_16x16x32_bf16 v[46:49], v[158:161], v[204:207], v[46:49]
	v_mfma_f32_16x16x32_bf16 v[30:33], v[154:157], v[208:211], v[30:33]
	v_mfma_f32_16x16x32_bf16 v[30:33], v[158:161], v[212:215], v[30:33]
	v_mfma_f32_16x16x32_bf16 v[14:17], v[154:157], v[216:219], v[14:17]
	v_mfma_f32_16x16x32_bf16 v[14:17], v[158:161], v[220:223], v[14:17]
	v_mfma_f32_16x16x32_bf16 v[6:9], v[162:165], v[216:219], v[6:9]
	v_mfma_f32_16x16x32_bf16 v[6:9], v[166:169], v[220:223], v[6:9]
	v_mfma_f32_16x16x32_bf16 v[22:25], v[162:165], v[208:211], v[22:25]
	v_mfma_f32_16x16x32_bf16 v[22:25], v[166:169], v[212:215], v[22:25]
	v_mfma_f32_16x16x32_bf16 v[38:41], v[162:165], v[200:203], v[38:41]
	v_mfma_f32_16x16x32_bf16 v[38:41], v[166:169], v[204:207], v[38:41]
	v_mfma_f32_16x16x32_bf16 v[54:57], v[162:165], v[188:191], v[54:57]
	v_mfma_f32_16x16x32_bf16 v[54:57], v[166:169], v[196:199], v[54:57]
	s_setprio 0
	s_setprio 1
	v_mfma_f32_16x16x32_bf16 v[58:61], v[170:173], v[188:191], v[58:61]
	v_mfma_f32_16x16x32_bf16 v[58:61], v[174:177], v[196:199], v[58:61]
	v_mfma_f32_16x16x32_bf16 v[42:45], v[170:173], v[200:203], v[42:45]
	v_mfma_f32_16x16x32_bf16 v[42:45], v[174:177], v[204:207], v[42:45]
	v_mfma_f32_16x16x32_bf16 v[26:29], v[170:173], v[208:211], v[26:29]
	v_mfma_f32_16x16x32_bf16 v[26:29], v[174:177], v[212:215], v[26:29]
	v_mfma_f32_16x16x32_bf16 v[10:13], v[170:173], v[216:219], v[10:13]
	v_mfma_f32_16x16x32_bf16 v[10:13], v[174:177], v[220:223], v[10:13]
	v_mfma_f32_16x16x32_bf16 v[2:5], v[180:183], v[216:219], v[2:5]
	v_mfma_f32_16x16x32_bf16 v[2:5], v[184:187], v[220:223], v[2:5]
	v_mfma_f32_16x16x32_bf16 v[18:21], v[180:183], v[208:211], v[18:21]
	v_mfma_f32_16x16x32_bf16 v[18:21], v[184:187], v[212:215], v[18:21]
	v_mfma_f32_16x16x32_bf16 v[34:37], v[180:183], v[200:203], v[34:37]
	v_mfma_f32_16x16x32_bf16 v[34:37], v[184:187], v[204:207], v[34:37]
	v_mfma_f32_16x16x32_bf16 v[50:53], v[180:183], v[188:191], v[50:53]
	v_mfma_f32_16x16x32_bf16 v[50:53], v[184:187], v[196:199], v[50:53]
	s_setprio 0
	s_barrier
; #define PG8_STAGE(bufoff, gbase, voff) do { _Pragma("unroll") for (int _i = 0; _i < 2; ++_i) \
;         __builtin_amdgcn_global_load_lds((const unsigned*)((const char*)(gbase) + (voff)[_i]), (PG8_LAS unsigned*)(lds + (bufoff) + ldsw + _i * 8192), 16, 0, 0); } while (0)
; #define PG8_LDA(dst, b, h) do { _Pragma("unroll") for (int m = 0; m < 4; ++m) _Pragma("unroll") for (int k = 0; k < 2; ++k) dst[m][k] = *(const PG8_LAS bf16x8*)(lds + PG8_SA(b, h) + aoff + m * 2048 + k * 1024); } while (0)
; #define PG8_LDB(dst, b, h) do { _Pragma("unroll") for (int n = 0; n < 2; ++n) _Pragma("unroll") for (int k = 0; k < 2; ++k) dst[n][k] = *(const PG8_LAS bf16x8*)(lds + PG8_SB(b, h) + boff + n * 2048 + k * 1024); } while (0)
; #define PG8_MMA(ai, bj, At, Bt) do { __builtin_amdgcn_s_setprio(1); _Pragma("unroll") for (int m = 0; m < 4; ++m) _Pragma("unroll") for (int n = 0; n < 2; ++n) _Pragma("unroll") for (int k = 0; k < 2; ++k) \
;         acc[ai][bj][m][n] = __builtin_amdgcn_mfma_f32_16x16x32_bf16(Bt[n][k], At[m][k], acc[ai][bj][m][n], 0, 0, 0); __builtin_amdgcn_s_setprio(0); } while (0)
; #define PG8_WAIT_V(n) asm volatile("s_waitcnt vmcnt(" #n ")" ::: "memory")
; #define PG8_WAIT_L(n) asm volatile("s_waitcnt lgkmcnt(" #n ")" ::: "memory")
; #define PG8_BAR __builtin_amdgcn_s_barrier()
; #define PG8_SCHED __builtin_amdgcn_sched_barrier(0)
; template <class Epi, class Sched, bool ALIGN_EPI = false, bool SP2 = false>
; __device__ __forceinline__ void gemm_phase(PG8_LAS unsigned char* lds, const Gemm g, const Sched& S, const Epi& E) {
;     ...
;             PG8_LDB(B0, 1, 0); PG8_LDB(B1, 1, 1); PG8_SCHED; PG8_LDA(At, 1, 0); PG8_STAGE(PG8_SA(0, 1), a2 + hstep, voffA);
;             PG8_WAIT_V(8); PG8_WAIT_L(0); PG8_BAR; PG8_MMA(0, 0, At, B0); PG8_MMA(0, 1, At, B1); PG8_BAR; PG8_SCHED;
;             PG8_LDA(At, 1, 1); PG8_STAGE(PG8_SB(1, 0), b3, voffB); PG8_STAGE(PG8_SB(1, 1), b3 + hstep, voffB); PG8_STAGE(PG8_SA(1, 0), a3, voffA);
;             PG8_WAIT_V(8); PG8_WAIT_L(0); PG8_BAR; PG8_MMA(1, 0, At, B0); PG8_MMA(1, 1, At, B1); PG8_BAR; PG8_SCHED;
	s_add_i32 s77, 0, 0x18000
	v_add_u32_e32 v138, s77, v148
	s_add_i32 s78, 0, 0x1c000
	ds_read_b128 v[154:157], v138
	ds_read_b128 v[158:161], v138 offset:1024
	ds_read_b128 v[162:165], v138 offset:2048
	ds_read_b128 v[166:169], v138 offset:3072
	v_add_u32_e32 v138, s78, v148
	ds_read_b128 v[170:173], v138
	ds_read_b128 v[174:177], v138 offset:1024
	ds_read_b128 v[180:183], v138 offset:2048
	ds_read_b128 v[184:187], v138 offset:3072
	s_mov_b32 m0, s28
	s_nop 0
	global_load_lds_dwordx4 v130, s[74:75]
	s_mov_b32 m0, s29
	s_nop 0
	global_load_lds_dwordx4 v134, s[74:75]
	s_add_u32 s74, s74, 0x4000
	s_addc_u32 s75, s75, 0
	s_mov_b32 m0, s30
	ds_read_b128 v[188:191], v152 offset:32768
	ds_read_b128 v[196:199], v152 offset:33792
	ds_read_b128 v[200:203], v152 offset:34816
	ds_read_b128 v[204:207], v152 offset:35840
	ds_read_b128 v[208:211], v152 offset:36864
	ds_read_b128 v[212:215], v152 offset:37888
	ds_read_b128 v[216:219], v152 offset:38912
	ds_read_b128 v[220:223], v152 offset:39936
	global_load_lds_dwordx4 v130, s[74:75]
	s_mov_b32 m0, s31
	s_nop 0
	global_load_lds_dwordx4 v134, s[74:75]
	s_waitcnt vmcnt(8)
	s_waitcnt lgkmcnt(0)
	s_barrier
	s_setprio 1
	s_waitcnt lgkmcnt(0)
	v_mfma_f32_16x16x32_bf16 v[126:129], v[154:157], v[188:191], v[126:129]
	v_mfma_f32_16x16x32_bf16 v[126:129], v[158:161], v[196:199], v[126:129]
	v_mfma_f32_16x16x32_bf16 v[110:113], v[154:157], v[200:203], v[110:113]
	v_mfma_f32_16x16x32_bf16 v[110:113], v[158:161], v[204:207], v[110:113]
	v_mfma_f32_16x16x32_bf16 v[94:97], v[154:157], v[208:211], v[94:97]
	v_mfma_f32_16x16x32_bf16 v[94:97], v[158:161], v[212:215], v[94:97]
	v_mfma_f32_16x16x32_bf16 v[78:81], v[154:157], v[216:219], v[78:81]
	v_mfma_f32_16x16x32_bf16 v[78:81], v[158:161], v[220:223], v[78:81]
	v_mfma_f32_16x16x32_bf16 v[70:73], v[162:165], v[216:219], v[70:73]
	v_mfma_f32_16x16x32_bf16 v[70:73], v[166:169], v[220:223], v[70:73]
	v_mfma_f32_16x16x32_bf16 v[86:89], v[162:165], v[208:211], v[86:89]
	v_mfma_f32_16x16x32_bf16 v[86:89], v[166:169], v[212:215], v[86:89]
	v_mfma_f32_16x16x32_bf16 v[102:105], v[162:165], v[200:203], v[102:105]
	v_mfma_f32_16x16x32_bf16 v[102:105], v[166:169], v[204:207], v[102:105]
	v_mfma_f32_16x16x32_bf16 v[118:121], v[162:165], v[188:191], v[118:121]
	v_mfma_f32_16x16x32_bf16 v[118:121], v[166:169], v[196:199], v[118:121]
	s_setprio 0
	s_setprio 1
	v_mfma_f32_16x16x32_bf16 v[122:125], v[170:173], v[188:191], v[122:125]
	v_mfma_f32_16x16x32_bf16 v[122:125], v[174:177], v[196:199], v[122:125]
	v_mfma_f32_16x16x32_bf16 v[106:109], v[170:173], v[200:203], v[106:109]
	v_mfma_f32_16x16x32_bf16 v[106:109], v[174:177], v[204:207], v[106:109]
	v_mfma_f32_16x16x32_bf16 v[90:93], v[170:173], v[208:211], v[90:93]
	v_mfma_f32_16x16x32_bf16 v[90:93], v[174:177], v[212:215], v[90:93]
	v_mfma_f32_16x16x32_bf16 v[74:77], v[170:173], v[216:219], v[74:77]
	v_mfma_f32_16x16x32_bf16 v[74:77], v[174:177], v[220:223], v[74:77]
	v_mfma_f32_16x16x32_bf16 v[66:69], v[180:183], v[216:219], v[66:69]
	v_mfma_f32_16x16x32_bf16 v[66:69], v[184:187], v[220:223], v[66:69]
	v_mfma_f32_16x16x32_bf16 v[82:85], v[180:183], v[208:211], v[82:85]
	v_mfma_f32_16x16x32_bf16 v[82:85], v[184:187], v[212:215], v[82:85]
	v_mfma_f32_16x16x32_bf16 v[98:101], v[180:183], v[200:203], v[98:101]
	v_mfma_f32_16x16x32_bf16 v[98:101], v[184:187], v[204:207], v[98:101]
	v_mfma_f32_16x16x32_bf16 v[114:117], v[180:183], v[188:191], v[114:117]
	v_mfma_f32_16x16x32_bf16 v[114:117], v[184:187], v[196:199], v[114:117]
	s_setprio 0
	s_barrier
	s_add_u32 s74, s72, 0x8000
	s_addc_u32 s75, s73, 0
	s_add_i32 s77, s77, s3
	s_mov_b32 m0, s77
	ds_read_b128 v[188:191], v152 offset:49152
	ds_read_b128 v[196:199], v152 offset:50176
	ds_read_b128 v[200:203], v152 offset:51200
	ds_read_b128 v[204:207], v152 offset:52224
	ds_read_b128 v[208:211], v152 offset:53248
	ds_read_b128 v[212:215], v152 offset:54272
	ds_read_b128 v[216:219], v152 offset:55296
	ds_read_b128 v[220:223], v152 offset:56320
	global_load_lds_dwordx4 v132, s[74:75]
	s_add_i32 m0, s77, 0x2000
	s_add_u32 s72, s72, 0xc000
	v_lshl_add_u64 v[224:225], s[74:75], 0, v[136:137]
	s_addc_u32 s73, s73, 0
	s_add_i32 s74, s78, s3
	global_load_lds_dwordx4 v[224:225], off
	s_mov_b32 m0, s74
	s_nop 0
	global_load_lds_dwordx4 v132, s[72:73]
	s_add_i32 m0, s74, 0x2000
	s_nop 0
	global_load_lds_dwordx4 v136, s[72:73]
	s_waitcnt vmcnt(6)
	s_waitcnt lgkmcnt(0)
	s_barrier
	s_setprio 1
	s_waitcnt lgkmcnt(0)
	v_mfma_f32_16x16x32_bf16 v[62:65], v[154:157], v[188:191], v[62:65]
	v_mfma_f32_16x16x32_bf16 v[62:65], v[158:161], v[196:199], v[62:65]
	v_mfma_f32_16x16x32_bf16 v[46:49], v[154:157], v[200:203], v[46:49]
	v_mfma_f32_16x16x32_bf16 v[46:49], v[158:161], v[204:207], v[46:49]
	v_mfma_f32_16x16x32_bf16 v[30:33], v[154:157], v[208:211], v[30:33]
	v_mfma_f32_16x16x32_bf16 v[30:33], v[158:161], v[212:215], v[30:33]
	v_mfma_f32_16x16x32_bf16 v[14:17], v[154:157], v[216:219], v[14:17]
	v_mfma_f32_16x16x32_bf16 v[14:17], v[158:161], v[220:223], v[14:17]
	v_mfma_f32_16x16x32_bf16 v[6:9], v[162:165], v[216:219], v[6:9]
	v_mfma_f32_16x16x32_bf16 v[6:9], v[166:169], v[220:223], v[6:9]
	v_mfma_f32_16x16x32_bf16 v[22:25], v[162:165], v[208:211], v[22:25]
	v_mfma_f32_16x16x32_bf16 v[22:25], v[166:169], v[212:215], v[22:25]
	v_mfma_f32_16x16x32_bf16 v[38:41], v[162:165], v[200:203], v[38:41]
	v_mfma_f32_16x16x32_bf16 v[38:41], v[166:169], v[204:207], v[38:41]
	v_mfma_f32_16x16x32_bf16 v[54:57], v[162:165], v[188:191], v[54:57]
	v_mfma_f32_16x16x32_bf16 v[54:57], v[166:169], v[196:199], v[54:57]
	s_setprio 0
	s_setprio 1
	v_mfma_f32_16x16x32_bf16 v[58:61], v[170:173], v[188:191], v[58:61]
	v_mfma_f32_16x16x32_bf16 v[58:61], v[174:177], v[196:199], v[58:61]
	v_mfma_f32_16x16x32_bf16 v[42:45], v[170:173], v[200:203], v[42:45]
	v_mfma_f32_16x16x32_bf16 v[42:45], v[174:177], v[204:207], v[42:45]
	v_mfma_f32_16x16x32_bf16 v[26:29], v[170:173], v[208:211], v[26:29]
	v_mfma_f32_16x16x32_bf16 v[26:29], v[174:177], v[212:215], v[26:29]
	v_mfma_f32_16x16x32_bf16 v[10:13], v[170:173], v[216:219], v[10:13]
	v_mfma_f32_16x16x32_bf16 v[10:13], v[174:177], v[220:223], v[10:13]
	v_mfma_f32_16x16x32_bf16 v[2:5], v[180:183], v[216:219], v[2:5]
	v_mfma_f32_16x16x32_bf16 v[2:5], v[184:187], v[220:223], v[2:5]
	v_mfma_f32_16x16x32_bf16 v[18:21], v[180:183], v[208:211], v[18:21]
	v_mfma_f32_16x16x32_bf16 v[18:21], v[184:187], v[212:215], v[18:21]
	v_mfma_f32_16x16x32_bf16 v[34:37], v[180:183], v[200:203], v[34:37]
	v_mfma_f32_16x16x32_bf16 v[34:37], v[184:187], v[204:207], v[34:37]
	v_mfma_f32_16x16x32_bf16 v[50:53], v[180:183], v[188:191], v[50:53]
	v_mfma_f32_16x16x32_bf16 v[50:53], v[184:187], v[196:199], v[50:53]
	s_setprio 0
	s_barrier
	s_add_i32 s76, s76, 2
	s_add_u32 s48, s48, 0x10000
	s_addc_u32 s49, s49, 0
	s_add_u32 s68, s68, 0x10000
	s_addc_u32 s69, s69, 0
	s_cmp_gt_u32 s76, 61
	s_cbranch_scc0 .LBB0_115
	s_and_b64 vcc, exec, s[14:15]
	s_cbranch_vccz .LBB0_118
	s_barrier

; #define PG8_STAGE(bufoff, gbase, voff) do { _Pragma("unroll") for (int _i = 0; _i < 2; ++_i) \
;         __builtin_amdgcn_global_load_lds((const unsigned*)((const char*)(gbase) + (voff)[_i]), (PG8_LAS unsigned*)(lds + (bufoff) + ldsw + _i * 8192), 16, 0, 0); } while (0)
; #define PG8_LDA(dst, b, h) do { _Pragma("unroll") for (int m = 0; m < 4; ++m) _Pragma("unroll") for (int k = 0; k < 2; ++k) dst[m][k] = *(const PG8_LAS bf16x8*)(lds + PG8_SA(b, h) + aoff + m * 2048 + k * 1024); } while (0)
; #define PG8_LDB(dst, b, h) do { _Pragma("unroll") for (int n = 0; n < 2; ++n) _Pragma("unroll") for (int k = 0; k < 2; ++k) dst[n][k] = *(const PG8_LAS bf16x8*)(lds + PG8_SB(b, h) + boff + n * 2048 + k * 1024); } while (0)
; #define PG8_MMA(ai, bj, At, Bt) do { __builtin_amdgcn_s_setprio(1); _Pragma("unroll") for (int m = 0; m < 4; ++m) _Pragma("unroll") for (int n = 0; n < 2; ++n) _Pragma("unroll") for (int k = 0; k < 2; ++k) \
;         acc[ai][bj][m][n] = __builtin_amdgcn_mfma_f32_16x16x32_bf16(Bt[n][k], At[m][k], acc[ai][bj][m][n], 0, 0, 0); __builtin_amdgcn_s_setprio(0); } while (0)
; #define PG8_WAIT_V(n) asm volatile("s_waitcnt vmcnt(" #n ")" ::: "memory")
; #define PG8_WAIT_L(n) asm volatile("s_waitcnt lgkmcnt(" #n ")" ::: "memory")
; template <class Epi, class Sched, bool ALIGN_EPI = false, bool SP2 = false>
; __device__ __forceinline__ void gemm_phase(PG8_LAS unsigned char* lds, const Gemm g, const Sched& S, const Epi& E) {
;     ...
;         for (; t < tend; t += 2) {
;             const bool last = (t == nt - 2);
;             const char* a1 = cA + (size_t)(t + 1) * kstep;
;             const char* a2 = last ? nA : cA + (size_t)(t + 2) * kstep; const char* b2 = last ? nB : cB + (size_t)(t + 2) * kstep;
;             const char* a3 = a2 + kstep; const char* b3 = b2 + kstep;
;             if (last && has_next) S.a_ready(nxt);
;             if constexpr (SP2) {
;             PG8_LDB(B0, 0, 0); PG8_LDB(B1, 0, 1); PG8_SCHED; PG8_LDA(At, 0, 0); PG8_STAGE(PG8_SA(1, 1), a1 + hstep, voffA);
;             PG8_WAIT_V(8); PG8_WAIT_L(0); PG8_BAR; PG8_MMA(0, 0, At, B0); PG8_MMA(0, 1, At, B1); PG8_BAR; PG8_SCHED;
;             PG8_LDA(At, 0, 1); PG8_STAGE(PG8_SB(0, 0), b2, voffB); PG8_STAGE(PG8_SB(0, 1), b2 + hstep, voffB); PG8_STAGE(PG8_SA(0, 0), a2, voffA);
;             PG8_WAIT_V(8); PG8_WAIT_L(0); PG8_BAR; PG8_MMA(1, 0, At, B0); PG8_MMA(1, 1, At, B1); PG8_BAR; PG8_SCHED;
.LBB0_200:
	ds_read_b128 v[148:151], v154
	ds_read_b128 v[158:161], v154 offset:1024
	ds_read_b128 v[162:165], v154 offset:2048
	ds_read_b128 v[166:169], v154 offset:3072
	ds_read_b128 v[170:173], v155
	ds_read_b128 v[174:177], v155 offset:1024
	ds_read_b128 v[180:183], v155 offset:2048
	ds_read_b128 v[184:187], v155 offset:3072
	s_add_u32 s46, s44, 0x4000
	s_addc_u32 s47, s45, 0
	s_cmpk_eq_i32 s76, 0xa8
	s_cselect_b32 s50, s6, s46
	s_cselect_b32 s51, s7, s47
	s_cselect_b32 s48, s24, s74
	s_cselect_b32 s49, s25, s75
	s_add_u32 s46, s50, 0x8000
	s_addc_u32 s47, s51, 0
	s_sub_u32 s46, s44, 0x4000
	s_subb_u32 s47, s45, 0
	s_mov_b32 m0, s57
	s_nop 0
	global_load_lds_dwordx4 v130, s[46:47]
	s_mov_b32 m0, s58
	s_nop 0
	global_load_lds_dwordx4 v134, s[46:47]
	s_add_i32 m0, s26, 0xc000
	ds_read_b128 v[188:191], v156
	ds_read_b128 v[196:199], v156 offset:1024
	ds_read_b128 v[200:203], v156 offset:2048
	ds_read_b128 v[204:207], v156 offset:3072
	ds_read_b128 v[208:211], v156 offset:4096
	ds_read_b128 v[212:215], v156 offset:5120
	ds_read_b128 v[216:219], v156 offset:6144
	ds_read_b128 v[220:223], v156 offset:7168
	global_load_lds_dwordx4 v140, s[44:45]
	s_add_i32 m0, s26, 0xe000
	s_nop 0
	global_load_lds_dwordx4 v142, s[44:45]
	s_waitcnt vmcnt(8)
	s_waitcnt lgkmcnt(0)
	s_barrier
	s_setprio 1
	s_waitcnt lgkmcnt(0)
	v_mfma_f32_16x16x32_bf16 v[126:129], v[148:151], v[188:191], v[126:129]
	v_mfma_f32_16x16x32_bf16 v[126:129], v[158:161], v[196:199], v[126:129]
	v_mfma_f32_16x16x32_bf16 v[110:113], v[148:151], v[200:203], v[110:113]
	v_mfma_f32_16x16x32_bf16 v[110:113], v[158:161], v[204:207], v[110:113]
	v_mfma_f32_16x16x32_bf16 v[94:97], v[148:151], v[208:211], v[94:97]
	v_mfma_f32_16x16x32_bf16 v[94:97], v[158:161], v[212:215], v[94:97]
	v_mfma_f32_16x16x32_bf16 v[78:81], v[148:151], v[216:219], v[78:81]
	v_mfma_f32_16x16x32_bf16 v[78:81], v[158:161], v[220:223], v[78:81]
	v_mfma_f32_16x16x32_bf16 v[74:77], v[162:165], v[216:219], v[74:77]
	v_mfma_f32_16x16x32_bf16 v[74:77], v[166:169], v[220:223], v[74:77]
	v_mfma_f32_16x16x32_bf16 v[90:93], v[162:165], v[208:211], v[90:93]
	v_mfma_f32_16x16x32_bf16 v[90:93], v[166:169], v[212:215], v[90:93]
	v_mfma_f32_16x16x32_bf16 v[106:109], v[162:165], v[200:203], v[106:109]
	v_mfma_f32_16x16x32_bf16 v[106:109], v[166:169], v[204:207], v[106:109]
	v_mfma_f32_16x16x32_bf16 v[122:125], v[162:165], v[188:191], v[122:125]
	v_mfma_f32_16x16x32_bf16 v[122:125], v[166:169], v[196:199], v[122:125]
	s_setprio 0
	s_setprio 1
	v_mfma_f32_16x16x32_bf16 v[118:121], v[170:173], v[188:191], v[118:121]
	v_mfma_f32_16x16x32_bf16 v[118:121], v[174:177], v[196:199], v[118:121]
	v_mfma_f32_16x16x32_bf16 v[102:105], v[170:173], v[200:203], v[102:105]
	v_mfma_f32_16x16x32_bf16 v[102:105], v[174:177], v[204:207], v[102:105]
	v_mfma_f32_16x16x32_bf16 v[86:89], v[170:173], v[208:211], v[86:89]
	v_mfma_f32_16x16x32_bf16 v[86:89], v[174:177], v[212:215], v[86:89]
	v_mfma_f32_16x16x32_bf16 v[70:73], v[170:173], v[216:219], v[70:73]
	v_mfma_f32_16x16x32_bf16 v[70:73], v[174:177], v[220:223], v[70:73]
	v_mfma_f32_16x16x32_bf16 v[66:69], v[180:183], v[216:219], v[66:69]
	v_mfma_f32_16x16x32_bf16 v[66:69], v[184:187], v[220:223], v[66:69]
	v_mfma_f32_16x16x32_bf16 v[82:85], v[180:183], v[208:211], v[82:85]
	v_mfma_f32_16x16x32_bf16 v[82:85], v[184:187], v[212:215], v[82:85]
	v_mfma_f32_16x16x32_bf16 v[98:101], v[180:183], v[200:203], v[98:101]
	v_mfma_f32_16x16x32_bf16 v[98:101], v[184:187], v[204:207], v[98:101]
	v_mfma_f32_16x16x32_bf16 v[114:117], v[180:183], v[188:191], v[114:117]
	v_mfma_f32_16x16x32_bf16 v[114:117], v[184:187], v[196:199], v[114:117]
	s_setprio 0
	s_barrier
	s_add_i32 s77, s59, s3
	s_mov_b32 m0, s77
	ds_read_b128 v[188:191], v156 offset:16384
	ds_read_b128 v[196:199], v156 offset:17408
	ds_read_b128 v[200:203], v156 offset:18432
	ds_read_b128 v[204:207], v156 offset:19456
	ds_read_b128 v[208:211], v156 offset:20480
	ds_read_b128 v[212:215], v156 offset:21504
	ds_read_b128 v[216:219], v156 offset:22528
	ds_read_b128 v[220:223], v156 offset:23552
	global_load_lds_dwordx4 v132, s[48:49]
	s_add_i32 m0, s77, 0x2000
	s_add_u32 s78, s48, 0x4000
	s_addc_u32 s79, s49, 0
	s_add_i32 s77, s61, s3
	global_load_lds_dwordx4 v136, s[48:49]
	s_mov_b32 m0, s77
	s_nop 0
	global_load_lds_dwordx4 v132, s[78:79]
	s_add_i32 m0, s77, 0x2000
	s_nop 0
	global_load_lds_dwordx4 v136, s[78:79]
	s_waitcnt vmcnt(6)
	s_waitcnt lgkmcnt(0)
	s_barrier
	s_setprio 1
	s_waitcnt lgkmcnt(0)
	v_mfma_f32_16x16x32_bf16 v[62:65], v[148:151], v[188:191], v[62:65]
	v_mfma_f32_16x16x32_bf16 v[62:65], v[158:161], v[196:199], v[62:65]
	v_mfma_f32_16x16x32_bf16 v[46:49], v[148:151], v[200:203], v[46:49]
	v_mfma_f32_16x16x32_bf16 v[46:49], v[158:161], v[204:207], v[46:49]
	v_mfma_f32_16x16x32_bf16 v[30:33], v[148:151], v[208:211], v[30:33]
	v_mfma_f32_16x16x32_bf16 v[30:33], v[158:161], v[212:215], v[30:33]
	v_mfma_f32_16x16x32_bf16 v[14:17], v[148:151], v[216:219], v[14:17]
	v_mfma_f32_16x16x32_bf16 v[14:17], v[158:161], v[220:223], v[14:17]
	v_mfma_f32_16x16x32_bf16 v[10:13], v[162:165], v[216:219], v[10:13]
	v_mfma_f32_16x16x32_bf16 v[10:13], v[166:169], v[220:223], v[10:13]
	v_mfma_f32_16x16x32_bf16 v[26:29], v[162:165], v[208:211], v[26:29]
	v_mfma_f32_16x16x32_bf16 v[26:29], v[166:169], v[212:215], v[26:29]
	v_mfma_f32_16x16x32_bf16 v[42:45], v[162:165], v[200:203], v[42:45]
	v_mfma_f32_16x16x32_bf16 v[42:45], v[166:169], v[204:207], v[42:45]
	v_mfma_f32_16x16x32_bf16 v[58:61], v[162:165], v[188:191], v[58:61]
	v_mfma_f32_16x16x32_bf16 v[58:61], v[166:169], v[196:199], v[58:61]
	s_setprio 0
	s_setprio 1
	v_mfma_f32_16x16x32_bf16 v[54:57], v[170:173], v[188:191], v[54:57]
	v_mfma_f32_16x16x32_bf16 v[54:57], v[174:177], v[196:199], v[54:57]
	v_mfma_f32_16x16x32_bf16 v[38:41], v[170:173], v[200:203], v[38:41]
	v_mfma_f32_16x16x32_bf16 v[38:41], v[174:177], v[204:207], v[38:41]
	v_mfma_f32_16x16x32_bf16 v[22:25], v[170:173], v[208:211], v[22:25]
	v_mfma_f32_16x16x32_bf16 v[22:25], v[174:177], v[212:215], v[22:25]
	v_mfma_f32_16x16x32_bf16 v[6:9], v[170:173], v[216:219], v[6:9]
	v_mfma_f32_16x16x32_bf16 v[6:9], v[174:177], v[220:223], v[6:9]
	v_mfma_f32_16x16x32_bf16 v[2:5], v[180:183], v[216:219], v[2:5]
	v_mfma_f32_16x16x32_bf16 v[2:5], v[184:187], v[220:223], v[2:5]
	v_mfma_f32_16x16x32_bf16 v[18:21], v[180:183], v[208:211], v[18:21]
	v_mfma_f32_16x16x32_bf16 v[18:21], v[184:187], v[212:215], v[18:21]
	v_mfma_f32_16x16x32_bf16 v[34:37], v[180:183], v[200:203], v[34:37]
	v_mfma_f32_16x16x32_bf16 v[34:37], v[184:187], v[204:207], v[34:37]
	v_mfma_f32_16x16x32_bf16 v[50:53], v[180:183], v[188:191], v[50:53]
	v_mfma_f32_16x16x32_bf16 v[50:53], v[184:187], v[196:199], v[50:53]
	s_setprio 0
	s_barrier
; #define PG8_STAGE(bufoff, gbase, voff) do { _Pragma("unroll") for (int _i = 0; _i < 2; ++_i) \
;         __builtin_amdgcn_global_load_lds((const unsigned*)((const char*)(gbase) + (voff)[_i]), (PG8_LAS unsigned*)(lds + (bufoff) + ldsw + _i * 8192), 16, 0, 0); } while (0)
; #define PG8_LDA(dst, b, h) do { _Pragma("unroll") for (int m = 0; m < 4; ++m) _Pragma("unroll") for (int k = 0; k < 2; ++k) dst[m][k] = *(const PG8_LAS bf16x8*)(lds + PG8_SA(b, h) + aoff + m * 2048 + k * 1024); } while (0)
; #define PG8_LDB(dst, b, h) do { _Pragma("unroll") for (int n = 0; n < 2; ++n) _Pragma("unroll") for (int k = 0; k < 2; ++k) dst[n][k] = *(const PG8_LAS bf16x8*)(lds + PG8_SB(b, h) + boff + n * 2048 + k * 1024); } while (0)
; #define PG8_MMA(ai, bj, At, Bt) do { __builtin_amdgcn_s_setprio(1); _Pragma("unroll") for (int m = 0; m < 4; ++m) _Pragma("unroll") for (int n = 0; n < 2; ++n) _Pragma("unroll") for (int k = 0; k < 2; ++k) \
;         acc[ai][bj][m][n] = __builtin_amdgcn_mfma_f32_16x16x32_bf16(Bt[n][k], At[m][k], acc[ai][bj][m][n], 0, 0, 0); __builtin_amdgcn_s_setprio(0); } while (0)
; #define PG8_WAIT_V(n) asm volatile("s_waitcnt vmcnt(" #n ")" ::: "memory")
; #define PG8_WAIT_L(n) asm volatile("s_waitcnt lgkmcnt(" #n ")" ::: "memory")
; #define PG8_BAR __builtin_amdgcn_s_barrier()
; #define PG8_SCHED __builtin_amdgcn_sched_barrier(0)
; template <class Epi, class Sched, bool ALIGN_EPI = false, bool SP2 = false>
; __device__ __forceinline__ void gemm_phase(PG8_LAS unsigned char* lds, const Gemm g, const Sched& S, const Epi& E) {
;     ...
;             PG8_LDB(B0, 1, 0); PG8_LDB(B1, 1, 1); PG8_SCHED; PG8_LDA(At, 1, 0); PG8_STAGE(PG8_SA(0, 1), a2 + hstep, voffA);
;             PG8_WAIT_V(8); PG8_WAIT_L(0); PG8_BAR; PG8_MMA(0, 0, At, B0); PG8_MMA(0, 1, At, B1); PG8_BAR; PG8_SCHED;
;             PG8_LDA(At, 1, 1); PG8_STAGE(PG8_SB(1, 0), b3, voffB); PG8_STAGE(PG8_SB(1, 1), b3 + hstep, voffB); PG8_STAGE(PG8_SA(1, 0), a3, voffA);
;             PG8_WAIT_V(8); PG8_WAIT_L(0); PG8_BAR; PG8_MMA(1, 0, At, B0); PG8_MMA(1, 1, At, B1); PG8_BAR; PG8_SCHED;
	s_add_i32 s77, 0, 0x18000
	v_add_u32_e32 v138, s77, v153
	s_add_i32 s78, 0, 0x1c000
	ds_read_b128 v[148:151], v138
	ds_read_b128 v[158:161], v138 offset:1024
	ds_read_b128 v[162:165], v138 offset:2048
	ds_read_b128 v[166:169], v138 offset:3072
	v_add_u32_e32 v138, s78, v153
	ds_read_b128 v[170:173], v138
	ds_read_b128 v[174:177], v138 offset:1024
	ds_read_b128 v[180:183], v138 offset:2048
	ds_read_b128 v[184:187], v138 offset:3072
	s_mov_b32 m0, s26
	s_nop 0
	global_load_lds_dwordx4 v130, s[50:51]
	s_mov_b32 m0, s27
	s_nop 0
	global_load_lds_dwordx4 v134, s[50:51]
	s_add_u32 s50, s50, 0x4000
	s_addc_u32 s51, s51, 0
	s_mov_b32 m0, s28
	ds_read_b128 v[188:191], v156 offset:32768
	ds_read_b128 v[196:199], v156 offset:33792
	ds_read_b128 v[200:203], v156 offset:34816
	ds_read_b128 v[204:207], v156 offset:35840
	ds_read_b128 v[208:211], v156 offset:36864
	ds_read_b128 v[212:215], v156 offset:37888
	ds_read_b128 v[216:219], v156 offset:38912
	ds_read_b128 v[220:223], v156 offset:39936
	global_load_lds_dwordx4 v130, s[50:51]
	s_mov_b32 m0, s29
	s_nop 0
	global_load_lds_dwordx4 v134, s[50:51]
	s_waitcnt vmcnt(8)
	s_waitcnt lgkmcnt(0)
	s_barrier
	s_setprio 1
	s_waitcnt lgkmcnt(0)
	v_mfma_f32_16x16x32_bf16 v[126:129], v[148:151], v[188:191], v[126:129]
	v_mfma_f32_16x16x32_bf16 v[126:129], v[158:161], v[196:199], v[126:129]
	v_mfma_f32_16x16x32_bf16 v[110:113], v[148:151], v[200:203], v[110:113]
	v_mfma_f32_16x16x32_bf16 v[110:113], v[158:161], v[204:207], v[110:113]
	v_mfma_f32_16x16x32_bf16 v[94:97], v[148:151], v[208:211], v[94:97]
	v_mfma_f32_16x16x32_bf16 v[94:97], v[158:161], v[212:215], v[94:97]
	v_mfma_f32_16x16x32_bf16 v[78:81], v[148:151], v[216:219], v[78:81]
	v_mfma_f32_16x16x32_bf16 v[78:81], v[158:161], v[220:223], v[78:81]
	v_mfma_f32_16x16x32_bf16 v[74:77], v[162:165], v[216:219], v[74:77]
	v_mfma_f32_16x16x32_bf16 v[74:77], v[166:169], v[220:223], v[74:77]
	v_mfma_f32_16x16x32_bf16 v[90:93], v[162:165], v[208:211], v[90:93]
	v_mfma_f32_16x16x32_bf16 v[90:93], v[166:169], v[212:215], v[90:93]
	v_mfma_f32_16x16x32_bf16 v[106:109], v[162:165], v[200:203], v[106:109]
	v_mfma_f32_16x16x32_bf16 v[106:109], v[166:169], v[204:207], v[106:109]
	v_mfma_f32_16x16x32_bf16 v[122:125], v[162:165], v[188:191], v[122:125]
	v_mfma_f32_16x16x32_bf16 v[122:125], v[166:169], v[196:199], v[122:125]
	s_setprio 0
	s_setprio 1
	v_mfma_f32_16x16x32_bf16 v[118:121], v[170:173], v[188:191], v[118:121]
	v_mfma_f32_16x16x32_bf16 v[118:121], v[174:177], v[196:199], v[118:121]
	v_mfma_f32_16x16x32_bf16 v[102:105], v[170:173], v[200:203], v[102:105]
	v_mfma_f32_16x16x32_bf16 v[102:105], v[174:177], v[204:207], v[102:105]
	v_mfma_f32_16x16x32_bf16 v[86:89], v[170:173], v[208:211], v[86:89]
	v_mfma_f32_16x16x32_bf16 v[86:89], v[174:177], v[212:215], v[86:89]
	v_mfma_f32_16x16x32_bf16 v[70:73], v[170:173], v[216:219], v[70:73]
	v_mfma_f32_16x16x32_bf16 v[70:73], v[174:177], v[220:223], v[70:73]
	v_mfma_f32_16x16x32_bf16 v[66:69], v[180:183], v[216:219], v[66:69]
	v_mfma_f32_16x16x32_bf16 v[66:69], v[184:187], v[220:223], v[66:69]
	v_mfma_f32_16x16x32_bf16 v[82:85], v[180:183], v[208:211], v[82:85]
	v_mfma_f32_16x16x32_bf16 v[82:85], v[184:187], v[212:215], v[82:85]
	v_mfma_f32_16x16x32_bf16 v[98:101], v[180:183], v[200:203], v[98:101]
	v_mfma_f32_16x16x32_bf16 v[98:101], v[184:187], v[204:207], v[98:101]
	v_mfma_f32_16x16x32_bf16 v[114:117], v[180:183], v[188:191], v[114:117]
	v_mfma_f32_16x16x32_bf16 v[114:117], v[184:187], v[196:199], v[114:117]
	s_setprio 0
	s_barrier
	s_add_u32 s50, s48, 0x8000
	s_addc_u32 s51, s49, 0
	s_add_i32 s77, s77, s3
	s_mov_b32 m0, s77
	ds_read_b128 v[188:191], v156 offset:49152
	ds_read_b128 v[196:199], v156 offset:50176
	ds_read_b128 v[200:203], v156 offset:51200
	ds_read_b128 v[204:207], v156 offset:52224
	ds_read_b128 v[208:211], v156 offset:53248
	ds_read_b128 v[212:215], v156 offset:54272
	ds_read_b128 v[216:219], v156 offset:55296
	ds_read_b128 v[220:223], v156 offset:56320
	global_load_lds_dwordx4 v132, s[50:51]
	s_add_i32 m0, s77, 0x2000
	s_add_u32 s48, s48, 0xc000
	v_lshl_add_u64 v[224:225], s[50:51], 0, v[136:137]
	s_addc_u32 s49, s49, 0
	s_add_i32 s50, s78, s3
	global_load_lds_dwordx4 v[224:225], off
	s_mov_b32 m0, s50
	s_nop 0
	global_load_lds_dwordx4 v132, s[48:49]
	s_add_i32 m0, s50, 0x2000
	s_nop 0
	global_load_lds_dwordx4 v136, s[48:49]
	s_waitcnt vmcnt(6)
	s_waitcnt lgkmcnt(0)
	s_barrier
	s_setprio 1
	s_waitcnt lgkmcnt(0)
	v_mfma_f32_16x16x32_bf16 v[62:65], v[148:151], v[188:191], v[62:65]
	v_mfma_f32_16x16x32_bf16 v[62:65], v[158:161], v[196:199], v[62:65]
	v_mfma_f32_16x16x32_bf16 v[46:49], v[148:151], v[200:203], v[46:49]
	v_mfma_f32_16x16x32_bf16 v[46:49], v[158:161], v[204:207], v[46:49]
	v_mfma_f32_16x16x32_bf16 v[30:33], v[148:151], v[208:211], v[30:33]
	v_mfma_f32_16x16x32_bf16 v[30:33], v[158:161], v[212:215], v[30:33]
	v_mfma_f32_16x16x32_bf16 v[14:17], v[148:151], v[216:219], v[14:17]
	v_mfma_f32_16x16x32_bf16 v[14:17], v[158:161], v[220:223], v[14:17]
	v_mfma_f32_16x16x32_bf16 v[10:13], v[162:165], v[216:219], v[10:13]
	v_mfma_f32_16x16x32_bf16 v[10:13], v[166:169], v[220:223], v[10:13]
	v_mfma_f32_16x16x32_bf16 v[26:29], v[162:165], v[208:211], v[26:29]
	v_mfma_f32_16x16x32_bf16 v[26:29], v[166:169], v[212:215], v[26:29]
	v_mfma_f32_16x16x32_bf16 v[42:45], v[162:165], v[200:203], v[42:45]
	v_mfma_f32_16x16x32_bf16 v[42:45], v[166:169], v[204:207], v[42:45]
	v_mfma_f32_16x16x32_bf16 v[58:61], v[162:165], v[188:191], v[58:61]
	v_mfma_f32_16x16x32_bf16 v[58:61], v[166:169], v[196:199], v[58:61]
	s_setprio 0
	s_setprio 1
	v_mfma_f32_16x16x32_bf16 v[54:57], v[170:173], v[188:191], v[54:57]
	v_mfma_f32_16x16x32_bf16 v[54:57], v[174:177], v[196:199], v[54:57]
	v_mfma_f32_16x16x32_bf16 v[38:41], v[170:173], v[200:203], v[38:41]
	v_mfma_f32_16x16x32_bf16 v[38:41], v[174:177], v[204:207], v[38:41]
	v_mfma_f32_16x16x32_bf16 v[22:25], v[170:173], v[208:211], v[22:25]
	v_mfma_f32_16x16x32_bf16 v[22:25], v[174:177], v[212:215], v[22:25]
	v_mfma_f32_16x16x32_bf16 v[6:9], v[170:173], v[216:219], v[6:9]
	v_mfma_f32_16x16x32_bf16 v[6:9], v[174:177], v[220:223], v[6:9]
	v_mfma_f32_16x16x32_bf16 v[2:5], v[180:183], v[216:219], v[2:5]
	v_mfma_f32_16x16x32_bf16 v[2:5], v[184:187], v[220:223], v[2:5]
	v_mfma_f32_16x16x32_bf16 v[18:21], v[180:183], v[208:211], v[18:21]
	v_mfma_f32_16x16x32_bf16 v[18:21], v[184:187], v[212:215], v[18:21]
	v_mfma_f32_16x16x32_bf16 v[34:37], v[180:183], v[200:203], v[34:37]
	v_mfma_f32_16x16x32_bf16 v[34:37], v[184:187], v[204:207], v[34:37]
	v_mfma_f32_16x16x32_bf16 v[50:53], v[180:183], v[188:191], v[50:53]
	v_mfma_f32_16x16x32_bf16 v[50:53], v[184:187], v[196:199], v[50:53]
	s_setprio 0
	s_barrier
	s_add_i32 s76, s76, 2
	s_add_u32 s44, s44, 0x10000
	s_addc_u32 s45, s45, 0
	s_add_u32 s74, s74, 0x10000
	s_addc_u32 s75, s75, 0
	s_cmpk_gt_u32 s76, 0xa9
	s_cbranch_scc0 .LBB0_200
	s_and_b64 vcc, exec, s[18:19]
	s_cbranch_vccz .LBB0_203
	s_barrier

; #define PG8_STAGE(bufoff, gbase, voff) do { _Pragma("unroll") for (int _i = 0; _i < 2; ++_i) \
;         __builtin_amdgcn_global_load_lds((const unsigned*)((const char*)(gbase) + (voff)[_i]), (PG8_LAS unsigned*)(lds + (bufoff) + ldsw + _i * 8192), 16, 0, 0); } while (0)
; #define PG8_LDA(dst, b, h) do { _Pragma("unroll") for (int m = 0; m < 4; ++m) _Pragma("unroll") for (int k = 0; k < 2; ++k) dst[m][k] = *(const PG8_LAS bf16x8*)(lds + PG8_SA(b, h) + aoff + m * 2048 + k * 1024); } while (0)
; #define PG8_LDB(dst, b, h) do { _Pragma("unroll") for (int n = 0; n < 2; ++n) _Pragma("unroll") for (int k = 0; k < 2; ++k) dst[n][k] = *(const PG8_LAS bf16x8*)(lds + PG8_SB(b, h) + boff + n * 2048 + k * 1024); } while (0)
; #define PG8_MMA(ai, bj, At, Bt) do { __builtin_amdgcn_s_setprio(1); _Pragma("unroll") for (int m = 0; m < 4; ++m) _Pragma("unroll") for (int n = 0; n < 2; ++n) _Pragma("unroll") for (int k = 0; k < 2; ++k) \
;         acc[ai][bj][m][n] = __builtin_amdgcn_mfma_f32_16x16x32_bf16(Bt[n][k], At[m][k], acc[ai][bj][m][n], 0, 0, 0); __builtin_amdgcn_s_setprio(0); } while (0)
; #define PG8_WAIT_V(n) asm volatile("s_waitcnt vmcnt(" #n ")" ::: "memory")
; #define PG8_WAIT_L(n) asm volatile("s_waitcnt lgkmcnt(" #n ")" ::: "memory")
; template <class Epi, class Sched, bool ALIGN_EPI = false, bool SP2 = false>
; __device__ __forceinline__ void gemm_phase(PG8_LAS unsigned char* lds, const Gemm g, const Sched& S, const Epi& E) {
;     ...
;         for (; t < tend; t += 2) {
;             const bool last = (t == nt - 2);
;             const char* a1 = cA + (size_t)(t + 1) * kstep;
;             const char* a2 = last ? nA : cA + (size_t)(t + 2) * kstep; const char* b2 = last ? nB : cB + (size_t)(t + 2) * kstep;
;             const char* a3 = a2 + kstep; const char* b3 = b2 + kstep;
;             if (last && has_next) S.a_ready(nxt);
;             if constexpr (SP2) {
;             PG8_LDB(B0, 0, 0); PG8_LDB(B1, 0, 1); PG8_SCHED; PG8_LDA(At, 0, 0); PG8_STAGE(PG8_SA(1, 1), a1 + hstep, voffA);
;             PG8_WAIT_V(8); PG8_WAIT_L(0); PG8_BAR; PG8_MMA(0, 0, At, B0); PG8_MMA(0, 1, At, B1); PG8_BAR; PG8_SCHED;
;             PG8_LDA(At, 0, 1); PG8_STAGE(PG8_SB(0, 0), b2, voffB); PG8_STAGE(PG8_SB(0, 1), b2 + hstep, voffB); PG8_STAGE(PG8_SA(0, 0), a2, voffA);
;             PG8_WAIT_V(8); PG8_WAIT_L(0); PG8_BAR; PG8_MMA(1, 0, At, B0); PG8_MMA(1, 1, At, B1); PG8_BAR; PG8_SCHED;
.LBB0_290:
	ds_read_b128 v[146:149], v162
	ds_read_b128 v[150:153], v162 offset:1024
	ds_read_b128 v[154:157], v162 offset:2048
	ds_read_b128 v[168:171], v162 offset:3072
	ds_read_b128 v[172:175], v163
	ds_read_b128 v[180:183], v163 offset:1024
	ds_read_b128 v[184:187], v163 offset:2048
	ds_read_b128 v[188:191], v163 offset:3072
	s_add_u32 s59, s72, 0x4000
	s_addc_u32 s62, s73, 0
	s_cmp_eq_u32 s58, 60
	s_cselect_b32 s78, s19, s59
	s_cselect_b32 s79, s5, s62
	s_cselect_b32 s76, s26, s33
	s_cselect_b32 s77, s17, s56
	s_add_u32 s74, s78, 0x8000
	s_addc_u32 s75, s79, 0
	s_sub_u32 s74, s72, 0x4000
	s_subb_u32 s75, s73, 0
	s_mov_b32 m0, s51
	s_nop 0
	global_load_lds_dwordx4 v130, s[74:75]
	s_mov_b32 m0, s57
	s_nop 0
	global_load_lds_dwordx4 v134, s[74:75]
	s_add_i32 m0, s15, 0xc000
	ds_read_b128 v[198:201], v164
	ds_read_b128 v[202:205], v164 offset:1024
	ds_read_b128 v[206:209], v164 offset:2048
	ds_read_b128 v[210:213], v164 offset:3072
	ds_read_b128 v[214:217], v164 offset:4096
	ds_read_b128 v[218:221], v164 offset:5120
	ds_read_b128 v[222:225], v164 offset:6144
	ds_read_b128 v[226:229], v164 offset:7168
	global_load_lds_dwordx4 v138, s[72:73]
	s_add_i32 m0, s15, 0xe000
	s_nop 0
	global_load_lds_dwordx4 v140, s[72:73]
	s_waitcnt vmcnt(8)
	s_waitcnt lgkmcnt(0)
	s_barrier
	s_setprio 1
	s_waitcnt lgkmcnt(0)
	v_mfma_f32_16x16x32_bf16 v[126:129], v[146:149], v[198:201], v[126:129]
	v_mfma_f32_16x16x32_bf16 v[126:129], v[150:153], v[202:205], v[126:129]
	v_mfma_f32_16x16x32_bf16 v[110:113], v[146:149], v[206:209], v[110:113]
	v_mfma_f32_16x16x32_bf16 v[110:113], v[150:153], v[210:213], v[110:113]
	v_mfma_f32_16x16x32_bf16 v[94:97], v[146:149], v[214:217], v[94:97]
	v_mfma_f32_16x16x32_bf16 v[94:97], v[150:153], v[218:221], v[94:97]
	v_mfma_f32_16x16x32_bf16 v[78:81], v[146:149], v[222:225], v[78:81]
	v_mfma_f32_16x16x32_bf16 v[78:81], v[150:153], v[226:229], v[78:81]
	v_mfma_f32_16x16x32_bf16 v[74:77], v[154:157], v[222:225], v[74:77]
	v_mfma_f32_16x16x32_bf16 v[74:77], v[168:171], v[226:229], v[74:77]
	v_mfma_f32_16x16x32_bf16 v[90:93], v[154:157], v[214:217], v[90:93]
	v_mfma_f32_16x16x32_bf16 v[90:93], v[168:171], v[218:221], v[90:93]
	v_mfma_f32_16x16x32_bf16 v[106:109], v[154:157], v[206:209], v[106:109]
	v_mfma_f32_16x16x32_bf16 v[106:109], v[168:171], v[210:213], v[106:109]
	v_mfma_f32_16x16x32_bf16 v[122:125], v[154:157], v[198:201], v[122:125]
	v_mfma_f32_16x16x32_bf16 v[122:125], v[168:171], v[202:205], v[122:125]
	s_setprio 0
	s_setprio 1
	v_mfma_f32_16x16x32_bf16 v[118:121], v[172:175], v[198:201], v[118:121]
	v_mfma_f32_16x16x32_bf16 v[118:121], v[180:183], v[202:205], v[118:121]
	v_mfma_f32_16x16x32_bf16 v[102:105], v[172:175], v[206:209], v[102:105]
	v_mfma_f32_16x16x32_bf16 v[102:105], v[180:183], v[210:213], v[102:105]
	v_mfma_f32_16x16x32_bf16 v[86:89], v[172:175], v[214:217], v[86:89]
	v_mfma_f32_16x16x32_bf16 v[86:89], v[180:183], v[218:221], v[86:89]
	v_mfma_f32_16x16x32_bf16 v[70:73], v[172:175], v[222:225], v[70:73]
	v_mfma_f32_16x16x32_bf16 v[70:73], v[180:183], v[226:229], v[70:73]
	v_mfma_f32_16x16x32_bf16 v[66:69], v[184:187], v[222:225], v[66:69]
	v_mfma_f32_16x16x32_bf16 v[66:69], v[188:191], v[226:229], v[66:69]
	v_mfma_f32_16x16x32_bf16 v[82:85], v[184:187], v[214:217], v[82:85]
	v_mfma_f32_16x16x32_bf16 v[82:85], v[188:191], v[218:221], v[82:85]
	v_mfma_f32_16x16x32_bf16 v[98:101], v[184:187], v[206:209], v[98:101]
	v_mfma_f32_16x16x32_bf16 v[98:101], v[188:191], v[210:213], v[98:101]
	v_mfma_f32_16x16x32_bf16 v[114:117], v[184:187], v[198:201], v[114:117]
	v_mfma_f32_16x16x32_bf16 v[114:117], v[188:191], v[202:205], v[114:117]
	s_setprio 0
	s_barrier
	s_add_i32 s59, s81, s3
	s_mov_b32 m0, s59
	ds_read_b128 v[198:201], v164 offset:16384
	ds_read_b128 v[202:205], v164 offset:17408
	ds_read_b128 v[206:209], v164 offset:18432
	ds_read_b128 v[210:213], v164 offset:19456
	ds_read_b128 v[214:217], v164 offset:20480
	ds_read_b128 v[218:221], v164 offset:21504
	ds_read_b128 v[222:225], v164 offset:22528
	ds_read_b128 v[226:229], v164 offset:23552
	global_load_lds_dwordx4 v132, s[76:77]
	s_add_i32 m0, s59, 0x2000
	s_add_u32 s62, s76, 0x4000
	s_addc_u32 s63, s77, 0
	s_add_i32 s59, s82, s3
	global_load_lds_dwordx4 v136, s[76:77]
	s_mov_b32 m0, s59
	s_nop 0
	global_load_lds_dwordx4 v132, s[62:63]
	s_add_i32 m0, s59, 0x2000
	s_nop 0
	global_load_lds_dwordx4 v136, s[62:63]
	s_waitcnt vmcnt(6)
	s_waitcnt lgkmcnt(0)
	s_barrier
	s_setprio 1
	s_waitcnt lgkmcnt(0)
	v_mfma_f32_16x16x32_bf16 v[62:65], v[146:149], v[198:201], v[62:65]
	v_mfma_f32_16x16x32_bf16 v[62:65], v[150:153], v[202:205], v[62:65]
	v_mfma_f32_16x16x32_bf16 v[46:49], v[146:149], v[206:209], v[46:49]
	v_mfma_f32_16x16x32_bf16 v[46:49], v[150:153], v[210:213], v[46:49]
	v_mfma_f32_16x16x32_bf16 v[30:33], v[146:149], v[214:217], v[30:33]
	v_mfma_f32_16x16x32_bf16 v[30:33], v[150:153], v[218:221], v[30:33]
	v_mfma_f32_16x16x32_bf16 v[14:17], v[146:149], v[222:225], v[14:17]
	v_mfma_f32_16x16x32_bf16 v[14:17], v[150:153], v[226:229], v[14:17]
	v_mfma_f32_16x16x32_bf16 v[10:13], v[154:157], v[222:225], v[10:13]
	v_mfma_f32_16x16x32_bf16 v[10:13], v[168:171], v[226:229], v[10:13]
	v_mfma_f32_16x16x32_bf16 v[26:29], v[154:157], v[214:217], v[26:29]
	v_mfma_f32_16x16x32_bf16 v[26:29], v[168:171], v[218:221], v[26:29]
	v_mfma_f32_16x16x32_bf16 v[42:45], v[154:157], v[206:209], v[42:45]
	v_mfma_f32_16x16x32_bf16 v[42:45], v[168:171], v[210:213], v[42:45]
	v_mfma_f32_16x16x32_bf16 v[58:61], v[154:157], v[198:201], v[58:61]
	v_mfma_f32_16x16x32_bf16 v[58:61], v[168:171], v[202:205], v[58:61]
	s_setprio 0
	s_setprio 1
	v_mfma_f32_16x16x32_bf16 v[54:57], v[172:175], v[198:201], v[54:57]
	v_mfma_f32_16x16x32_bf16 v[54:57], v[180:183], v[202:205], v[54:57]
	v_mfma_f32_16x16x32_bf16 v[38:41], v[172:175], v[206:209], v[38:41]
	v_mfma_f32_16x16x32_bf16 v[38:41], v[180:183], v[210:213], v[38:41]
	v_mfma_f32_16x16x32_bf16 v[22:25], v[172:175], v[214:217], v[22:25]
	v_mfma_f32_16x16x32_bf16 v[22:25], v[180:183], v[218:221], v[22:25]
	v_mfma_f32_16x16x32_bf16 v[6:9], v[172:175], v[222:225], v[6:9]
	v_mfma_f32_16x16x32_bf16 v[6:9], v[180:183], v[226:229], v[6:9]
	v_mfma_f32_16x16x32_bf16 v[2:5], v[184:187], v[222:225], v[2:5]
	v_mfma_f32_16x16x32_bf16 v[2:5], v[188:191], v[226:229], v[2:5]
	v_mfma_f32_16x16x32_bf16 v[18:21], v[184:187], v[214:217], v[18:21]
	v_mfma_f32_16x16x32_bf16 v[18:21], v[188:191], v[218:221], v[18:21]
	v_mfma_f32_16x16x32_bf16 v[34:37], v[184:187], v[206:209], v[34:37]
	v_mfma_f32_16x16x32_bf16 v[34:37], v[188:191], v[210:213], v[34:37]
	v_mfma_f32_16x16x32_bf16 v[50:53], v[184:187], v[198:201], v[50:53]
	v_mfma_f32_16x16x32_bf16 v[50:53], v[188:191], v[202:205], v[50:53]
	s_setprio 0
	s_barrier
; #define PG8_STAGE(bufoff, gbase, voff) do { _Pragma("unroll") for (int _i = 0; _i < 2; ++_i) \
;         __builtin_amdgcn_global_load_lds((const unsigned*)((const char*)(gbase) + (voff)[_i]), (PG8_LAS unsigned*)(lds + (bufoff) + ldsw + _i * 8192), 16, 0, 0); } while (0)
; #define PG8_LDA(dst, b, h) do { _Pragma("unroll") for (int m = 0; m < 4; ++m) _Pragma("unroll") for (int k = 0; k < 2; ++k) dst[m][k] = *(const PG8_LAS bf16x8*)(lds + PG8_SA(b, h) + aoff + m * 2048 + k * 1024); } while (0)
; #define PG8_LDB(dst, b, h) do { _Pragma("unroll") for (int n = 0; n < 2; ++n) _Pragma("unroll") for (int k = 0; k < 2; ++k) dst[n][k] = *(const PG8_LAS bf16x8*)(lds + PG8_SB(b, h) + boff + n * 2048 + k * 1024); } while (0)
; #define PG8_MMA(ai, bj, At, Bt) do { __builtin_amdgcn_s_setprio(1); _Pragma("unroll") for (int m = 0; m < 4; ++m) _Pragma("unroll") for (int n = 0; n < 2; ++n) _Pragma("unroll") for (int k = 0; k < 2; ++k) \
;         acc[ai][bj][m][n] = __builtin_amdgcn_mfma_f32_16x16x32_bf16(Bt[n][k], At[m][k], acc[ai][bj][m][n], 0, 0, 0); __builtin_amdgcn_s_setprio(0); } while (0)
; #define PG8_WAIT_V(n) asm volatile("s_waitcnt vmcnt(" #n ")" ::: "memory")
; #define PG8_WAIT_L(n) asm volatile("s_waitcnt lgkmcnt(" #n ")" ::: "memory")
; #define PG8_BAR __builtin_amdgcn_s_barrier()
; #define PG8_SCHED __builtin_amdgcn_sched_barrier(0)
; template <class Epi, class Sched, bool ALIGN_EPI = false, bool SP2 = false>
; __device__ __forceinline__ void gemm_phase(PG8_LAS unsigned char* lds, const Gemm g, const Sched& S, const Epi& E) {
;     ...
;             PG8_LDB(B0, 1, 0); PG8_LDB(B1, 1, 1); PG8_SCHED; PG8_LDA(At, 1, 0); PG8_STAGE(PG8_SA(0, 1), a2 + hstep, voffA);
;             PG8_WAIT_V(8); PG8_WAIT_L(0); PG8_BAR; PG8_MMA(0, 0, At, B0); PG8_MMA(0, 1, At, B1); PG8_BAR; PG8_SCHED;
;             PG8_LDA(At, 1, 1); PG8_STAGE(PG8_SB(1, 0), b3, voffB); PG8_STAGE(PG8_SB(1, 1), b3 + hstep, voffB); PG8_STAGE(PG8_SA(1, 0), a3, voffA);
;             PG8_WAIT_V(8); PG8_WAIT_L(0); PG8_BAR; PG8_MMA(1, 0, At, B0); PG8_MMA(1, 1, At, B1); PG8_BAR; PG8_SCHED;
	s_add_i32 s59, 0, 0x18000
	v_add_u32_e32 v158, s59, v160
	s_add_i32 s64, 0, 0x1c000
	ds_read_b128 v[146:149], v158
	ds_read_b128 v[150:153], v158 offset:1024
	ds_read_b128 v[154:157], v158 offset:2048
	ds_read_b128 v[168:171], v158 offset:3072
	v_add_u32_e32 v158, s64, v160
	ds_read_b128 v[172:175], v158
	ds_read_b128 v[180:183], v158 offset:1024
	ds_read_b128 v[184:187], v158 offset:2048
	ds_read_b128 v[188:191], v158 offset:3072
	s_mov_b32 m0, s15
	s_nop 0
	global_load_lds_dwordx4 v130, s[78:79]
	s_mov_b32 m0, s27
	s_nop 0
	global_load_lds_dwordx4 v134, s[78:79]
	s_add_u32 s62, s78, 0x4000
	s_addc_u32 s63, s79, 0
	s_mov_b32 m0, s28
	ds_read_b128 v[198:201], v164 offset:32768
	ds_read_b128 v[202:205], v164 offset:33792
	ds_read_b128 v[206:209], v164 offset:34816
	ds_read_b128 v[210:213], v164 offset:35840
	ds_read_b128 v[214:217], v164 offset:36864
	ds_read_b128 v[218:221], v164 offset:37888
	ds_read_b128 v[222:225], v164 offset:38912
	ds_read_b128 v[226:229], v164 offset:39936
	global_load_lds_dwordx4 v130, s[62:63]
	s_mov_b32 m0, s29
	s_nop 0
	global_load_lds_dwordx4 v134, s[62:63]
	s_waitcnt vmcnt(8)
	s_waitcnt lgkmcnt(0)
	s_barrier
	s_setprio 1
	s_waitcnt lgkmcnt(0)
	v_mfma_f32_16x16x32_bf16 v[126:129], v[146:149], v[198:201], v[126:129]
	v_mfma_f32_16x16x32_bf16 v[126:129], v[150:153], v[202:205], v[126:129]
	v_mfma_f32_16x16x32_bf16 v[110:113], v[146:149], v[206:209], v[110:113]
	v_mfma_f32_16x16x32_bf16 v[110:113], v[150:153], v[210:213], v[110:113]
	v_mfma_f32_16x16x32_bf16 v[94:97], v[146:149], v[214:217], v[94:97]
	v_mfma_f32_16x16x32_bf16 v[94:97], v[150:153], v[218:221], v[94:97]
	v_mfma_f32_16x16x32_bf16 v[78:81], v[146:149], v[222:225], v[78:81]
	v_mfma_f32_16x16x32_bf16 v[78:81], v[150:153], v[226:229], v[78:81]
	v_mfma_f32_16x16x32_bf16 v[74:77], v[154:157], v[222:225], v[74:77]
	v_mfma_f32_16x16x32_bf16 v[74:77], v[168:171], v[226:229], v[74:77]
	v_mfma_f32_16x16x32_bf16 v[90:93], v[154:157], v[214:217], v[90:93]
	v_mfma_f32_16x16x32_bf16 v[90:93], v[168:171], v[218:221], v[90:93]
	v_mfma_f32_16x16x32_bf16 v[106:109], v[154:157], v[206:209], v[106:109]
	v_mfma_f32_16x16x32_bf16 v[106:109], v[168:171], v[210:213], v[106:109]
	v_mfma_f32_16x16x32_bf16 v[122:125], v[154:157], v[198:201], v[122:125]
	v_mfma_f32_16x16x32_bf16 v[122:125], v[168:171], v[202:205], v[122:125]
	s_setprio 0
	s_setprio 1
	v_mfma_f32_16x16x32_bf16 v[118:121], v[172:175], v[198:201], v[118:121]
	v_mfma_f32_16x16x32_bf16 v[118:121], v[180:183], v[202:205], v[118:121]
	v_mfma_f32_16x16x32_bf16 v[102:105], v[172:175], v[206:209], v[102:105]
	v_mfma_f32_16x16x32_bf16 v[102:105], v[180:183], v[210:213], v[102:105]
	v_mfma_f32_16x16x32_bf16 v[86:89], v[172:175], v[214:217], v[86:89]
	v_mfma_f32_16x16x32_bf16 v[86:89], v[180:183], v[218:221], v[86:89]
	v_mfma_f32_16x16x32_bf16 v[70:73], v[172:175], v[222:225], v[70:73]
	v_mfma_f32_16x16x32_bf16 v[70:73], v[180:183], v[226:229], v[70:73]
	v_mfma_f32_16x16x32_bf16 v[66:69], v[184:187], v[222:225], v[66:69]
	v_mfma_f32_16x16x32_bf16 v[66:69], v[188:191], v[226:229], v[66:69]
	v_mfma_f32_16x16x32_bf16 v[82:85], v[184:187], v[214:217], v[82:85]
	v_mfma_f32_16x16x32_bf16 v[82:85], v[188:191], v[218:221], v[82:85]
	v_mfma_f32_16x16x32_bf16 v[98:101], v[184:187], v[206:209], v[98:101]
	v_mfma_f32_16x16x32_bf16 v[98:101], v[188:191], v[210:213], v[98:101]
	v_mfma_f32_16x16x32_bf16 v[114:117], v[184:187], v[198:201], v[114:117]
	v_mfma_f32_16x16x32_bf16 v[114:117], v[188:191], v[202:205], v[114:117]
	s_setprio 0
	s_barrier
	s_add_u32 s62, s76, 0x8000
	s_addc_u32 s63, s77, 0
	s_add_i32 s59, s59, s3
	s_mov_b32 m0, s59
	ds_read_b128 v[198:201], v164 offset:49152
	ds_read_b128 v[202:205], v164 offset:50176
	ds_read_b128 v[206:209], v164 offset:51200
	ds_read_b128 v[210:213], v164 offset:52224
	ds_read_b128 v[214:217], v164 offset:53248
	ds_read_b128 v[218:221], v164 offset:54272
	ds_read_b128 v[222:225], v164 offset:55296
	ds_read_b128 v[226:229], v164 offset:56320
	global_load_lds_dwordx4 v132, s[62:63]
	s_add_i32 m0, s59, 0x2000
	v_lshl_add_u64 v[158:159], s[62:63], 0, v[136:137]
	s_add_u32 s62, s76, 0xc000
	s_addc_u32 s63, s77, 0
	s_add_i32 s59, s64, s3
	global_load_lds_dwordx4 v[158:159], off
	s_mov_b32 m0, s59
	s_nop 0
	global_load_lds_dwordx4 v132, s[62:63]
	s_add_i32 m0, s59, 0x2000
	s_nop 0
	global_load_lds_dwordx4 v136, s[62:63]
	s_waitcnt vmcnt(6)
	s_waitcnt lgkmcnt(0)
	s_barrier
	s_setprio 1
	s_waitcnt lgkmcnt(0)
	v_mfma_f32_16x16x32_bf16 v[62:65], v[146:149], v[198:201], v[62:65]
	v_mfma_f32_16x16x32_bf16 v[62:65], v[150:153], v[202:205], v[62:65]
	v_mfma_f32_16x16x32_bf16 v[46:49], v[146:149], v[206:209], v[46:49]
	v_mfma_f32_16x16x32_bf16 v[46:49], v[150:153], v[210:213], v[46:49]
	v_mfma_f32_16x16x32_bf16 v[30:33], v[146:149], v[214:217], v[30:33]
	v_mfma_f32_16x16x32_bf16 v[30:33], v[150:153], v[218:221], v[30:33]
	v_mfma_f32_16x16x32_bf16 v[14:17], v[146:149], v[222:225], v[14:17]
	v_mfma_f32_16x16x32_bf16 v[14:17], v[150:153], v[226:229], v[14:17]
	v_mfma_f32_16x16x32_bf16 v[10:13], v[154:157], v[222:225], v[10:13]
	v_mfma_f32_16x16x32_bf16 v[10:13], v[168:171], v[226:229], v[10:13]
	v_mfma_f32_16x16x32_bf16 v[26:29], v[154:157], v[214:217], v[26:29]
	v_mfma_f32_16x16x32_bf16 v[26:29], v[168:171], v[218:221], v[26:29]
	v_mfma_f32_16x16x32_bf16 v[42:45], v[154:157], v[206:209], v[42:45]
	v_mfma_f32_16x16x32_bf16 v[42:45], v[168:171], v[210:213], v[42:45]
	v_mfma_f32_16x16x32_bf16 v[58:61], v[154:157], v[198:201], v[58:61]
	v_mfma_f32_16x16x32_bf16 v[58:61], v[168:171], v[202:205], v[58:61]
	s_setprio 0
	s_setprio 1
	v_mfma_f32_16x16x32_bf16 v[54:57], v[172:175], v[198:201], v[54:57]
	v_mfma_f32_16x16x32_bf16 v[54:57], v[180:183], v[202:205], v[54:57]
	v_mfma_f32_16x16x32_bf16 v[38:41], v[172:175], v[206:209], v[38:41]
	v_mfma_f32_16x16x32_bf16 v[38:41], v[180:183], v[210:213], v[38:41]
	v_mfma_f32_16x16x32_bf16 v[22:25], v[172:175], v[214:217], v[22:25]
	v_mfma_f32_16x16x32_bf16 v[22:25], v[180:183], v[218:221], v[22:25]
	v_mfma_f32_16x16x32_bf16 v[6:9], v[172:175], v[222:225], v[6:9]
	v_mfma_f32_16x16x32_bf16 v[6:9], v[180:183], v[226:229], v[6:9]
	v_mfma_f32_16x16x32_bf16 v[2:5], v[184:187], v[222:225], v[2:5]
	v_mfma_f32_16x16x32_bf16 v[2:5], v[188:191], v[226:229], v[2:5]
	v_mfma_f32_16x16x32_bf16 v[18:21], v[184:187], v[214:217], v[18:21]
	v_mfma_f32_16x16x32_bf16 v[18:21], v[188:191], v[218:221], v[18:21]
	v_mfma_f32_16x16x32_bf16 v[34:37], v[184:187], v[206:209], v[34:37]
	v_mfma_f32_16x16x32_bf16 v[34:37], v[188:191], v[210:213], v[34:37]
	v_mfma_f32_16x16x32_bf16 v[50:53], v[184:187], v[198:201], v[50:53]
	v_mfma_f32_16x16x32_bf16 v[50:53], v[188:191], v[202:205], v[50:53]
	s_setprio 0
	s_barrier
	s_add_i32 s58, s58, 2
	s_add_u32 s72, s72, 0x10000
	s_addc_u32 s73, s73, 0
	s_add_u32 s33, s33, 0x10000
	s_addc_u32 s56, s56, 0
	s_cmp_gt_u32 s58, 61
	s_cbranch_scc0 .LBB0_290
	s_and_b64 vcc, exec, s[12:13]
	s_cbranch_vccz .LBB0_293
	s_barrier

; #define PG8_STAGE(bufoff, gbase, voff) do { _Pragma("unroll") for (int _i = 0; _i < 2; ++_i) \
;         __builtin_amdgcn_global_load_lds((const unsigned*)((const char*)(gbase) + (voff)[_i]), (PG8_LAS unsigned*)(lds + (bufoff) + ldsw + _i * 8192), 16, 0, 0); } while (0)
; #define PG8_LDA(dst, b, h) do { _Pragma("unroll") for (int m = 0; m < 4; ++m) _Pragma("unroll") for (int k = 0; k < 2; ++k) dst[m][k] = *(const PG8_LAS bf16x8*)(lds + PG8_SA(b, h) + aoff + m * 2048 + k * 1024); } while (0)
; #define PG8_LDB(dst, b, h) do { _Pragma("unroll") for (int n = 0; n < 2; ++n) _Pragma("unroll") for (int k = 0; k < 2; ++k) dst[n][k] = *(const PG8_LAS bf16x8*)(lds + PG8_SB(b, h) + boff + n * 2048 + k * 1024); } while (0)
; #define PG8_MMA(ai, bj, At, Bt) do { __builtin_amdgcn_s_setprio(1); _Pragma("unroll") for (int m = 0; m < 4; ++m) _Pragma("unroll") for (int n = 0; n < 2; ++n) _Pragma("unroll") for (int k = 0; k < 2; ++k) \
;         acc[ai][bj][m][n] = __builtin_amdgcn_mfma_f32_16x16x32_bf16(Bt[n][k], At[m][k], acc[ai][bj][m][n], 0, 0, 0); __builtin_amdgcn_s_setprio(0); } while (0)
; #define PG8_WAIT_V(n) asm volatile("s_waitcnt vmcnt(" #n ")" ::: "memory")
; #define PG8_WAIT_L(n) asm volatile("s_waitcnt lgkmcnt(" #n ")" ::: "memory")
; #define PG8_BAR __builtin_amdgcn_s_barrier()
; #define PG8_SCHED __builtin_amdgcn_sched_barrier(0)
; template <class Epi, class Sched, bool ALIGN_EPI = false, bool SP2 = false>
; __device__ __forceinline__ void gemm_phase(PG8_LAS unsigned char* lds, const Gemm g, const Sched& S, const Epi& E) {
;     ...
;             PG8_LDB(B0, 0, 0); PG8_LDB(B1, 0, 1); PG8_SCHED; PG8_LDA(At, 0, 0); PG8_STAGE(PG8_SA(1, 1), a1 + hstep, voffA);
;             PG8_WAIT_V(8); PG8_WAIT_L(0); PG8_BAR; PG8_MMA(0, 0, At, B0); PG8_MMA(0, 1, At, B1); PG8_BAR; PG8_SCHED;
;             PG8_LDA(At, 0, 1); PG8_STAGE(PG8_SB(0, 0), b2, voffB); PG8_STAGE(PG8_SB(0, 1), b2 + hstep, voffB); PG8_STAGE(PG8_SA(0, 0), a2, voffA);
;             PG8_WAIT_V(8); PG8_WAIT_L(0); PG8_BAR; PG8_MMA(1, 0, At, B0); PG8_MMA(1, 1, At, B1); PG8_BAR; PG8_SCHED;
.LBB0_682:
	ds_read_b128 v[166:169], v163
	ds_read_b128 v[170:173], v163 offset:1024
	ds_read_b128 v[174:177], v163 offset:2048
	ds_read_b128 v[180:183], v163 offset:3072
	ds_read_b128 v[184:187], v164
	ds_read_b128 v[188:191], v164 offset:1024
	ds_read_b128 v[198:201], v164 offset:2048
	ds_read_b128 v[202:205], v164 offset:3072
	v_lshl_add_u64 v[242:243], v[130:131], 0, s[44:45]
	s_add_i32 s83, s29, 0xc000
	v_lshl_add_u64 v[238:239], v[242:243], 0, s[10:11]
	s_mov_b32 m0, s83
	v_lshl_add_u64 v[244:245], v[132:133], 0, s[44:45]
	s_add_i32 s84, s29, 0xe000
	ds_read_b128 v[206:209], v165
	ds_read_b128 v[210:213], v165 offset:1024
	ds_read_b128 v[214:217], v165 offset:2048
	ds_read_b128 v[218:221], v165 offset:3072
	ds_read_b128 v[222:225], v165 offset:4096
	ds_read_b128 v[226:229], v165 offset:5120
	ds_read_b128 v[230:233], v165 offset:6144
	ds_read_b128 v[234:237], v165 offset:7168
	global_load_lds_dwordx4 v[238:239], off
	v_lshl_add_u64 v[238:239], v[244:245], 0, s[10:11]
	s_mov_b32 m0, s84
	s_nop 0
	global_load_lds_dwordx4 v[238:239], off
	s_waitcnt vmcnt(8)
	s_waitcnt lgkmcnt(0)
	s_barrier
	s_setprio 1
	s_waitcnt lgkmcnt(0)
	v_mfma_f32_16x16x32_bf16 v[14:17], v[166:169], v[206:209], v[14:17]
	v_mfma_f32_16x16x32_bf16 v[14:17], v[170:173], v[210:213], v[14:17]
	v_mfma_f32_16x16x32_bf16 v[38:41], v[166:169], v[214:217], v[38:41]
	v_mfma_f32_16x16x32_bf16 v[38:41], v[170:173], v[218:221], v[38:41]
	v_mfma_f32_16x16x32_bf16 v[70:73], v[166:169], v[222:225], v[70:73]
	v_mfma_f32_16x16x32_bf16 v[70:73], v[170:173], v[226:229], v[70:73]
	v_mfma_f32_16x16x32_bf16 v[94:97], v[166:169], v[230:233], v[94:97]
	v_mfma_f32_16x16x32_bf16 v[94:97], v[170:173], v[234:237], v[94:97]
	v_mfma_f32_16x16x32_bf16 v[90:93], v[174:177], v[230:233], v[90:93]
	v_mfma_f32_16x16x32_bf16 v[90:93], v[180:183], v[234:237], v[90:93]
	v_mfma_f32_16x16x32_bf16 v[66:69], v[174:177], v[222:225], v[66:69]
	v_mfma_f32_16x16x32_bf16 v[66:69], v[180:183], v[226:229], v[66:69]
	v_mfma_f32_16x16x32_bf16 v[34:37], v[174:177], v[214:217], v[34:37]
	v_mfma_f32_16x16x32_bf16 v[34:37], v[180:183], v[218:221], v[34:37]
	v_mfma_f32_16x16x32_bf16 v[10:13], v[174:177], v[206:209], v[10:13]
	v_mfma_f32_16x16x32_bf16 v[10:13], v[180:183], v[210:213], v[10:13]
	s_setprio 0
	s_setprio 1
	v_mfma_f32_16x16x32_bf16 v[30:33], v[184:187], v[206:209], v[30:33]
	v_mfma_f32_16x16x32_bf16 v[30:33], v[188:191], v[210:213], v[30:33]
	v_mfma_f32_16x16x32_bf16 v[54:57], v[184:187], v[214:217], v[54:57]
	v_mfma_f32_16x16x32_bf16 v[54:57], v[188:191], v[218:221], v[54:57]
	v_mfma_f32_16x16x32_bf16 v[86:89], v[184:187], v[222:225], v[86:89]
	v_mfma_f32_16x16x32_bf16 v[86:89], v[188:191], v[226:229], v[86:89]
	v_mfma_f32_16x16x32_bf16 v[110:113], v[184:187], v[230:233], v[110:113]
	v_mfma_f32_16x16x32_bf16 v[110:113], v[188:191], v[234:237], v[110:113]
	v_mfma_f32_16x16x32_bf16 v[106:109], v[198:201], v[230:233], v[106:109]
	v_mfma_f32_16x16x32_bf16 v[106:109], v[202:205], v[234:237], v[106:109]
	v_mfma_f32_16x16x32_bf16 v[82:85], v[198:201], v[222:225], v[82:85]
	v_mfma_f32_16x16x32_bf16 v[82:85], v[202:205], v[226:229], v[82:85]
	v_mfma_f32_16x16x32_bf16 v[50:53], v[198:201], v[214:217], v[50:53]
	v_mfma_f32_16x16x32_bf16 v[50:53], v[202:205], v[218:221], v[50:53]
	v_mfma_f32_16x16x32_bf16 v[26:29], v[198:201], v[206:209], v[26:29]
	v_mfma_f32_16x16x32_bf16 v[26:29], v[202:205], v[210:213], v[26:29]
	s_setprio 0
	s_barrier
	v_lshl_add_u64 v[246:247], v[156:157], 0, s[44:45]
	s_add_i32 s85, s80, s28
	v_lshl_add_u64 v[238:239], v[246:247], 0, s[14:15]
	s_mov_b32 m0, s85
	v_lshl_add_u64 v[248:249], v[158:159], 0, s[44:45]
	s_add_i32 s86, s85, 0x2000
	ds_read_b128 v[206:209], v165 offset:16384
	ds_read_b128 v[210:213], v165 offset:17408
	ds_read_b128 v[214:217], v165 offset:18432
	ds_read_b128 v[218:221], v165 offset:19456
	ds_read_b128 v[222:225], v165 offset:20480
	ds_read_b128 v[226:229], v165 offset:21504
	ds_read_b128 v[230:233], v165 offset:22528
	ds_read_b128 v[234:237], v165 offset:23552
	global_load_lds_dwordx4 v[238:239], off
	v_lshl_add_u64 v[238:239], v[248:249], 0, s[14:15]
	s_mov_b32 m0, s86
	s_add_i32 s87, s81, s28
	global_load_lds_dwordx4 v[238:239], off
	v_lshl_add_u64 v[238:239], v[246:247], 0, s[16:17]
	s_mov_b32 m0, s87
	s_add_i32 s88, s87, 0x2000
	global_load_lds_dwordx4 v[238:239], off
	v_lshl_add_u64 v[238:239], v[248:249], 0, s[16:17]
	s_mov_b32 m0, s88
	s_nop 0
	global_load_lds_dwordx4 v[238:239], off
	v_lshl_add_u64 v[238:239], v[242:243], 0, s[14:15]
	s_mov_b32 m0, s29
	s_nop 0
	global_load_lds_dwordx4 v[238:239], off
	v_lshl_add_u64 v[238:239], v[244:245], 0, s[14:15]
	s_mov_b32 m0, s30
	s_nop 0
	global_load_lds_dwordx4 v[238:239], off
	s_waitcnt vmcnt(8)
	s_waitcnt lgkmcnt(0)
	s_barrier
; #define PG8_STAGE(bufoff, gbase, voff) do { _Pragma("unroll") for (int _i = 0; _i < 2; ++_i) \
;         __builtin_amdgcn_global_load_lds((const unsigned*)((const char*)(gbase) + (voff)[_i]), (PG8_LAS unsigned*)(lds + (bufoff) + ldsw + _i * 8192), 16, 0, 0); } while (0)
; #define PG8_LDA(dst, b, h) do { _Pragma("unroll") for (int m = 0; m < 4; ++m) _Pragma("unroll") for (int k = 0; k < 2; ++k) dst[m][k] = *(const PG8_LAS bf16x8*)(lds + PG8_SA(b, h) + aoff + m * 2048 + k * 1024); } while (0)
; #define PG8_LDB(dst, b, h) do { _Pragma("unroll") for (int n = 0; n < 2; ++n) _Pragma("unroll") for (int k = 0; k < 2; ++k) dst[n][k] = *(const PG8_LAS bf16x8*)(lds + PG8_SB(b, h) + boff + n * 2048 + k * 1024); } while (0)
; #define PG8_MMA(ai, bj, At, Bt) do { __builtin_amdgcn_s_setprio(1); _Pragma("unroll") for (int m = 0; m < 4; ++m) _Pragma("unroll") for (int n = 0; n < 2; ++n) _Pragma("unroll") for (int k = 0; k < 2; ++k) \
;         acc[ai][bj][m][n] = __builtin_amdgcn_mfma_f32_16x16x32_bf16(Bt[n][k], At[m][k], acc[ai][bj][m][n], 0, 0, 0); __builtin_amdgcn_s_setprio(0); } while (0)
; #define PG8_WAIT_V(n) asm volatile("s_waitcnt vmcnt(" #n ")" ::: "memory")
; #define PG8_WAIT_L(n) asm volatile("s_waitcnt lgkmcnt(" #n ")" ::: "memory")
; #define PG8_BAR __builtin_amdgcn_s_barrier()
; #define PG8_SCHED __builtin_amdgcn_sched_barrier(0)
; template <class Epi, class Sched, bool ALIGN_EPI = false, bool SP2 = false>
; __device__ __forceinline__ void gemm_phase(PG8_LAS unsigned char* lds, const Gemm g, const Sched& S, const Epi& E) {
;     ...
;             PG8_WAIT_V(8); PG8_WAIT_L(0); PG8_BAR; PG8_MMA(1, 0, At, B0); PG8_MMA(1, 1, At, B1); PG8_BAR; PG8_SCHED;
;             PG8_LDB(B0, 1, 0); PG8_LDB(B1, 1, 1); PG8_SCHED; PG8_LDA(At, 1, 0); PG8_STAGE(PG8_SA(0, 1), a2 + hstep, voffA);
;             PG8_WAIT_V(8); PG8_WAIT_L(0); PG8_BAR; PG8_MMA(0, 0, At, B0); PG8_MMA(0, 1, At, B1); PG8_BAR; PG8_SCHED;
	s_setprio 1
	s_waitcnt lgkmcnt(0)
	v_mfma_f32_16x16x32_bf16 v[126:129], v[166:169], v[206:209], v[126:129]
	v_mfma_f32_16x16x32_bf16 v[126:129], v[170:173], v[210:213], v[126:129]
	v_mfma_f32_16x16x32_bf16 v[102:105], v[166:169], v[214:217], v[102:105]
	v_mfma_f32_16x16x32_bf16 v[102:105], v[170:173], v[218:221], v[102:105]
	v_mfma_f32_16x16x32_bf16 v[62:65], v[166:169], v[222:225], v[62:65]
	v_mfma_f32_16x16x32_bf16 v[62:65], v[170:173], v[226:229], v[62:65]
	v_mfma_f32_16x16x32_bf16 v[22:25], v[166:169], v[230:233], v[22:25]
	v_mfma_f32_16x16x32_bf16 v[22:25], v[170:173], v[234:237], v[22:25]
	v_mfma_f32_16x16x32_bf16 v[18:21], v[174:177], v[230:233], v[18:21]
	v_mfma_f32_16x16x32_bf16 v[18:21], v[180:183], v[234:237], v[18:21]
	v_mfma_f32_16x16x32_bf16 v[58:61], v[174:177], v[222:225], v[58:61]
	v_mfma_f32_16x16x32_bf16 v[58:61], v[180:183], v[226:229], v[58:61]
	v_mfma_f32_16x16x32_bf16 v[98:101], v[174:177], v[214:217], v[98:101]
	v_mfma_f32_16x16x32_bf16 v[98:101], v[180:183], v[218:221], v[98:101]
	v_mfma_f32_16x16x32_bf16 v[122:125], v[174:177], v[206:209], v[122:125]
	v_mfma_f32_16x16x32_bf16 v[122:125], v[180:183], v[210:213], v[122:125]
	s_setprio 0
	s_setprio 1
	v_mfma_f32_16x16x32_bf16 v[118:121], v[184:187], v[206:209], v[118:121]
	v_mfma_f32_16x16x32_bf16 v[118:121], v[188:191], v[210:213], v[118:121]
	v_mfma_f32_16x16x32_bf16 v[78:81], v[184:187], v[214:217], v[78:81]
	v_mfma_f32_16x16x32_bf16 v[78:81], v[188:191], v[218:221], v[78:81]
	v_mfma_f32_16x16x32_bf16 v[46:49], v[184:187], v[222:225], v[46:49]
	v_mfma_f32_16x16x32_bf16 v[46:49], v[188:191], v[226:229], v[46:49]
	v_mfma_f32_16x16x32_bf16 v[6:9], v[184:187], v[230:233], v[6:9]
	v_mfma_f32_16x16x32_bf16 v[6:9], v[188:191], v[234:237], v[6:9]
	v_mfma_f32_16x16x32_bf16 v[2:5], v[198:201], v[230:233], v[2:5]
	v_mfma_f32_16x16x32_bf16 v[2:5], v[202:205], v[234:237], v[2:5]
	v_mfma_f32_16x16x32_bf16 v[42:45], v[198:201], v[222:225], v[42:45]
	v_mfma_f32_16x16x32_bf16 v[42:45], v[202:205], v[226:229], v[42:45]
	v_mfma_f32_16x16x32_bf16 v[74:77], v[198:201], v[214:217], v[74:77]
	v_mfma_f32_16x16x32_bf16 v[74:77], v[202:205], v[218:221], v[74:77]
	v_mfma_f32_16x16x32_bf16 v[114:117], v[198:201], v[206:209], v[114:117]
	v_mfma_f32_16x16x32_bf16 v[114:117], v[202:205], v[210:213], v[114:117]
	s_setprio 0
	s_barrier
	s_add_i32 s89, 0, 0x18000
	s_add_i32 s91, 0, 0x1c000
	v_add_u32_e32 v142, s89, v161
	v_add_u32_e32 v167, s91, v161
	ds_read_b128 v[168:171], v142
	ds_read_b128 v[172:175], v142 offset:1024
	ds_read_b128 v[180:183], v142 offset:2048
	ds_read_b128 v[184:187], v142 offset:3072
	ds_read_b128 v[188:191], v167
	ds_read_b128 v[198:201], v167 offset:1024
	ds_read_b128 v[202:205], v167 offset:2048
	ds_read_b128 v[206:209], v167 offset:3072
	s_mov_b32 m0, s31
	v_lshl_add_u64 v[176:177], v[242:243], 0, s[16:17]
	ds_read_b128 v[210:213], v165 offset:32768
	ds_read_b128 v[214:217], v165 offset:33792
	ds_read_b128 v[218:221], v165 offset:34816
	ds_read_b128 v[222:225], v165 offset:35840
	ds_read_b128 v[226:229], v165 offset:36864
	ds_read_b128 v[230:233], v165 offset:37888
	ds_read_b128 v[234:237], v165 offset:38912
	ds_read_b128 v[238:241], v165 offset:39936
	global_load_lds_dwordx4 v[176:177], off
	v_lshl_add_u64 v[176:177], v[244:245], 0, s[16:17]
	s_mov_b32 m0, s35
	s_nop 0
	global_load_lds_dwordx4 v[176:177], off
	s_waitcnt vmcnt(8)
	s_waitcnt lgkmcnt(0)
	s_barrier
	s_setprio 1
	s_waitcnt lgkmcnt(0)
	v_mfma_f32_16x16x32_bf16 v[14:17], v[168:171], v[210:213], v[14:17]
	v_mfma_f32_16x16x32_bf16 v[14:17], v[172:175], v[214:217], v[14:17]
	v_mfma_f32_16x16x32_bf16 v[38:41], v[168:171], v[218:221], v[38:41]
	v_mfma_f32_16x16x32_bf16 v[38:41], v[172:175], v[222:225], v[38:41]
	v_mfma_f32_16x16x32_bf16 v[70:73], v[168:171], v[226:229], v[70:73]
	v_mfma_f32_16x16x32_bf16 v[70:73], v[172:175], v[230:233], v[70:73]
	v_mfma_f32_16x16x32_bf16 v[94:97], v[168:171], v[234:237], v[94:97]
	v_mfma_f32_16x16x32_bf16 v[94:97], v[172:175], v[238:241], v[94:97]
	v_mfma_f32_16x16x32_bf16 v[90:93], v[180:183], v[234:237], v[90:93]
	v_mfma_f32_16x16x32_bf16 v[90:93], v[184:187], v[238:241], v[90:93]
	v_mfma_f32_16x16x32_bf16 v[66:69], v[180:183], v[226:229], v[66:69]
	v_mfma_f32_16x16x32_bf16 v[66:69], v[184:187], v[230:233], v[66:69]
	v_mfma_f32_16x16x32_bf16 v[34:37], v[180:183], v[218:221], v[34:37]
	v_mfma_f32_16x16x32_bf16 v[34:37], v[184:187], v[222:225], v[34:37]
	v_mfma_f32_16x16x32_bf16 v[10:13], v[180:183], v[210:213], v[10:13]
	v_mfma_f32_16x16x32_bf16 v[10:13], v[184:187], v[214:217], v[10:13]
	s_setprio 0
	s_setprio 1
	v_mfma_f32_16x16x32_bf16 v[30:33], v[188:191], v[210:213], v[30:33]
	v_mfma_f32_16x16x32_bf16 v[30:33], v[198:201], v[214:217], v[30:33]
	v_mfma_f32_16x16x32_bf16 v[54:57], v[188:191], v[218:221], v[54:57]
	v_mfma_f32_16x16x32_bf16 v[54:57], v[198:201], v[222:225], v[54:57]
	v_mfma_f32_16x16x32_bf16 v[86:89], v[188:191], v[226:229], v[86:89]
	v_mfma_f32_16x16x32_bf16 v[86:89], v[198:201], v[230:233], v[86:89]
	v_mfma_f32_16x16x32_bf16 v[110:113], v[188:191], v[234:237], v[110:113]
	v_mfma_f32_16x16x32_bf16 v[110:113], v[198:201], v[238:241], v[110:113]
	v_mfma_f32_16x16x32_bf16 v[106:109], v[202:205], v[234:237], v[106:109]
	v_mfma_f32_16x16x32_bf16 v[106:109], v[206:209], v[238:241], v[106:109]
	v_mfma_f32_16x16x32_bf16 v[82:85], v[202:205], v[226:229], v[82:85]
	v_mfma_f32_16x16x32_bf16 v[82:85], v[206:209], v[230:233], v[82:85]
	v_mfma_f32_16x16x32_bf16 v[50:53], v[202:205], v[218:221], v[50:53]
	v_mfma_f32_16x16x32_bf16 v[50:53], v[206:209], v[222:225], v[50:53]
	v_mfma_f32_16x16x32_bf16 v[26:29], v[202:205], v[210:213], v[26:29]
	v_mfma_f32_16x16x32_bf16 v[26:29], v[206:209], v[214:217], v[26:29]
	s_setprio 0
	s_barrier
; __device__ __forceinline__ float bflo(unsigned w) { return __uint_as_float(w << 16); }
; __device__ __forceinline__ float bfhi(unsigned w) { return __uint_as_float(w & 0xffff0000u); }
; #define PG8_STAGE(bufoff, gbase, voff) do { _Pragma("unroll") for (int _i = 0; _i < 2; ++_i) \
;         __builtin_amdgcn_global_load_lds((const unsigned*)((const char*)(gbase) + (voff)[_i]), (PG8_LAS unsigned*)(lds + (bufoff) + ldsw + _i * 8192), 16, 0, 0); } while (0)
; #define PG8_LDA(dst, b, h) do { _Pragma("unroll") for (int m = 0; m < 4; ++m) _Pragma("unroll") for (int k = 0; k < 2; ++k) dst[m][k] = *(const PG8_LAS bf16x8*)(lds + PG8_SA(b, h) + aoff + m * 2048 + k * 1024); } while (0)
; #define PG8_BAR __builtin_amdgcn_s_barrier()
;     __device__ __forceinline__ void mid(f32x4 (&acc)[2][2][4][2], const Unit& u, int wr, int wc, int fr, int fq) const {
;         int row0 = u.pm * BM + wr * 64 + fr; const int col0 = u.pn * BM + wc * 32 + 8 * fq;
;         asm volatile("" : "+v"(row0));
; #pragma unroll
;         for (int ai = 0; ai < 2; ++ai)
; #pragma unroll
;             for (int m = 0; m < 4; ++m) { const bf16_t* pr = P + (size_t)(row0 + ai * HALF + m * 16) * NP + col0;
; #pragma unroll
;                 for (int bj = 0; bj < 2; ++bj) { const u32x4 a = *(const u32x4*)(pr + PC_GA + bj * HALF), b = *(const u32x4*)(pr + PC_GB + bj * HALF);
;                     const f32x4 b0 = {bflo(b.x), bfhi(b.x), bflo(b.y), bfhi(b.y)}, b1 = {bflo(b.z), bfhi(b.z), bflo(b.w), bfhi(b.w)};
;                     const f32x4 a0 = {bflo(a.x), bfhi(a.x), bflo(a.y), bfhi(a.y)}, a1 = {bflo(a.z), bfhi(a.z), bflo(a.w), bfhi(a.w)};
;                     f32x4 r0, r1;
; #pragma unroll
;                     for (int j = 0; j < 4; ++j) { r0[j] = a0[j] * __builtin_amdgcn_rcpf(fmaxf(b0[j], 1e-30f)); r1[j] = a1[j] * __builtin_amdgcn_rcpf(fmaxf(b1[j], 1e-30f)); }
;                     acc[ai][bj][m][0] *= r0; acc[ai][bj][m][1] *= r1; }
; template <class Epi, class Sched, bool ALIGN_EPI = false, bool SP2 = false>
; __device__ __forceinline__ void gemm_phase(PG8_LAS unsigned char* lds, const Gemm g, const Sched& S, const Epi& E) {
;     ...
;             PG8_LDA(At, 1, 1); PG8_STAGE(PG8_SB(1, 0), b3, voffB); PG8_STAGE(PG8_SB(1, 1), b3 + hstep, voffB); PG8_STAGE(PG8_SA(1, 0), a3, voffA);
;             PG8_WAIT_V(8); PG8_WAIT_L(0); PG8_BAR; PG8_MMA(1, 0, At, B0); PG8_MMA(1, 1, At, B1); PG8_BAR; PG8_SCHED;
	s_add_i32 s89, s89, s28
	v_lshl_add_u64 v[176:177], v[246:247], 0, s[22:23]
	s_mov_b32 m0, s89
	s_add_i32 s90, s89, 0x2000
	ds_read_b128 v[210:213], v165 offset:49152
	ds_read_b128 v[214:217], v165 offset:50176
	ds_read_b128 v[218:221], v165 offset:51200
	ds_read_b128 v[222:225], v165 offset:52224
	ds_read_b128 v[226:229], v165 offset:53248
	ds_read_b128 v[230:233], v165 offset:54272
	ds_read_b128 v[234:237], v165 offset:55296
	ds_read_b128 v[238:241], v165 offset:56320
	global_load_lds_dwordx4 v[176:177], off
	v_lshl_add_u64 v[176:177], v[248:249], 0, s[22:23]
	s_mov_b32 m0, s90
	s_add_i32 s91, s91, s28
	global_load_lds_dwordx4 v[176:177], off
	v_lshl_add_u64 v[176:177], v[246:247], 0, s[36:37]
	s_mov_b32 m0, s91
	s_add_i32 s92, s91, 0x2000
	global_load_lds_dwordx4 v[176:177], off
	v_lshl_add_u64 v[176:177], v[248:249], 0, s[36:37]
	s_mov_b32 m0, s92
	s_nop 0
	global_load_lds_dwordx4 v[176:177], off
	v_lshl_add_u64 v[176:177], v[242:243], 0, s[22:23]
	s_mov_b32 m0, s75
	s_nop 0
	global_load_lds_dwordx4 v[176:177], off
	v_lshl_add_u64 v[176:177], v[244:245], 0, s[22:23]
	s_mov_b32 m0, s76
	s_nop 0
	global_load_lds_dwordx4 v[176:177], off
	s_waitcnt vmcnt(8)
	s_waitcnt lgkmcnt(0)
	s_barrier
	s_setprio 1
	s_waitcnt lgkmcnt(0)
	v_mfma_f32_16x16x32_bf16 v[126:129], v[168:171], v[210:213], v[126:129]
	v_mfma_f32_16x16x32_bf16 v[126:129], v[172:175], v[214:217], v[126:129]
	v_mfma_f32_16x16x32_bf16 v[102:105], v[168:171], v[218:221], v[102:105]
	v_mfma_f32_16x16x32_bf16 v[102:105], v[172:175], v[222:225], v[102:105]
	v_mfma_f32_16x16x32_bf16 v[62:65], v[168:171], v[226:229], v[62:65]
	v_mfma_f32_16x16x32_bf16 v[62:65], v[172:175], v[230:233], v[62:65]
	v_mfma_f32_16x16x32_bf16 v[22:25], v[168:171], v[234:237], v[22:25]
	v_mfma_f32_16x16x32_bf16 v[22:25], v[172:175], v[238:241], v[22:25]
	v_mfma_f32_16x16x32_bf16 v[18:21], v[180:183], v[234:237], v[18:21]
	v_mfma_f32_16x16x32_bf16 v[18:21], v[184:187], v[238:241], v[18:21]
	v_mfma_f32_16x16x32_bf16 v[58:61], v[180:183], v[226:229], v[58:61]
	v_mfma_f32_16x16x32_bf16 v[58:61], v[184:187], v[230:233], v[58:61]
	v_mfma_f32_16x16x32_bf16 v[98:101], v[180:183], v[218:221], v[98:101]
	v_mfma_f32_16x16x32_bf16 v[98:101], v[184:187], v[222:225], v[98:101]
	v_mfma_f32_16x16x32_bf16 v[122:125], v[180:183], v[210:213], v[122:125]
	v_mfma_f32_16x16x32_bf16 v[122:125], v[184:187], v[214:217], v[122:125]
	s_setprio 0
	s_setprio 1
	v_mfma_f32_16x16x32_bf16 v[118:121], v[188:191], v[210:213], v[118:121]
	v_mfma_f32_16x16x32_bf16 v[118:121], v[198:201], v[214:217], v[118:121]
	v_mfma_f32_16x16x32_bf16 v[78:81], v[188:191], v[218:221], v[78:81]
	v_mfma_f32_16x16x32_bf16 v[78:81], v[198:201], v[222:225], v[78:81]
	v_mfma_f32_16x16x32_bf16 v[46:49], v[188:191], v[226:229], v[46:49]
	v_mfma_f32_16x16x32_bf16 v[46:49], v[198:201], v[230:233], v[46:49]
	v_mfma_f32_16x16x32_bf16 v[6:9], v[188:191], v[234:237], v[6:9]
	v_mfma_f32_16x16x32_bf16 v[6:9], v[198:201], v[238:241], v[6:9]
	v_mfma_f32_16x16x32_bf16 v[2:5], v[202:205], v[234:237], v[2:5]
	v_mfma_f32_16x16x32_bf16 v[2:5], v[206:209], v[238:241], v[2:5]
	v_mfma_f32_16x16x32_bf16 v[42:45], v[202:205], v[226:229], v[42:45]
	v_mfma_f32_16x16x32_bf16 v[42:45], v[206:209], v[230:233], v[42:45]
	v_mfma_f32_16x16x32_bf16 v[74:77], v[202:205], v[218:221], v[74:77]
	v_mfma_f32_16x16x32_bf16 v[74:77], v[206:209], v[222:225], v[74:77]
	v_mfma_f32_16x16x32_bf16 v[114:117], v[202:205], v[210:213], v[114:117]
	v_mfma_f32_16x16x32_bf16 v[114:117], v[206:209], v[214:217], v[114:117]
	s_setprio 0
	s_barrier
	s_add_i32 s27, s27, 2
	s_add_u32 s44, s44, 0x10000
	s_addc_u32 s45, s45, 0
	s_cmp_lt_u32 s27, 30
	s_cbranch_scc1 .LBB0_682
	s_ashr_i32 s41, s40, 31
	s_lshl_b64 s[44:45], s[40:41], 21
	s_add_u32 s44, s18, s44
	s_addc_u32 s45, s19, s45
	s_ashr_i32 s39, s38, 31
	s_lshl_b64 s[46:47], s[38:39], 21
	v_readlane_b32 s58, v255, 15
	v_readlane_b32 s59, v255, 16
	s_add_u32 s46, s58, s46
	s_addc_u32 s47, s59, s47
	s_lshl_b32 s39, s26, 8
	v_or_b32_e32 v130, s39, v162
	v_ashrrev_i32_e32 v131, 31, v130
	v_lshl_add_u32 v166, s70, 8, v160
	v_lshl_add_u64 v[156:157], v[130:131], 1, s[24:25]
	v_mov_b32_e32 v168, v166
	s_and_b64 s[26:27], s[0:1], exec
	v_mad_i64_i32 v[158:159], s[58:59], v168, s78, v[156:157]
	v_add_co_u32_e32 v174, vcc, s61, v158
	s_cselect_b32 s41, s45, s51
	s_nop 0
	v_addc_co_u32_e32 v175, vcc, 0, v159, vcc
	v_add_co_u32_e32 v158, vcc, s77, v158
	global_load_dwordx4 v[130:133], v[174:175], off
	s_nop 0
	v_addc_co_u32_e32 v159, vcc, 0, v159, vcc
	global_load_dwordx4 v[170:173], v[158:159], off
	s_cselect_b32 s93, s44, s50
	s_cselect_b32 s27, s47, s49
	s_cselect_b32 s97, s46, s48
	s_add_u32 s50, s50, 0x10c000
	s_addc_u32 s51, s51, 0
	s_add_u32 s26, s48, 0x110000
	s_addc_u32 s33, s49, 0
	s_mov_b32 s56, 30
	s_waitcnt vmcnt(0)
; __device__ __forceinline__ float bflo(unsigned w) { return __uint_as_float(w << 16); }
; __device__ __forceinline__ float bfhi(unsigned w) { return __uint_as_float(w & 0xffff0000u); }
;     __device__ __forceinline__ void mid(f32x4 (&acc)[2][2][4][2], const Unit& u, int wr, int wc, int fr, int fq) const {
;     ...
;             for (int m = 0; m < 4; ++m) { const bf16_t* pr = P + (size_t)(row0 + ai * HALF + m * 16) * NP + col0;
; #pragma unroll
;                 for (int bj = 0; bj < 2; ++bj) { const u32x4 a = *(const u32x4*)(pr + PC_GA + bj * HALF), b = *(const u32x4*)(pr + PC_GB + bj * HALF);
;                     const f32x4 b0 = {bflo(b.x), bfhi(b.x), bflo(b.y), bfhi(b.y)}, b1 = {bflo(b.z), bfhi(b.z), bflo(b.w), bfhi(b.w)};
;                     const f32x4 a0 = {bflo(a.x), bfhi(a.x), bflo(a.y), bfhi(a.y)}, a1 = {bflo(a.z), bfhi(a.z), bflo(a.w), bfhi(a.w)};
;                     f32x4 r0, r1;
; #pragma unroll
;                     for (int j = 0; j < 4; ++j) { r0[j] = a0[j] * __builtin_amdgcn_rcpf(fmaxf(b0[j], 1e-30f)); r1[j] = a1[j] * __builtin_amdgcn_rcpf(fmaxf(b1[j], 1e-30f)); }
;                     acc[ai][bj][m][0] *= r0; acc[ai][bj][m][1] *= r1; }
	v_and_b32_e32 v177, 0xffff0000, v130
	v_lshlrev_b32_e32 v169, 16, v170
	v_max_f32_e32 v169, v169, v169
	v_lshlrev_b32_e32 v178, 16, v171
	v_and_b32_e32 v179, 0xffff0000, v171
	v_lshlrev_b32_e32 v171, 16, v172
	v_max_f32_e32 v169, 0xda24260, v169
	v_and_b32_e32 v176, 0xffff0000, v170
	v_rcp_f32_e32 v170, v169
	v_max_f32_e32 v169, v171, v171
	v_max_f32_e32 v169, 0xda24260, v169
	v_and_b32_e32 v180, 0xffff0000, v172
	v_rcp_f32_e32 v172, v169
	v_max_f32_e32 v169, v176, v176
	v_max_f32_e32 v169, 0xda24260, v169
	v_lshlrev_b32_e32 v176, 16, v130
	v_max_f32_e32 v130, v180, v180
	v_rcp_f32_e32 v171, v169
	v_max_f32_e32 v130, 0xda24260, v130
	v_lshlrev_b32_e32 v181, 16, v173
	v_and_b32_e32 v182, 0xffff0000, v173
	v_rcp_f32_e32 v173, v130
	v_max_f32_e32 v130, v178, v178
	v_pk_mul_f32 v[170:171], v[170:171], v[176:177]
	v_lshlrev_b32_e32 v176, 16, v132
	v_and_b32_e32 v177, 0xffff0000, v132
	v_max_f32_e32 v130, 0xda24260, v130
	v_pk_mul_f32 v[172:173], v[172:173], v[176:177]
	v_rcp_f32_e32 v176, v130
	v_max_f32_e32 v130, v181, v181
	v_lshlrev_b32_e32 v180, 16, v131
	v_and_b32_e32 v181, 0xffff0000, v131
	v_max_f32_e32 v131, v182, v182
	v_max_f32_e32 v130, 0xda24260, v130
	v_max_f32_e32 v131, 0xda24260, v131
	v_rcp_f32_e32 v130, v130
	v_rcp_f32_e32 v131, v131
	v_max_f32_e32 v132, v179, v179
	v_max_f32_e32 v132, 0xda24260, v132
	v_rcp_f32_e32 v177, v132
	v_lshlrev_b32_e32 v132, 16, v133
	v_and_b32_e32 v133, 0xffff0000, v133
	v_pk_mul_f32 v[130:131], v[130:131], v[132:133]
	v_pk_mul_f32 v[14:15], v[14:15], v[170:171]
	v_pk_mul_f32 v[12:13], v[12:13], v[130:131]
	v_pk_mul_f32 v[10:11], v[10:11], v[172:173]
	global_load_dwordx4 v[130:133], v[174:175], off offset:256
	global_load_dwordx4 v[170:173], v[158:159], off offset:256
	v_pk_mul_f32 v[176:177], v[176:177], v[180:181]
	s_waitcnt vmcnt(0)
	v_lshlrev_b32_e32 v158, 16, v170
	v_and_b32_e32 v159, 0xffff0000, v170
	v_lshlrev_b32_e32 v169, 16, v171
	v_and_b32_e32 v174, 0xffff0000, v171
	v_lshlrev_b32_e32 v170, 16, v172
	v_and_b32_e32 v171, 0xffff0000, v172
	v_max_f32_e32 v158, v158, v158
	v_max_f32_e32 v159, v159, v159
	v_pk_mul_f32 v[16:17], v[16:17], v[176:177]
	v_lshlrev_b32_e32 v175, 16, v173
	v_and_b32_e32 v176, 0xffff0000, v173
	v_max_f32_e32 v158, 0xda24260, v158
	v_max_f32_e32 v170, v170, v170
	v_max_f32_e32 v159, 0xda24260, v159
	v_lshlrev_b32_e32 v172, 16, v130
	v_and_b32_e32 v173, 0xffff0000, v130
	v_max_f32_e32 v130, v171, v171
	v_rcp_f32_e32 v158, v158
	v_max_f32_e32 v170, 0xda24260, v170
	v_rcp_f32_e32 v159, v159
	v_max_f32_e32 v130, 0xda24260, v130
	v_rcp_f32_e32 v170, v170
	v_rcp_f32_e32 v171, v130
	v_max_f32_e32 v130, v169, v169
	v_pk_mul_f32 v[158:159], v[158:159], v[172:173]
	v_lshlrev_b32_e32 v172, 16, v132
	v_and_b32_e32 v173, 0xffff0000, v132
	v_max_f32_e32 v130, 0xda24260, v130
	v_pk_mul_f32 v[170:171], v[170:171], v[172:173]
	v_rcp_f32_e32 v172, v130
	v_max_f32_e32 v130, v175, v175
	v_max_f32_e32 v132, v174, v174
	v_lshlrev_b32_e32 v174, 16, v131
	v_and_b32_e32 v175, 0xffff0000, v131
	v_max_f32_e32 v131, v176, v176
	v_max_f32_e32 v130, 0xda24260, v130
	v_max_f32_e32 v131, 0xda24260, v131
	v_rcp_f32_e32 v130, v130
	v_rcp_f32_e32 v131, v131
	v_max_f32_e32 v132, 0xda24260, v132
	v_rcp_f32_e32 v173, v132
	v_lshlrev_b32_e32 v132, 16, v133
	v_and_b32_e32 v133, 0xffff0000, v133
	v_pk_mul_f32 v[130:131], v[130:131], v[132:133]
	v_pk_mul_f32 v[30:31], v[30:31], v[158:159]
	v_pk_mul_f32 v[28:29], v[28:29], v[130:131]
	v_add_u32_e32 v130, 16, v168
	v_mad_i64_i32 v[158:159], s[58:59], v130, s78, v[156:157]
	v_pk_mul_f32 v[172:173], v[172:173], v[174:175]
	v_add_co_u32_e32 v174, vcc, s61, v158
	v_pk_mul_f32 v[32:33], v[32:33], v[172:173]
	s_nop 0
	v_addc_co_u32_e32 v175, vcc, 0, v159, vcc
	v_add_co_u32_e32 v158, vcc, s77, v158
	v_pk_mul_f32 v[26:27], v[26:27], v[170:171]
	s_nop 0
	v_addc_co_u32_e32 v159, vcc, 0, v159, vcc
	global_load_dwordx4 v[130:133], v[174:175], off
	global_load_dwordx4 v[170:173], v[158:159], off
	s_waitcnt vmcnt(1)
	v_and_b32_e32 v177, 0xffff0000, v130
	s_waitcnt vmcnt(0)
	v_lshlrev_b32_e32 v169, 16, v170
	v_max_f32_e32 v169, v169, v169
	v_lshlrev_b32_e32 v178, 16, v171
	v_and_b32_e32 v179, 0xffff0000, v171
	v_lshlrev_b32_e32 v171, 16, v172
	v_max_f32_e32 v169, 0xda24260, v169
	v_and_b32_e32 v176, 0xffff0000, v170
	v_rcp_f32_e32 v170, v169
	v_max_f32_e32 v169, v171, v171
	v_max_f32_e32 v169, 0xda24260, v169
	v_and_b32_e32 v180, 0xffff0000, v172
	v_rcp_f32_e32 v172, v169
	v_max_f32_e32 v169, v176, v176
	v_max_f32_e32 v169, 0xda24260, v169
	v_lshlrev_b32_e32 v176, 16, v130
	v_max_f32_e32 v130, v180, v180
	v_rcp_f32_e32 v171, v169
	v_max_f32_e32 v130, 0xda24260, v130
	v_lshlrev_b32_e32 v181, 16, v173
	v_and_b32_e32 v182, 0xffff0000, v173
	v_rcp_f32_e32 v173, v130
	v_max_f32_e32 v130, v178, v178
	v_pk_mul_f32 v[170:171], v[170:171], v[176:177]
	v_lshlrev_b32_e32 v176, 16, v132
	v_and_b32_e32 v177, 0xffff0000, v132
	v_max_f32_e32 v130, 0xda24260, v130
	v_pk_mul_f32 v[172:173], v[172:173], v[176:177]
	v_rcp_f32_e32 v176, v130
	v_max_f32_e32 v130, v181, v181
	v_lshlrev_b32_e32 v180, 16, v131
	v_and_b32_e32 v181, 0xffff0000, v131
	v_max_f32_e32 v131, v182, v182
	v_max_f32_e32 v130, 0xda24260, v130
	v_max_f32_e32 v131, 0xda24260, v131
	v_rcp_f32_e32 v130, v130
	v_rcp_f32_e32 v131, v131
	v_max_f32_e32 v132, v179, v179
	v_max_f32_e32 v132, 0xda24260, v132
	v_rcp_f32_e32 v177, v132
	v_lshlrev_b32_e32 v132, 16, v133
	v_and_b32_e32 v133, 0xffff0000, v133
	v_pk_mul_f32 v[130:131], v[130:131], v[132:133]
	v_pk_mul_f32 v[38:39], v[38:39], v[170:171]
	v_pk_mul_f32 v[36:37], v[36:37], v[130:131]
	v_pk_mul_f32 v[34:35], v[34:35], v[172:173]
	global_load_dwordx4 v[130:133], v[174:175], off offset:256
	global_load_dwordx4 v[170:173], v[158:159], off offset:256
	v_pk_mul_f32 v[176:177], v[176:177], v[180:181]
	s_waitcnt vmcnt(0)
; __device__ __forceinline__ float bflo(unsigned w) { return __uint_as_float(w << 16); }
; __device__ __forceinline__ float bfhi(unsigned w) { return __uint_as_float(w & 0xffff0000u); }
;     __device__ __forceinline__ void mid(f32x4 (&acc)[2][2][4][2], const Unit& u, int wr, int wc, int fr, int fq) const {
;     ...
;             for (int m = 0; m < 4; ++m) { const bf16_t* pr = P + (size_t)(row0 + ai * HALF + m * 16) * NP + col0;
; #pragma unroll
;                 for (int bj = 0; bj < 2; ++bj) { const u32x4 a = *(const u32x4*)(pr + PC_GA + bj * HALF), b = *(const u32x4*)(pr + PC_GB + bj * HALF);
;                     const f32x4 b0 = {bflo(b.x), bfhi(b.x), bflo(b.y), bfhi(b.y)}, b1 = {bflo(b.z), bfhi(b.z), bflo(b.w), bfhi(b.w)};
;                     const f32x4 a0 = {bflo(a.x), bfhi(a.x), bflo(a.y), bfhi(a.y)}, a1 = {bflo(a.z), bfhi(a.z), bflo(a.w), bfhi(a.w)};
;                     f32x4 r0, r1;
; #pragma unroll
;                     for (int j = 0; j < 4; ++j) { r0[j] = a0[j] * __builtin_amdgcn_rcpf(fmaxf(b0[j], 1e-30f)); r1[j] = a1[j] * __builtin_amdgcn_rcpf(fmaxf(b1[j], 1e-30f)); }
;                     acc[ai][bj][m][0] *= r0; acc[ai][bj][m][1] *= r1; }
	v_lshlrev_b32_e32 v158, 16, v170
	v_and_b32_e32 v159, 0xffff0000, v170
	v_lshlrev_b32_e32 v169, 16, v171
	v_and_b32_e32 v174, 0xffff0000, v171
	v_lshlrev_b32_e32 v170, 16, v172
	v_and_b32_e32 v171, 0xffff0000, v172
	v_max_f32_e32 v158, v158, v158
	v_max_f32_e32 v159, v159, v159
	v_pk_mul_f32 v[40:41], v[40:41], v[176:177]
	v_lshlrev_b32_e32 v175, 16, v173
	v_and_b32_e32 v176, 0xffff0000, v173
	v_max_f32_e32 v158, 0xda24260, v158
	v_max_f32_e32 v170, v170, v170
	v_max_f32_e32 v159, 0xda24260, v159
	v_lshlrev_b32_e32 v172, 16, v130
	v_and_b32_e32 v173, 0xffff0000, v130
	v_max_f32_e32 v130, v171, v171
	v_rcp_f32_e32 v158, v158
	v_max_f32_e32 v170, 0xda24260, v170
	v_rcp_f32_e32 v159, v159
	v_max_f32_e32 v130, 0xda24260, v130
	v_rcp_f32_e32 v170, v170
	v_rcp_f32_e32 v171, v130
	v_max_f32_e32 v130, v169, v169
	v_pk_mul_f32 v[158:159], v[158:159], v[172:173]
	v_lshlrev_b32_e32 v172, 16, v132
	v_and_b32_e32 v173, 0xffff0000, v132
	v_max_f32_e32 v130, 0xda24260, v130
	v_pk_mul_f32 v[170:171], v[170:171], v[172:173]
	v_rcp_f32_e32 v172, v130
	v_max_f32_e32 v130, v175, v175
	v_max_f32_e32 v132, v174, v174
	v_lshlrev_b32_e32 v174, 16, v131
	v_and_b32_e32 v175, 0xffff0000, v131
	v_max_f32_e32 v131, v176, v176
	v_max_f32_e32 v130, 0xda24260, v130
	v_max_f32_e32 v131, 0xda24260, v131
	v_rcp_f32_e32 v130, v130
	v_rcp_f32_e32 v131, v131
	v_max_f32_e32 v132, 0xda24260, v132
	v_rcp_f32_e32 v173, v132
	v_lshlrev_b32_e32 v132, 16, v133
	v_and_b32_e32 v133, 0xffff0000, v133
	v_pk_mul_f32 v[130:131], v[130:131], v[132:133]
	v_pk_mul_f32 v[54:55], v[54:55], v[158:159]
	v_pk_mul_f32 v[52:53], v[52:53], v[130:131]
	v_add_u32_e32 v130, 32, v168
	v_mad_i64_i32 v[158:159], s[58:59], v130, s78, v[156:157]
	v_pk_mul_f32 v[172:173], v[172:173], v[174:175]
	v_add_co_u32_e32 v174, vcc, s61, v158
	v_pk_mul_f32 v[56:57], v[56:57], v[172:173]
	s_nop 0
	v_addc_co_u32_e32 v175, vcc, 0, v159, vcc
	v_add_co_u32_e32 v158, vcc, s77, v158
	v_pk_mul_f32 v[50:51], v[50:51], v[170:171]
	s_nop 0
	v_addc_co_u32_e32 v159, vcc, 0, v159, vcc
	global_load_dwordx4 v[130:133], v[174:175], off
	global_load_dwordx4 v[170:173], v[158:159], off
	s_waitcnt vmcnt(1)
	v_and_b32_e32 v177, 0xffff0000, v130
	s_waitcnt vmcnt(0)
	v_lshlrev_b32_e32 v169, 16, v170
	v_max_f32_e32 v169, v169, v169
	v_lshlrev_b32_e32 v178, 16, v171
	v_and_b32_e32 v179, 0xffff0000, v171
	v_lshlrev_b32_e32 v171, 16, v172
	v_max_f32_e32 v169, 0xda24260, v169
	v_and_b32_e32 v176, 0xffff0000, v170
	v_rcp_f32_e32 v170, v169
	v_max_f32_e32 v169, v171, v171
	v_max_f32_e32 v169, 0xda24260, v169
	v_and_b32_e32 v180, 0xffff0000, v172
	v_rcp_f32_e32 v172, v169
	v_max_f32_e32 v169, v176, v176
	v_max_f32_e32 v169, 0xda24260, v169
	v_lshlrev_b32_e32 v176, 16, v130
	v_max_f32_e32 v130, v180, v180
	v_rcp_f32_e32 v171, v169
	v_max_f32_e32 v130, 0xda24260, v130
	v_lshlrev_b32_e32 v181, 16, v173
	v_and_b32_e32 v182, 0xffff0000, v173
	v_rcp_f32_e32 v173, v130
	v_max_f32_e32 v130, v178, v178
	v_pk_mul_f32 v[170:171], v[170:171], v[176:177]
	v_lshlrev_b32_e32 v176, 16, v132
	v_and_b32_e32 v177, 0xffff0000, v132
	v_max_f32_e32 v130, 0xda24260, v130
	v_pk_mul_f32 v[172:173], v[172:173], v[176:177]
	v_rcp_f32_e32 v176, v130
	v_max_f32_e32 v130, v181, v181
	v_lshlrev_b32_e32 v180, 16, v131
	v_and_b32_e32 v181, 0xffff0000, v131
	v_max_f32_e32 v131, v182, v182
	v_max_f32_e32 v130, 0xda24260, v130
	v_max_f32_e32 v131, 0xda24260, v131
	v_rcp_f32_e32 v130, v130
	v_rcp_f32_e32 v131, v131
	v_max_f32_e32 v132, v179, v179
	v_max_f32_e32 v132, 0xda24260, v132
	v_rcp_f32_e32 v177, v132
	v_lshlrev_b32_e32 v132, 16, v133
	v_and_b32_e32 v133, 0xffff0000, v133
	v_pk_mul_f32 v[130:131], v[130:131], v[132:133]
	v_pk_mul_f32 v[70:71], v[70:71], v[170:171]
	v_pk_mul_f32 v[68:69], v[68:69], v[130:131]
	v_pk_mul_f32 v[66:67], v[66:67], v[172:173]
	global_load_dwordx4 v[130:133], v[174:175], off offset:256
	global_load_dwordx4 v[170:173], v[158:159], off offset:256
	v_pk_mul_f32 v[176:177], v[176:177], v[180:181]
	s_waitcnt vmcnt(0)
	v_lshlrev_b32_e32 v158, 16, v170
	v_and_b32_e32 v159, 0xffff0000, v170
	v_lshlrev_b32_e32 v169, 16, v171
	v_and_b32_e32 v174, 0xffff0000, v171
	v_lshlrev_b32_e32 v170, 16, v172
	v_and_b32_e32 v171, 0xffff0000, v172
	v_max_f32_e32 v158, v158, v158
	v_max_f32_e32 v159, v159, v159
	v_pk_mul_f32 v[72:73], v[72:73], v[176:177]
	v_lshlrev_b32_e32 v175, 16, v173
	v_and_b32_e32 v176, 0xffff0000, v173
	v_max_f32_e32 v158, 0xda24260, v158
	v_max_f32_e32 v170, v170, v170
	v_max_f32_e32 v159, 0xda24260, v159
	v_lshlrev_b32_e32 v172, 16, v130
	v_and_b32_e32 v173, 0xffff0000, v130
	v_max_f32_e32 v130, v171, v171
	v_rcp_f32_e32 v158, v158
	v_max_f32_e32 v170, 0xda24260, v170
	v_rcp_f32_e32 v159, v159
	v_max_f32_e32 v130, 0xda24260, v130
	v_rcp_f32_e32 v170, v170
	v_rcp_f32_e32 v171, v130
	v_max_f32_e32 v130, v169, v169
	v_pk_mul_f32 v[158:159], v[158:159], v[172:173]
	v_lshlrev_b32_e32 v172, 16, v132
	v_and_b32_e32 v173, 0xffff0000, v132
	v_max_f32_e32 v130, 0xda24260, v130
	v_pk_mul_f32 v[170:171], v[170:171], v[172:173]
	v_rcp_f32_e32 v172, v130
	v_max_f32_e32 v130, v175, v175
	v_max_f32_e32 v132, v174, v174
	v_lshlrev_b32_e32 v174, 16, v131
	v_and_b32_e32 v175, 0xffff0000, v131
	v_max_f32_e32 v131, v176, v176
	v_max_f32_e32 v130, 0xda24260, v130
	v_max_f32_e32 v131, 0xda24260, v131
	v_rcp_f32_e32 v130, v130
	v_rcp_f32_e32 v131, v131
	v_max_f32_e32 v132, 0xda24260, v132
	v_rcp_f32_e32 v173, v132
	v_lshlrev_b32_e32 v132, 16, v133
	v_and_b32_e32 v133, 0xffff0000, v133
	v_pk_mul_f32 v[130:131], v[130:131], v[132:133]
	v_pk_mul_f32 v[86:87], v[86:87], v[158:159]
	v_pk_mul_f32 v[84:85], v[84:85], v[130:131]
	v_add_u32_e32 v130, 48, v168
	v_mad_i64_i32 v[158:159], s[58:59], v130, s78, v[156:157]
	v_pk_mul_f32 v[172:173], v[172:173], v[174:175]
	v_add_co_u32_e32 v174, vcc, s61, v158
	v_pk_mul_f32 v[88:89], v[88:89], v[172:173]
	s_nop 0
	v_addc_co_u32_e32 v175, vcc, 0, v159, vcc
	v_add_co_u32_e32 v158, vcc, s77, v158
	v_pk_mul_f32 v[82:83], v[82:83], v[170:171]
	s_nop 0
	v_addc_co_u32_e32 v159, vcc, 0, v159, vcc
	global_load_dwordx4 v[130:133], v[174:175], off
	global_load_dwordx4 v[170:173], v[158:159], off
	s_waitcnt vmcnt(1)
; __device__ __forceinline__ float bflo(unsigned w) { return __uint_as_float(w << 16); }
; __device__ __forceinline__ float bfhi(unsigned w) { return __uint_as_float(w & 0xffff0000u); }
;     __device__ __forceinline__ void mid(f32x4 (&acc)[2][2][4][2], const Unit& u, int wr, int wc, int fr, int fq) const {
;     ...
;             for (int m = 0; m < 4; ++m) { const bf16_t* pr = P + (size_t)(row0 + ai * HALF + m * 16) * NP + col0;
; #pragma unroll
;                 for (int bj = 0; bj < 2; ++bj) { const u32x4 a = *(const u32x4*)(pr + PC_GA + bj * HALF), b = *(const u32x4*)(pr + PC_GB + bj * HALF);
;                     const f32x4 b0 = {bflo(b.x), bfhi(b.x), bflo(b.y), bfhi(b.y)}, b1 = {bflo(b.z), bfhi(b.z), bflo(b.w), bfhi(b.w)};
;                     const f32x4 a0 = {bflo(a.x), bfhi(a.x), bflo(a.y), bfhi(a.y)}, a1 = {bflo(a.z), bfhi(a.z), bflo(a.w), bfhi(a.w)};
;                     f32x4 r0, r1;
; #pragma unroll
;                     for (int j = 0; j < 4; ++j) { r0[j] = a0[j] * __builtin_amdgcn_rcpf(fmaxf(b0[j], 1e-30f)); r1[j] = a1[j] * __builtin_amdgcn_rcpf(fmaxf(b1[j], 1e-30f)); }
;                     acc[ai][bj][m][0] *= r0; acc[ai][bj][m][1] *= r1; }
	v_and_b32_e32 v177, 0xffff0000, v130
	s_waitcnt vmcnt(0)
	v_lshlrev_b32_e32 v169, 16, v170
	v_max_f32_e32 v169, v169, v169
	v_lshlrev_b32_e32 v178, 16, v171
	v_and_b32_e32 v179, 0xffff0000, v171
	v_lshlrev_b32_e32 v171, 16, v172
	v_max_f32_e32 v169, 0xda24260, v169
	v_and_b32_e32 v176, 0xffff0000, v170
	v_rcp_f32_e32 v170, v169
	v_max_f32_e32 v169, v171, v171
	v_max_f32_e32 v169, 0xda24260, v169
	v_and_b32_e32 v180, 0xffff0000, v172
	v_rcp_f32_e32 v172, v169
	v_max_f32_e32 v169, v176, v176
	v_max_f32_e32 v169, 0xda24260, v169
	v_lshlrev_b32_e32 v176, 16, v130
	v_max_f32_e32 v130, v180, v180
	v_rcp_f32_e32 v171, v169
	v_max_f32_e32 v130, 0xda24260, v130
	v_lshlrev_b32_e32 v181, 16, v173
	v_and_b32_e32 v182, 0xffff0000, v173
	v_rcp_f32_e32 v173, v130
	v_max_f32_e32 v130, v178, v178
	v_pk_mul_f32 v[170:171], v[170:171], v[176:177]
	v_lshlrev_b32_e32 v176, 16, v132
	v_and_b32_e32 v177, 0xffff0000, v132
	v_max_f32_e32 v130, 0xda24260, v130
	v_pk_mul_f32 v[172:173], v[172:173], v[176:177]
	v_rcp_f32_e32 v176, v130
	v_max_f32_e32 v130, v181, v181
	v_lshlrev_b32_e32 v180, 16, v131
	v_and_b32_e32 v181, 0xffff0000, v131
	v_max_f32_e32 v131, v182, v182
	v_max_f32_e32 v130, 0xda24260, v130
	v_max_f32_e32 v131, 0xda24260, v131
	v_rcp_f32_e32 v130, v130
	v_rcp_f32_e32 v131, v131
	v_max_f32_e32 v132, v179, v179
	v_max_f32_e32 v132, 0xda24260, v132
	v_rcp_f32_e32 v177, v132
	v_lshlrev_b32_e32 v132, 16, v133
	v_and_b32_e32 v133, 0xffff0000, v133
	v_pk_mul_f32 v[130:131], v[130:131], v[132:133]
	v_pk_mul_f32 v[94:95], v[94:95], v[170:171]
	v_pk_mul_f32 v[92:93], v[92:93], v[130:131]
	v_pk_mul_f32 v[90:91], v[90:91], v[172:173]
	global_load_dwordx4 v[130:133], v[174:175], off offset:256
	global_load_dwordx4 v[170:173], v[158:159], off offset:256
	v_pk_mul_f32 v[176:177], v[176:177], v[180:181]
	s_waitcnt vmcnt(0)
	v_lshlrev_b32_e32 v158, 16, v170
	v_and_b32_e32 v159, 0xffff0000, v170
	v_lshlrev_b32_e32 v169, 16, v171
	v_and_b32_e32 v174, 0xffff0000, v171
	v_lshlrev_b32_e32 v170, 16, v172
	v_and_b32_e32 v171, 0xffff0000, v172
	v_max_f32_e32 v158, v158, v158
	v_max_f32_e32 v159, v159, v159
	v_pk_mul_f32 v[96:97], v[96:97], v[176:177]
	v_lshlrev_b32_e32 v175, 16, v173
	v_and_b32_e32 v176, 0xffff0000, v173
	v_max_f32_e32 v158, 0xda24260, v158
	v_max_f32_e32 v170, v170, v170
	v_max_f32_e32 v159, 0xda24260, v159
	v_lshlrev_b32_e32 v172, 16, v130
	v_and_b32_e32 v173, 0xffff0000, v130
	v_max_f32_e32 v130, v171, v171
	v_rcp_f32_e32 v158, v158
	v_max_f32_e32 v170, 0xda24260, v170
	v_rcp_f32_e32 v159, v159
	v_max_f32_e32 v130, 0xda24260, v130
	v_rcp_f32_e32 v170, v170
	v_rcp_f32_e32 v171, v130
	v_max_f32_e32 v130, v169, v169
	v_pk_mul_f32 v[158:159], v[158:159], v[172:173]
	v_lshlrev_b32_e32 v172, 16, v132
	v_and_b32_e32 v173, 0xffff0000, v132
	v_max_f32_e32 v130, 0xda24260, v130
	v_pk_mul_f32 v[170:171], v[170:171], v[172:173]
	v_rcp_f32_e32 v172, v130
	v_max_f32_e32 v130, v175, v175
	v_max_f32_e32 v132, v174, v174
	v_lshlrev_b32_e32 v174, 16, v131
	v_and_b32_e32 v175, 0xffff0000, v131
	v_max_f32_e32 v131, v176, v176
	v_max_f32_e32 v130, 0xda24260, v130
	v_max_f32_e32 v131, 0xda24260, v131
	v_rcp_f32_e32 v130, v130
	v_rcp_f32_e32 v131, v131
	v_max_f32_e32 v132, 0xda24260, v132
	v_rcp_f32_e32 v173, v132
	v_lshlrev_b32_e32 v132, 16, v133
	v_and_b32_e32 v133, 0xffff0000, v133
	v_pk_mul_f32 v[130:131], v[130:131], v[132:133]
	v_pk_mul_f32 v[110:111], v[110:111], v[158:159]
	v_pk_mul_f32 v[108:109], v[108:109], v[130:131]
	v_add_u32_e32 v130, 0x80, v168
	v_mad_i64_i32 v[158:159], s[58:59], v130, s78, v[156:157]
	v_pk_mul_f32 v[172:173], v[172:173], v[174:175]
	v_add_co_u32_e32 v174, vcc, s61, v158
	v_pk_mul_f32 v[112:113], v[112:113], v[172:173]
	s_nop 0
	v_addc_co_u32_e32 v175, vcc, 0, v159, vcc
	v_add_co_u32_e32 v158, vcc, s77, v158
	v_pk_mul_f32 v[106:107], v[106:107], v[170:171]
	s_nop 0
	v_addc_co_u32_e32 v159, vcc, 0, v159, vcc
	global_load_dwordx4 v[130:133], v[174:175], off
	global_load_dwordx4 v[170:173], v[158:159], off
	s_waitcnt vmcnt(1)
	v_and_b32_e32 v177, 0xffff0000, v130
	s_waitcnt vmcnt(0)
	v_lshlrev_b32_e32 v169, 16, v170
	v_max_f32_e32 v169, v169, v169
	v_lshlrev_b32_e32 v178, 16, v171
	v_and_b32_e32 v179, 0xffff0000, v171
	v_lshlrev_b32_e32 v171, 16, v172
	v_max_f32_e32 v169, 0xda24260, v169
	v_and_b32_e32 v176, 0xffff0000, v170
	v_rcp_f32_e32 v170, v169
	v_max_f32_e32 v169, v171, v171
	v_max_f32_e32 v169, 0xda24260, v169
	v_and_b32_e32 v180, 0xffff0000, v172
	v_rcp_f32_e32 v172, v169
	v_max_f32_e32 v169, v176, v176
	v_max_f32_e32 v169, 0xda24260, v169
	v_lshlrev_b32_e32 v176, 16, v130
	v_max_f32_e32 v130, v180, v180
	v_rcp_f32_e32 v171, v169
	v_max_f32_e32 v130, 0xda24260, v130
	v_lshlrev_b32_e32 v181, 16, v173
	v_and_b32_e32 v182, 0xffff0000, v173
	v_rcp_f32_e32 v173, v130
	v_max_f32_e32 v130, v178, v178
	v_pk_mul_f32 v[170:171], v[170:171], v[176:177]
	v_lshlrev_b32_e32 v176, 16, v132
	v_and_b32_e32 v177, 0xffff0000, v132
	v_max_f32_e32 v130, 0xda24260, v130
	v_pk_mul_f32 v[172:173], v[172:173], v[176:177]
	v_rcp_f32_e32 v176, v130
	v_max_f32_e32 v130, v181, v181
	v_lshlrev_b32_e32 v180, 16, v131
	v_and_b32_e32 v181, 0xffff0000, v131
	v_max_f32_e32 v131, v182, v182
	v_max_f32_e32 v130, 0xda24260, v130
	v_max_f32_e32 v131, 0xda24260, v131
	v_rcp_f32_e32 v130, v130
	v_rcp_f32_e32 v131, v131
	v_max_f32_e32 v132, v179, v179
	v_max_f32_e32 v132, 0xda24260, v132
	v_rcp_f32_e32 v177, v132
	v_lshlrev_b32_e32 v132, 16, v133
	v_and_b32_e32 v133, 0xffff0000, v133
	v_pk_mul_f32 v[130:131], v[130:131], v[132:133]
	v_pk_mul_f32 v[126:127], v[126:127], v[170:171]
	v_pk_mul_f32 v[124:125], v[124:125], v[130:131]
	v_pk_mul_f32 v[122:123], v[122:123], v[172:173]
	global_load_dwordx4 v[130:133], v[174:175], off offset:256
	global_load_dwordx4 v[170:173], v[158:159], off offset:256
	v_pk_mul_f32 v[176:177], v[176:177], v[180:181]
	s_waitcnt vmcnt(0)
; __device__ __forceinline__ float bflo(unsigned w) { return __uint_as_float(w << 16); }
; __device__ __forceinline__ float bfhi(unsigned w) { return __uint_as_float(w & 0xffff0000u); }
;     __device__ __forceinline__ void mid(f32x4 (&acc)[2][2][4][2], const Unit& u, int wr, int wc, int fr, int fq) const {
;     ...
;             for (int m = 0; m < 4; ++m) { const bf16_t* pr = P + (size_t)(row0 + ai * HALF + m * 16) * NP + col0;
; #pragma unroll
;                 for (int bj = 0; bj < 2; ++bj) { const u32x4 a = *(const u32x4*)(pr + PC_GA + bj * HALF), b = *(const u32x4*)(pr + PC_GB + bj * HALF);
;                     const f32x4 b0 = {bflo(b.x), bfhi(b.x), bflo(b.y), bfhi(b.y)}, b1 = {bflo(b.z), bfhi(b.z), bflo(b.w), bfhi(b.w)};
;                     const f32x4 a0 = {bflo(a.x), bfhi(a.x), bflo(a.y), bfhi(a.y)}, a1 = {bflo(a.z), bfhi(a.z), bflo(a.w), bfhi(a.w)};
;                     f32x4 r0, r1;
; #pragma unroll
;                     for (int j = 0; j < 4; ++j) { r0[j] = a0[j] * __builtin_amdgcn_rcpf(fmaxf(b0[j], 1e-30f)); r1[j] = a1[j] * __builtin_amdgcn_rcpf(fmaxf(b1[j], 1e-30f)); }
;                     acc[ai][bj][m][0] *= r0; acc[ai][bj][m][1] *= r1; }
	v_lshlrev_b32_e32 v158, 16, v170
	v_and_b32_e32 v159, 0xffff0000, v170
	v_lshlrev_b32_e32 v169, 16, v171
	v_and_b32_e32 v174, 0xffff0000, v171
	v_lshlrev_b32_e32 v170, 16, v172
	v_and_b32_e32 v171, 0xffff0000, v172
	v_max_f32_e32 v158, v158, v158
	v_max_f32_e32 v159, v159, v159
	v_pk_mul_f32 v[128:129], v[128:129], v[176:177]
	v_lshlrev_b32_e32 v175, 16, v173
	v_and_b32_e32 v176, 0xffff0000, v173
	v_max_f32_e32 v158, 0xda24260, v158
	v_max_f32_e32 v170, v170, v170
	v_max_f32_e32 v159, 0xda24260, v159
	v_lshlrev_b32_e32 v172, 16, v130
	v_and_b32_e32 v173, 0xffff0000, v130
	v_max_f32_e32 v130, v171, v171
	v_rcp_f32_e32 v158, v158
	v_max_f32_e32 v170, 0xda24260, v170
	v_rcp_f32_e32 v159, v159
	v_max_f32_e32 v130, 0xda24260, v130
	v_rcp_f32_e32 v170, v170
	v_rcp_f32_e32 v171, v130
	v_max_f32_e32 v130, v169, v169
	v_pk_mul_f32 v[158:159], v[158:159], v[172:173]
	v_lshlrev_b32_e32 v172, 16, v132
	v_and_b32_e32 v173, 0xffff0000, v132
	v_max_f32_e32 v130, 0xda24260, v130
	v_pk_mul_f32 v[170:171], v[170:171], v[172:173]
	v_rcp_f32_e32 v172, v130
	v_max_f32_e32 v130, v175, v175
	v_max_f32_e32 v132, v174, v174
	v_lshlrev_b32_e32 v174, 16, v131
	v_and_b32_e32 v175, 0xffff0000, v131
	v_max_f32_e32 v131, v176, v176
	v_max_f32_e32 v130, 0xda24260, v130
	v_max_f32_e32 v131, 0xda24260, v131
	v_rcp_f32_e32 v130, v130
	v_rcp_f32_e32 v131, v131
	v_max_f32_e32 v132, 0xda24260, v132
	v_rcp_f32_e32 v173, v132
	v_lshlrev_b32_e32 v132, 16, v133
	v_and_b32_e32 v133, 0xffff0000, v133
	v_pk_mul_f32 v[130:131], v[130:131], v[132:133]
	v_pk_mul_f32 v[118:119], v[118:119], v[158:159]
	v_pk_mul_f32 v[116:117], v[116:117], v[130:131]
	v_add_u32_e32 v130, 0x90, v168
	v_mad_i64_i32 v[158:159], s[58:59], v130, s78, v[156:157]
	v_pk_mul_f32 v[172:173], v[172:173], v[174:175]
	v_add_co_u32_e32 v174, vcc, s61, v158
	v_pk_mul_f32 v[120:121], v[120:121], v[172:173]
	s_nop 0
	v_addc_co_u32_e32 v175, vcc, 0, v159, vcc
	v_add_co_u32_e32 v158, vcc, s77, v158
	v_pk_mul_f32 v[114:115], v[114:115], v[170:171]
	s_nop 0
	v_addc_co_u32_e32 v159, vcc, 0, v159, vcc
	global_load_dwordx4 v[130:133], v[174:175], off
	global_load_dwordx4 v[170:173], v[158:159], off
	s_waitcnt vmcnt(1)
	v_and_b32_e32 v177, 0xffff0000, v130
	s_waitcnt vmcnt(0)
	v_lshlrev_b32_e32 v169, 16, v170
	v_max_f32_e32 v169, v169, v169
	v_lshlrev_b32_e32 v178, 16, v171
	v_and_b32_e32 v179, 0xffff0000, v171
	v_lshlrev_b32_e32 v171, 16, v172
	v_max_f32_e32 v169, 0xda24260, v169
	v_and_b32_e32 v176, 0xffff0000, v170
	v_rcp_f32_e32 v170, v169
	v_max_f32_e32 v169, v171, v171
	v_max_f32_e32 v169, 0xda24260, v169
	v_and_b32_e32 v180, 0xffff0000, v172
	v_rcp_f32_e32 v172, v169
	v_max_f32_e32 v169, v176, v176
	v_max_f32_e32 v169, 0xda24260, v169
	v_lshlrev_b32_e32 v176, 16, v130
	v_max_f32_e32 v130, v180, v180
	v_rcp_f32_e32 v171, v169
	v_max_f32_e32 v130, 0xda24260, v130
	v_lshlrev_b32_e32 v181, 16, v173
	v_and_b32_e32 v182, 0xffff0000, v173
	v_rcp_f32_e32 v173, v130
	v_max_f32_e32 v130, v178, v178
	v_pk_mul_f32 v[170:171], v[170:171], v[176:177]
	v_lshlrev_b32_e32 v176, 16, v132
	v_and_b32_e32 v177, 0xffff0000, v132
	v_max_f32_e32 v130, 0xda24260, v130
	v_pk_mul_f32 v[172:173], v[172:173], v[176:177]
	v_rcp_f32_e32 v176, v130
	v_max_f32_e32 v130, v181, v181
	v_lshlrev_b32_e32 v180, 16, v131
	v_and_b32_e32 v181, 0xffff0000, v131
	v_max_f32_e32 v131, v182, v182
	v_max_f32_e32 v130, 0xda24260, v130
	v_max_f32_e32 v131, 0xda24260, v131
	v_rcp_f32_e32 v130, v130
	v_rcp_f32_e32 v131, v131
	v_max_f32_e32 v132, v179, v179
	v_max_f32_e32 v132, 0xda24260, v132
	v_rcp_f32_e32 v177, v132
	v_lshlrev_b32_e32 v132, 16, v133
	v_and_b32_e32 v133, 0xffff0000, v133
	v_pk_mul_f32 v[130:131], v[130:131], v[132:133]
	v_pk_mul_f32 v[102:103], v[102:103], v[170:171]
	v_pk_mul_f32 v[100:101], v[100:101], v[130:131]
	v_pk_mul_f32 v[98:99], v[98:99], v[172:173]
	global_load_dwordx4 v[130:133], v[174:175], off offset:256
	global_load_dwordx4 v[170:173], v[158:159], off offset:256
	v_pk_mul_f32 v[176:177], v[176:177], v[180:181]
	s_waitcnt vmcnt(0)
	v_lshlrev_b32_e32 v158, 16, v170
	v_and_b32_e32 v159, 0xffff0000, v170
	v_lshlrev_b32_e32 v169, 16, v171
	v_and_b32_e32 v174, 0xffff0000, v171
	v_lshlrev_b32_e32 v170, 16, v172
	v_and_b32_e32 v171, 0xffff0000, v172
	v_max_f32_e32 v158, v158, v158
	v_max_f32_e32 v159, v159, v159
	v_pk_mul_f32 v[104:105], v[104:105], v[176:177]
	v_lshlrev_b32_e32 v175, 16, v173
	v_and_b32_e32 v176, 0xffff0000, v173
	v_max_f32_e32 v158, 0xda24260, v158
	v_max_f32_e32 v170, v170, v170
	v_max_f32_e32 v159, 0xda24260, v159
	v_lshlrev_b32_e32 v172, 16, v130
	v_and_b32_e32 v173, 0xffff0000, v130
	v_max_f32_e32 v130, v171, v171
	v_rcp_f32_e32 v158, v158
	v_max_f32_e32 v170, 0xda24260, v170
	v_rcp_f32_e32 v159, v159
	v_max_f32_e32 v130, 0xda24260, v130
	v_rcp_f32_e32 v170, v170
	v_rcp_f32_e32 v171, v130
	v_max_f32_e32 v130, v169, v169
	v_pk_mul_f32 v[158:159], v[158:159], v[172:173]
	v_lshlrev_b32_e32 v172, 16, v132
	v_and_b32_e32 v173, 0xffff0000, v132
	v_max_f32_e32 v130, 0xda24260, v130
	v_pk_mul_f32 v[170:171], v[170:171], v[172:173]
	v_rcp_f32_e32 v172, v130
	v_max_f32_e32 v130, v175, v175
	v_max_f32_e32 v132, v174, v174
	v_lshlrev_b32_e32 v174, 16, v131
	v_and_b32_e32 v175, 0xffff0000, v131
	v_max_f32_e32 v131, v176, v176
	v_max_f32_e32 v130, 0xda24260, v130
	v_max_f32_e32 v131, 0xda24260, v131
	v_rcp_f32_e32 v130, v130
	v_rcp_f32_e32 v131, v131
	v_max_f32_e32 v132, 0xda24260, v132
	v_rcp_f32_e32 v173, v132
	v_lshlrev_b32_e32 v132, 16, v133
	v_and_b32_e32 v133, 0xffff0000, v133
	v_pk_mul_f32 v[130:131], v[130:131], v[132:133]
	v_pk_mul_f32 v[78:79], v[78:79], v[158:159]
	v_pk_mul_f32 v[76:77], v[76:77], v[130:131]
	v_add_u32_e32 v130, 0xa0, v168
	v_mad_i64_i32 v[158:159], s[58:59], v130, s78, v[156:157]
	v_pk_mul_f32 v[172:173], v[172:173], v[174:175]
	v_add_co_u32_e32 v174, vcc, s61, v158
	v_pk_mul_f32 v[80:81], v[80:81], v[172:173]
	s_nop 0
	v_addc_co_u32_e32 v175, vcc, 0, v159, vcc
	v_add_co_u32_e32 v158, vcc, s77, v158
	v_pk_mul_f32 v[74:75], v[74:75], v[170:171]
	s_nop 0
	v_addc_co_u32_e32 v159, vcc, 0, v159, vcc
	global_load_dwordx4 v[130:133], v[174:175], off
	global_load_dwordx4 v[170:173], v[158:159], off
	s_waitcnt vmcnt(1)
; __device__ __forceinline__ float bflo(unsigned w) { return __uint_as_float(w << 16); }
; __device__ __forceinline__ float bfhi(unsigned w) { return __uint_as_float(w & 0xffff0000u); }
;     __device__ __forceinline__ void mid(f32x4 (&acc)[2][2][4][2], const Unit& u, int wr, int wc, int fr, int fq) const {
;     ...
;             for (int m = 0; m < 4; ++m) { const bf16_t* pr = P + (size_t)(row0 + ai * HALF + m * 16) * NP + col0;
; #pragma unroll
;                 for (int bj = 0; bj < 2; ++bj) { const u32x4 a = *(const u32x4*)(pr + PC_GA + bj * HALF), b = *(const u32x4*)(pr + PC_GB + bj * HALF);
;                     const f32x4 b0 = {bflo(b.x), bfhi(b.x), bflo(b.y), bfhi(b.y)}, b1 = {bflo(b.z), bfhi(b.z), bflo(b.w), bfhi(b.w)};
;                     const f32x4 a0 = {bflo(a.x), bfhi(a.x), bflo(a.y), bfhi(a.y)}, a1 = {bflo(a.z), bfhi(a.z), bflo(a.w), bfhi(a.w)};
;                     f32x4 r0, r1;
; #pragma unroll
;                     for (int j = 0; j < 4; ++j) { r0[j] = a0[j] * __builtin_amdgcn_rcpf(fmaxf(b0[j], 1e-30f)); r1[j] = a1[j] * __builtin_amdgcn_rcpf(fmaxf(b1[j], 1e-30f)); }
;                     acc[ai][bj][m][0] *= r0; acc[ai][bj][m][1] *= r1; }
	v_and_b32_e32 v177, 0xffff0000, v130
	s_waitcnt vmcnt(0)
	v_lshlrev_b32_e32 v169, 16, v170
	v_max_f32_e32 v169, v169, v169
	v_lshlrev_b32_e32 v178, 16, v171
	v_and_b32_e32 v179, 0xffff0000, v171
	v_lshlrev_b32_e32 v171, 16, v172
	v_max_f32_e32 v169, 0xda24260, v169
	v_and_b32_e32 v176, 0xffff0000, v170
	v_rcp_f32_e32 v170, v169
	v_max_f32_e32 v169, v171, v171
	v_max_f32_e32 v169, 0xda24260, v169
	v_and_b32_e32 v180, 0xffff0000, v172
	v_rcp_f32_e32 v172, v169
	v_max_f32_e32 v169, v176, v176
	v_max_f32_e32 v169, 0xda24260, v169
	v_lshlrev_b32_e32 v176, 16, v130
	v_max_f32_e32 v130, v180, v180
	v_rcp_f32_e32 v171, v169
	v_max_f32_e32 v130, 0xda24260, v130
	v_lshlrev_b32_e32 v181, 16, v173
	v_and_b32_e32 v182, 0xffff0000, v173
	v_rcp_f32_e32 v173, v130
	v_max_f32_e32 v130, v178, v178
	v_pk_mul_f32 v[170:171], v[170:171], v[176:177]
	v_lshlrev_b32_e32 v176, 16, v132
	v_and_b32_e32 v177, 0xffff0000, v132
	v_max_f32_e32 v130, 0xda24260, v130
	v_pk_mul_f32 v[172:173], v[172:173], v[176:177]
	v_rcp_f32_e32 v176, v130
	v_max_f32_e32 v130, v181, v181
	v_lshlrev_b32_e32 v180, 16, v131
	v_and_b32_e32 v181, 0xffff0000, v131
	v_max_f32_e32 v131, v182, v182
	v_max_f32_e32 v130, 0xda24260, v130
	v_max_f32_e32 v131, 0xda24260, v131
	v_rcp_f32_e32 v130, v130
	v_rcp_f32_e32 v131, v131
	v_max_f32_e32 v132, v179, v179
	v_max_f32_e32 v132, 0xda24260, v132
	v_rcp_f32_e32 v177, v132
	v_lshlrev_b32_e32 v132, 16, v133
	v_and_b32_e32 v133, 0xffff0000, v133
	v_pk_mul_f32 v[130:131], v[130:131], v[132:133]
	v_pk_mul_f32 v[62:63], v[62:63], v[170:171]
	v_pk_mul_f32 v[60:61], v[60:61], v[130:131]
	v_pk_mul_f32 v[58:59], v[58:59], v[172:173]
	global_load_dwordx4 v[130:133], v[174:175], off offset:256
	global_load_dwordx4 v[170:173], v[158:159], off offset:256
	v_pk_mul_f32 v[176:177], v[176:177], v[180:181]
	s_waitcnt vmcnt(0)
	v_lshlrev_b32_e32 v158, 16, v170
	v_and_b32_e32 v159, 0xffff0000, v170
	v_lshlrev_b32_e32 v169, 16, v171
	v_and_b32_e32 v174, 0xffff0000, v171
	v_lshlrev_b32_e32 v170, 16, v172
	v_and_b32_e32 v171, 0xffff0000, v172
	v_max_f32_e32 v158, v158, v158
	v_max_f32_e32 v159, v159, v159
	v_pk_mul_f32 v[64:65], v[64:65], v[176:177]
	v_lshlrev_b32_e32 v175, 16, v173
	v_and_b32_e32 v176, 0xffff0000, v173
	v_max_f32_e32 v158, 0xda24260, v158
	v_max_f32_e32 v170, v170, v170
	v_max_f32_e32 v159, 0xda24260, v159
	v_lshlrev_b32_e32 v172, 16, v130
	v_and_b32_e32 v173, 0xffff0000, v130
	v_max_f32_e32 v130, v171, v171
	v_rcp_f32_e32 v158, v158
	v_max_f32_e32 v170, 0xda24260, v170
	v_rcp_f32_e32 v159, v159
	v_max_f32_e32 v130, 0xda24260, v130
	v_rcp_f32_e32 v170, v170
	v_rcp_f32_e32 v171, v130
	v_max_f32_e32 v130, v169, v169
	v_pk_mul_f32 v[158:159], v[158:159], v[172:173]
	v_lshlrev_b32_e32 v172, 16, v132
	v_and_b32_e32 v173, 0xffff0000, v132
	v_max_f32_e32 v130, 0xda24260, v130
	v_pk_mul_f32 v[170:171], v[170:171], v[172:173]
	v_rcp_f32_e32 v172, v130
	v_max_f32_e32 v130, v175, v175
	v_max_f32_e32 v132, v174, v174
	v_lshlrev_b32_e32 v174, 16, v131
	v_and_b32_e32 v175, 0xffff0000, v131
	v_max_f32_e32 v131, v176, v176
	v_max_f32_e32 v130, 0xda24260, v130
	v_max_f32_e32 v131, 0xda24260, v131
	v_rcp_f32_e32 v130, v130
	v_rcp_f32_e32 v131, v131
	v_max_f32_e32 v132, 0xda24260, v132
	v_rcp_f32_e32 v173, v132
	v_lshlrev_b32_e32 v132, 16, v133
	v_and_b32_e32 v133, 0xffff0000, v133
	v_pk_mul_f32 v[130:131], v[130:131], v[132:133]
	v_pk_mul_f32 v[46:47], v[46:47], v[158:159]
	v_pk_mul_f32 v[44:45], v[44:45], v[130:131]
	v_add_u32_e32 v130, 0xb0, v168
	v_mad_i64_i32 v[156:157], s[58:59], v130, s78, v[156:157]
	v_add_co_u32_e32 v158, vcc, s61, v156
	v_pk_mul_f32 v[42:43], v[42:43], v[170:171]
	s_nop 0
	v_addc_co_u32_e32 v159, vcc, 0, v157, vcc
	v_add_co_u32_e32 v156, vcc, s77, v156
	global_load_dwordx4 v[130:133], v[158:159], off
	s_nop 0
	v_addc_co_u32_e32 v157, vcc, 0, v157, vcc
	global_load_dwordx4 v[168:171], v[156:157], off
	v_pk_mul_f32 v[172:173], v[172:173], v[174:175]
	s_waitcnt vmcnt(0)
	v_lshlrev_b32_e32 v174, 16, v169
	v_and_b32_e32 v175, 0xffff0000, v169
	v_lshlrev_b32_e32 v169, 16, v170
	v_max_f32_e32 v169, v169, v169
	v_pk_mul_f32 v[48:49], v[48:49], v[172:173]
	v_lshlrev_b32_e32 v172, 16, v168
	v_and_b32_e32 v173, 0xffff0000, v168
	v_max_f32_e32 v169, 0xda24260, v169
	v_and_b32_e32 v176, 0xffff0000, v170
	v_max_f32_e32 v168, v172, v172
	v_rcp_f32_e32 v170, v169
	v_max_f32_e32 v169, v173, v173
	v_max_f32_e32 v168, 0xda24260, v168
	v_max_f32_e32 v169, 0xda24260, v169
	v_lshlrev_b32_e32 v172, 16, v130
	v_and_b32_e32 v173, 0xffff0000, v130
	v_max_f32_e32 v130, v176, v176
	v_rcp_f32_e32 v168, v168
	v_rcp_f32_e32 v169, v169
	v_max_f32_e32 v130, 0xda24260, v130
	v_lshlrev_b32_e32 v177, 16, v171
	v_and_b32_e32 v178, 0xffff0000, v171
	v_rcp_f32_e32 v171, v130
	v_max_f32_e32 v130, v174, v174
	v_pk_mul_f32 v[168:169], v[168:169], v[172:173]
	v_lshlrev_b32_e32 v172, 16, v132
	v_and_b32_e32 v173, 0xffff0000, v132
	v_max_f32_e32 v130, 0xda24260, v130
	v_pk_mul_f32 v[170:171], v[170:171], v[172:173]
	v_rcp_f32_e32 v172, v130
	v_max_f32_e32 v130, v177, v177
	v_max_f32_e32 v132, v175, v175
	v_lshlrev_b32_e32 v174, 16, v131
	v_and_b32_e32 v175, 0xffff0000, v131
	v_max_f32_e32 v131, v178, v178
	v_max_f32_e32 v130, 0xda24260, v130
	v_max_f32_e32 v131, 0xda24260, v131
	v_rcp_f32_e32 v130, v130
	v_rcp_f32_e32 v131, v131
	v_max_f32_e32 v132, 0xda24260, v132
	v_rcp_f32_e32 v173, v132
	v_lshlrev_b32_e32 v132, 16, v133
	v_and_b32_e32 v133, 0xffff0000, v133
	v_pk_mul_f32 v[130:131], v[130:131], v[132:133]
	v_pk_mul_f32 v[18:19], v[18:19], v[170:171]
	v_pk_mul_f32 v[20:21], v[20:21], v[130:131]
	global_load_dwordx4 v[130:133], v[158:159], off offset:256
	s_nop 0
	global_load_dwordx4 v[156:159], v[156:157], off offset:256
	v_pk_mul_f32 v[172:173], v[172:173], v[174:175]
	v_pk_mul_f32 v[22:23], v[22:23], v[168:169]
	v_pk_mul_f32 v[24:25], v[24:25], v[172:173]
	s_waitcnt vmcnt(0)
; #define PG8_STAGE(bufoff, gbase, voff) do { _Pragma("unroll") for (int _i = 0; _i < 2; ++_i) \
;         __builtin_amdgcn_global_load_lds((const unsigned*)((const char*)(gbase) + (voff)[_i]), (PG8_LAS unsigned*)(lds + (bufoff) + ldsw + _i * 8192), 16, 0, 0); } while (0)
; #define PG8_LDA(dst, b, h) do { _Pragma("unroll") for (int m = 0; m < 4; ++m) _Pragma("unroll") for (int k = 0; k < 2; ++k) dst[m][k] = *(const PG8_LAS bf16x8*)(lds + PG8_SA(b, h) + aoff + m * 2048 + k * 1024); } while (0)
; #define PG8_LDB(dst, b, h) do { _Pragma("unroll") for (int n = 0; n < 2; ++n) _Pragma("unroll") for (int k = 0; k < 2; ++k) dst[n][k] = *(const PG8_LAS bf16x8*)(lds + PG8_SB(b, h) + boff + n * 2048 + k * 1024); } while (0)
; #define PG8_WAIT_V(n) asm volatile("s_waitcnt vmcnt(" #n ")" ::: "memory")
;     __device__ __forceinline__ void mid(f32x4 (&acc)[2][2][4][2], const Unit& u, int wr, int wc, int fr, int fq) const {
;     ...
;                     for (int j = 0; j < 4; ++j) { r0[j] = a0[j] * __builtin_amdgcn_rcpf(fmaxf(b0[j], 1e-30f)); r1[j] = a1[j] * __builtin_amdgcn_rcpf(fmaxf(b1[j], 1e-30f)); }
;                     acc[ai][bj][m][0] *= r0; acc[ai][bj][m][1] *= r1; }
;                 asm volatile("" ::: "memory"); }
; template <class Epi, class Sched, bool ALIGN_EPI = false, bool SP2 = false>
; __device__ __forceinline__ void gemm_phase(PG8_LAS unsigned char* lds, const Gemm g, const Sched& S, const Epi& E) {
;     ...
;         for (; t < tend; t += 2) {
;             const bool last = (t == nt - 2);
;             const char* a1 = cA + (size_t)(t + 1) * kstep;
;             const char* a2 = last ? nA : cA + (size_t)(t + 2) * kstep; const char* b2 = last ? nB : cB + (size_t)(t + 2) * kstep;
;             const char* a3 = a2 + kstep; const char* b3 = b2 + kstep;
;             if (last && has_next) S.a_ready(nxt);
;             if constexpr (SP2) {
;             PG8_LDB(B0, 0, 0); PG8_LDB(B1, 0, 1); PG8_SCHED; PG8_LDA(At, 0, 0); PG8_STAGE(PG8_SA(1, 1), a1 + hstep, voffA);
;             PG8_WAIT_V(8); PG8_WAIT_L(0); PG8_BAR; PG8_MMA(0, 0, At, B0); PG8_MMA(0, 1, At, B1); PG8_BAR; PG8_SCHED;
;             PG8_LDA(At, 0, 1); PG8_STAGE(PG8_SB(0, 0), b2, voffB); PG8_STAGE(PG8_SB(0, 1), b2 + hstep, voffB); PG8_STAGE(PG8_SA(0, 0), a2, voffA);
;             PG8_WAIT_V(8); PG8_WAIT_L(0); PG8_BAR; PG8_MMA(1, 0, At, B0); PG8_MMA(1, 1, At, B1); PG8_BAR; PG8_SCHED;
	v_lshlrev_b32_e32 v170, 16, v157
	v_and_b32_e32 v171, 0xffff0000, v157
	v_lshlrev_b32_e32 v157, 16, v158
	v_max_f32_e32 v157, v157, v157
	v_lshlrev_b32_e32 v168, 16, v156
	v_and_b32_e32 v169, 0xffff0000, v156
	v_max_f32_e32 v157, 0xda24260, v157
	v_and_b32_e32 v172, 0xffff0000, v158
	v_max_f32_e32 v156, v168, v168
	v_rcp_f32_e32 v158, v157
	v_max_f32_e32 v157, v169, v169
	v_max_f32_e32 v156, 0xda24260, v156
	v_max_f32_e32 v157, 0xda24260, v157
	v_lshlrev_b32_e32 v168, 16, v130
	v_and_b32_e32 v169, 0xffff0000, v130
	v_max_f32_e32 v130, v172, v172
	v_rcp_f32_e32 v156, v156
	v_rcp_f32_e32 v157, v157
	v_max_f32_e32 v130, 0xda24260, v130
	v_lshlrev_b32_e32 v173, 16, v159
	v_and_b32_e32 v174, 0xffff0000, v159
	v_rcp_f32_e32 v159, v130
	v_max_f32_e32 v130, v170, v170
	v_pk_mul_f32 v[156:157], v[156:157], v[168:169]
	v_lshlrev_b32_e32 v168, 16, v132
	v_and_b32_e32 v169, 0xffff0000, v132
	v_max_f32_e32 v130, 0xda24260, v130
	v_pk_mul_f32 v[158:159], v[158:159], v[168:169]
	v_rcp_f32_e32 v168, v130
	v_max_f32_e32 v130, v173, v173
	v_max_f32_e32 v132, v171, v171
	v_lshlrev_b32_e32 v170, 16, v131
	v_and_b32_e32 v171, 0xffff0000, v131
	v_max_f32_e32 v131, v174, v174
	v_max_f32_e32 v130, 0xda24260, v130
	v_max_f32_e32 v132, 0xda24260, v132
	v_max_f32_e32 v131, 0xda24260, v131
	v_rcp_f32_e32 v130, v130
	v_rcp_f32_e32 v169, v132
	v_rcp_f32_e32 v131, v131
	v_lshlrev_b32_e32 v132, 16, v133
	v_and_b32_e32 v133, 0xffff0000, v133
	v_pk_mul_f32 v[168:169], v[168:169], v[170:171]
	v_pk_mul_f32 v[130:131], v[130:131], v[132:133]
	v_pk_mul_f32 v[8:9], v[8:9], v[168:169]
	v_pk_mul_f32 v[6:7], v[6:7], v[156:157]
	v_pk_mul_f32 v[4:5], v[4:5], v[130:131]
	v_pk_mul_f32 v[2:3], v[2:3], v[158:159]
.LBB0_684:
	ds_read_b128 v[130:133], v163
	ds_read_b128 v[156:159], v163 offset:1024
	ds_read_b128 v[168:171], v163 offset:2048
	ds_read_b128 v[172:175], v163 offset:3072
	ds_read_b128 v[180:183], v164
	ds_read_b128 v[184:187], v164 offset:1024
	ds_read_b128 v[188:191], v164 offset:2048
	ds_read_b128 v[198:201], v164 offset:3072
	s_add_u32 s48, s50, 0x4000
	s_addc_u32 s49, s51, 0
	s_cmp_eq_u32 s56, 60
	s_cselect_b32 s72, s93, s48
	s_cselect_b32 s73, s41, s49
	s_cselect_b32 s70, s97, s26
	s_cselect_b32 s71, s27, s33
	s_add_u32 s48, s72, 0x8000
	s_addc_u32 s49, s73, 0
	s_mov_b32 m0, s83
	ds_read_b128 v[202:205], v165
	ds_read_b128 v[206:209], v165 offset:1024
	ds_read_b128 v[210:213], v165 offset:2048
	ds_read_b128 v[214:217], v165 offset:3072
	ds_read_b128 v[218:221], v165 offset:4096
	ds_read_b128 v[222:225], v165 offset:5120
	ds_read_b128 v[226:229], v165 offset:6144
	ds_read_b128 v[230:233], v165 offset:7168
	global_load_lds_dwordx4 v144, s[50:51]
	s_mov_b32 m0, s84
	s_nop 0
	global_load_lds_dwordx4 v146, s[50:51]
	s_waitcnt vmcnt(8)
	s_waitcnt lgkmcnt(0)
	s_barrier
	s_setprio 1
	s_waitcnt lgkmcnt(0)
	v_mfma_f32_16x16x32_bf16 v[14:17], v[130:133], v[202:205], v[14:17]
	v_mfma_f32_16x16x32_bf16 v[14:17], v[156:159], v[206:209], v[14:17]
	v_mfma_f32_16x16x32_bf16 v[38:41], v[130:133], v[210:213], v[38:41]
	v_mfma_f32_16x16x32_bf16 v[38:41], v[156:159], v[214:217], v[38:41]
	v_mfma_f32_16x16x32_bf16 v[70:73], v[130:133], v[218:221], v[70:73]
	v_mfma_f32_16x16x32_bf16 v[70:73], v[156:159], v[222:225], v[70:73]
	v_mfma_f32_16x16x32_bf16 v[94:97], v[130:133], v[226:229], v[94:97]
	v_mfma_f32_16x16x32_bf16 v[94:97], v[156:159], v[230:233], v[94:97]
	v_mfma_f32_16x16x32_bf16 v[90:93], v[168:171], v[226:229], v[90:93]
	v_mfma_f32_16x16x32_bf16 v[90:93], v[172:175], v[230:233], v[90:93]
	v_mfma_f32_16x16x32_bf16 v[66:69], v[168:171], v[218:221], v[66:69]
	v_mfma_f32_16x16x32_bf16 v[66:69], v[172:175], v[222:225], v[66:69]
	v_mfma_f32_16x16x32_bf16 v[34:37], v[168:171], v[210:213], v[34:37]
	v_mfma_f32_16x16x32_bf16 v[34:37], v[172:175], v[214:217], v[34:37]
	v_mfma_f32_16x16x32_bf16 v[10:13], v[168:171], v[202:205], v[10:13]
	v_mfma_f32_16x16x32_bf16 v[10:13], v[172:175], v[206:209], v[10:13]
	s_setprio 0
	s_setprio 1
	v_mfma_f32_16x16x32_bf16 v[30:33], v[180:183], v[202:205], v[30:33]
	v_mfma_f32_16x16x32_bf16 v[30:33], v[184:187], v[206:209], v[30:33]
	v_mfma_f32_16x16x32_bf16 v[54:57], v[180:183], v[210:213], v[54:57]
	v_mfma_f32_16x16x32_bf16 v[54:57], v[184:187], v[214:217], v[54:57]
	v_mfma_f32_16x16x32_bf16 v[86:89], v[180:183], v[218:221], v[86:89]
	v_mfma_f32_16x16x32_bf16 v[86:89], v[184:187], v[222:225], v[86:89]
	v_mfma_f32_16x16x32_bf16 v[110:113], v[180:183], v[226:229], v[110:113]
	v_mfma_f32_16x16x32_bf16 v[110:113], v[184:187], v[230:233], v[110:113]
	v_mfma_f32_16x16x32_bf16 v[106:109], v[188:191], v[226:229], v[106:109]
	v_mfma_f32_16x16x32_bf16 v[106:109], v[198:201], v[230:233], v[106:109]
	v_mfma_f32_16x16x32_bf16 v[82:85], v[188:191], v[218:221], v[82:85]
	v_mfma_f32_16x16x32_bf16 v[82:85], v[198:201], v[222:225], v[82:85]
	v_mfma_f32_16x16x32_bf16 v[50:53], v[188:191], v[210:213], v[50:53]
	v_mfma_f32_16x16x32_bf16 v[50:53], v[198:201], v[214:217], v[50:53]
	v_mfma_f32_16x16x32_bf16 v[26:29], v[188:191], v[202:205], v[26:29]
	v_mfma_f32_16x16x32_bf16 v[26:29], v[198:201], v[206:209], v[26:29]
	s_setprio 0
	s_barrier
	s_mov_b32 m0, s85
	s_add_u32 s58, s70, 0x4000
	ds_read_b128 v[202:205], v165 offset:16384
	ds_read_b128 v[206:209], v165 offset:17408
	ds_read_b128 v[210:213], v165 offset:18432
	ds_read_b128 v[214:217], v165 offset:19456
	ds_read_b128 v[218:221], v165 offset:20480
	ds_read_b128 v[222:225], v165 offset:21504
	ds_read_b128 v[226:229], v165 offset:22528
	ds_read_b128 v[230:233], v165 offset:23552
	global_load_lds_dwordx4 v136, s[70:71]
	s_mov_b32 m0, s86
	s_addc_u32 s59, s71, 0
	global_load_lds_dwordx4 v140, s[70:71]
	s_mov_b32 m0, s87
	s_nop 0
	global_load_lds_dwordx4 v136, s[58:59]
	s_mov_b32 m0, s88
	s_nop 0
	global_load_lds_dwordx4 v140, s[58:59]
	s_mov_b32 m0, s29
	s_nop 0
	global_load_lds_dwordx4 v134, s[72:73]
	s_mov_b32 m0, s30
	s_nop 0
	global_load_lds_dwordx4 v138, s[72:73]
	s_waitcnt vmcnt(8)
	s_waitcnt lgkmcnt(0)
	s_barrier
; #define PG8_STAGE(bufoff, gbase, voff) do { _Pragma("unroll") for (int _i = 0; _i < 2; ++_i) \
;         __builtin_amdgcn_global_load_lds((const unsigned*)((const char*)(gbase) + (voff)[_i]), (PG8_LAS unsigned*)(lds + (bufoff) + ldsw + _i * 8192), 16, 0, 0); } while (0)
; #define PG8_LDA(dst, b, h) do { _Pragma("unroll") for (int m = 0; m < 4; ++m) _Pragma("unroll") for (int k = 0; k < 2; ++k) dst[m][k] = *(const PG8_LAS bf16x8*)(lds + PG8_SA(b, h) + aoff + m * 2048 + k * 1024); } while (0)
; #define PG8_LDB(dst, b, h) do { _Pragma("unroll") for (int n = 0; n < 2; ++n) _Pragma("unroll") for (int k = 0; k < 2; ++k) dst[n][k] = *(const PG8_LAS bf16x8*)(lds + PG8_SB(b, h) + boff + n * 2048 + k * 1024); } while (0)
; #define PG8_MMA(ai, bj, At, Bt) do { __builtin_amdgcn_s_setprio(1); _Pragma("unroll") for (int m = 0; m < 4; ++m) _Pragma("unroll") for (int n = 0; n < 2; ++n) _Pragma("unroll") for (int k = 0; k < 2; ++k) \
;         acc[ai][bj][m][n] = __builtin_amdgcn_mfma_f32_16x16x32_bf16(Bt[n][k], At[m][k], acc[ai][bj][m][n], 0, 0, 0); __builtin_amdgcn_s_setprio(0); } while (0)
; #define PG8_WAIT_V(n) asm volatile("s_waitcnt vmcnt(" #n ")" ::: "memory")
; #define PG8_WAIT_L(n) asm volatile("s_waitcnt lgkmcnt(" #n ")" ::: "memory")
; #define PG8_BAR __builtin_amdgcn_s_barrier()
; #define PG8_SCHED __builtin_amdgcn_sched_barrier(0)
; template <class Epi, class Sched, bool ALIGN_EPI = false, bool SP2 = false>
; __device__ __forceinline__ void gemm_phase(PG8_LAS unsigned char* lds, const Gemm g, const Sched& S, const Epi& E) {
;     ...
;             PG8_WAIT_V(8); PG8_WAIT_L(0); PG8_BAR; PG8_MMA(1, 0, At, B0); PG8_MMA(1, 1, At, B1); PG8_BAR; PG8_SCHED;
;             PG8_LDB(B0, 1, 0); PG8_LDB(B1, 1, 1); PG8_SCHED; PG8_LDA(At, 1, 0); PG8_STAGE(PG8_SA(0, 1), a2 + hstep, voffA);
;             PG8_WAIT_V(8); PG8_WAIT_L(0); PG8_BAR; PG8_MMA(0, 0, At, B0); PG8_MMA(0, 1, At, B1); PG8_BAR; PG8_SCHED;
;             PG8_LDA(At, 1, 1); PG8_STAGE(PG8_SB(1, 0), b3, voffB); PG8_STAGE(PG8_SB(1, 1), b3 + hstep, voffB); PG8_STAGE(PG8_SA(1, 0), a3, voffA);
	s_setprio 1
	s_waitcnt lgkmcnt(0)
	v_mfma_f32_16x16x32_bf16 v[126:129], v[130:133], v[202:205], v[126:129]
	v_mfma_f32_16x16x32_bf16 v[126:129], v[156:159], v[206:209], v[126:129]
	v_mfma_f32_16x16x32_bf16 v[102:105], v[130:133], v[210:213], v[102:105]
	v_mfma_f32_16x16x32_bf16 v[102:105], v[156:159], v[214:217], v[102:105]
	v_mfma_f32_16x16x32_bf16 v[62:65], v[130:133], v[218:221], v[62:65]
	v_mfma_f32_16x16x32_bf16 v[62:65], v[156:159], v[222:225], v[62:65]
	v_mfma_f32_16x16x32_bf16 v[22:25], v[130:133], v[226:229], v[22:25]
	v_mfma_f32_16x16x32_bf16 v[22:25], v[156:159], v[230:233], v[22:25]
	v_mfma_f32_16x16x32_bf16 v[18:21], v[168:171], v[226:229], v[18:21]
	v_mfma_f32_16x16x32_bf16 v[18:21], v[172:175], v[230:233], v[18:21]
	v_mfma_f32_16x16x32_bf16 v[58:61], v[168:171], v[218:221], v[58:61]
	v_mfma_f32_16x16x32_bf16 v[58:61], v[172:175], v[222:225], v[58:61]
	v_mfma_f32_16x16x32_bf16 v[98:101], v[168:171], v[210:213], v[98:101]
	v_mfma_f32_16x16x32_bf16 v[98:101], v[172:175], v[214:217], v[98:101]
	v_mfma_f32_16x16x32_bf16 v[122:125], v[168:171], v[202:205], v[122:125]
	v_mfma_f32_16x16x32_bf16 v[122:125], v[172:175], v[206:209], v[122:125]
	s_setprio 0
	s_setprio 1
	v_mfma_f32_16x16x32_bf16 v[118:121], v[180:183], v[202:205], v[118:121]
	v_mfma_f32_16x16x32_bf16 v[118:121], v[184:187], v[206:209], v[118:121]
	v_mfma_f32_16x16x32_bf16 v[78:81], v[180:183], v[210:213], v[78:81]
	v_mfma_f32_16x16x32_bf16 v[78:81], v[184:187], v[214:217], v[78:81]
	v_mfma_f32_16x16x32_bf16 v[46:49], v[180:183], v[218:221], v[46:49]
	v_mfma_f32_16x16x32_bf16 v[46:49], v[184:187], v[222:225], v[46:49]
	v_mfma_f32_16x16x32_bf16 v[6:9], v[180:183], v[226:229], v[6:9]
	v_mfma_f32_16x16x32_bf16 v[6:9], v[184:187], v[230:233], v[6:9]
	v_mfma_f32_16x16x32_bf16 v[2:5], v[188:191], v[226:229], v[2:5]
	v_mfma_f32_16x16x32_bf16 v[2:5], v[198:201], v[230:233], v[2:5]
	v_mfma_f32_16x16x32_bf16 v[42:45], v[188:191], v[218:221], v[42:45]
	v_mfma_f32_16x16x32_bf16 v[42:45], v[198:201], v[222:225], v[42:45]
	v_mfma_f32_16x16x32_bf16 v[74:77], v[188:191], v[210:213], v[74:77]
	v_mfma_f32_16x16x32_bf16 v[74:77], v[198:201], v[214:217], v[74:77]
	v_mfma_f32_16x16x32_bf16 v[114:117], v[188:191], v[202:205], v[114:117]
	v_mfma_f32_16x16x32_bf16 v[114:117], v[198:201], v[206:209], v[114:117]
	s_setprio 0
	s_barrier
	ds_read_b128 v[130:133], v142
	ds_read_b128 v[156:159], v142 offset:1024
	ds_read_b128 v[168:171], v142 offset:2048
	ds_read_b128 v[172:175], v142 offset:3072
	ds_read_b128 v[180:183], v167
	ds_read_b128 v[184:187], v167 offset:1024
	ds_read_b128 v[188:191], v167 offset:2048
	ds_read_b128 v[198:201], v167 offset:3072
	s_add_u32 s58, s72, 0x4000
	s_addc_u32 s59, s73, 0
	s_mov_b32 m0, s31
	ds_read_b128 v[202:205], v165 offset:32768
	ds_read_b128 v[206:209], v165 offset:33792
	ds_read_b128 v[210:213], v165 offset:34816
	ds_read_b128 v[214:217], v165 offset:35840
	ds_read_b128 v[218:221], v165 offset:36864
	ds_read_b128 v[222:225], v165 offset:37888
	ds_read_b128 v[226:229], v165 offset:38912
	ds_read_b128 v[230:233], v165 offset:39936
	global_load_lds_dwordx4 v134, s[58:59]
	s_mov_b32 m0, s35
	s_nop 0
	global_load_lds_dwordx4 v138, s[58:59]
	s_waitcnt vmcnt(8)
	s_waitcnt lgkmcnt(0)
	s_barrier
	s_setprio 1
	s_waitcnt lgkmcnt(0)
	v_mfma_f32_16x16x32_bf16 v[14:17], v[130:133], v[202:205], v[14:17]
	v_mfma_f32_16x16x32_bf16 v[14:17], v[156:159], v[206:209], v[14:17]
	v_mfma_f32_16x16x32_bf16 v[38:41], v[130:133], v[210:213], v[38:41]
	v_mfma_f32_16x16x32_bf16 v[38:41], v[156:159], v[214:217], v[38:41]
	v_mfma_f32_16x16x32_bf16 v[70:73], v[130:133], v[218:221], v[70:73]
	v_mfma_f32_16x16x32_bf16 v[70:73], v[156:159], v[222:225], v[70:73]
	v_mfma_f32_16x16x32_bf16 v[94:97], v[130:133], v[226:229], v[94:97]
	v_mfma_f32_16x16x32_bf16 v[94:97], v[156:159], v[230:233], v[94:97]
	v_mfma_f32_16x16x32_bf16 v[90:93], v[168:171], v[226:229], v[90:93]
	v_mfma_f32_16x16x32_bf16 v[90:93], v[172:175], v[230:233], v[90:93]
	v_mfma_f32_16x16x32_bf16 v[66:69], v[168:171], v[218:221], v[66:69]
	v_mfma_f32_16x16x32_bf16 v[66:69], v[172:175], v[222:225], v[66:69]
	v_mfma_f32_16x16x32_bf16 v[34:37], v[168:171], v[210:213], v[34:37]
	v_mfma_f32_16x16x32_bf16 v[34:37], v[172:175], v[214:217], v[34:37]
	v_mfma_f32_16x16x32_bf16 v[10:13], v[168:171], v[202:205], v[10:13]
	v_mfma_f32_16x16x32_bf16 v[10:13], v[172:175], v[206:209], v[10:13]
	s_setprio 0
	s_setprio 1
	v_mfma_f32_16x16x32_bf16 v[30:33], v[180:183], v[202:205], v[30:33]
	v_mfma_f32_16x16x32_bf16 v[30:33], v[184:187], v[206:209], v[30:33]
	v_mfma_f32_16x16x32_bf16 v[54:57], v[180:183], v[210:213], v[54:57]
	v_mfma_f32_16x16x32_bf16 v[54:57], v[184:187], v[214:217], v[54:57]
	v_mfma_f32_16x16x32_bf16 v[86:89], v[180:183], v[218:221], v[86:89]
	v_mfma_f32_16x16x32_bf16 v[86:89], v[184:187], v[222:225], v[86:89]
	v_mfma_f32_16x16x32_bf16 v[110:113], v[180:183], v[226:229], v[110:113]
	v_mfma_f32_16x16x32_bf16 v[110:113], v[184:187], v[230:233], v[110:113]
	v_mfma_f32_16x16x32_bf16 v[106:109], v[188:191], v[226:229], v[106:109]
	v_mfma_f32_16x16x32_bf16 v[106:109], v[198:201], v[230:233], v[106:109]
	v_mfma_f32_16x16x32_bf16 v[82:85], v[188:191], v[218:221], v[82:85]
	v_mfma_f32_16x16x32_bf16 v[82:85], v[198:201], v[222:225], v[82:85]
	v_mfma_f32_16x16x32_bf16 v[50:53], v[188:191], v[210:213], v[50:53]
	v_mfma_f32_16x16x32_bf16 v[50:53], v[198:201], v[214:217], v[50:53]
	v_mfma_f32_16x16x32_bf16 v[26:29], v[188:191], v[202:205], v[26:29]
	v_mfma_f32_16x16x32_bf16 v[26:29], v[198:201], v[206:209], v[26:29]
	s_setprio 0
	s_barrier
; #define PG8_STAGE(bufoff, gbase, voff) do { _Pragma("unroll") for (int _i = 0; _i < 2; ++_i) \
;         __builtin_amdgcn_global_load_lds((const unsigned*)((const char*)(gbase) + (voff)[_i]), (PG8_LAS unsigned*)(lds + (bufoff) + ldsw + _i * 8192), 16, 0, 0); } while (0)
; #define PG8_LDA(dst, b, h) do { _Pragma("unroll") for (int m = 0; m < 4; ++m) _Pragma("unroll") for (int k = 0; k < 2; ++k) dst[m][k] = *(const PG8_LAS bf16x8*)(lds + PG8_SA(b, h) + aoff + m * 2048 + k * 1024); } while (0)
; #define PG8_LDB(dst, b, h) do { _Pragma("unroll") for (int n = 0; n < 2; ++n) _Pragma("unroll") for (int k = 0; k < 2; ++k) dst[n][k] = *(const PG8_LAS bf16x8*)(lds + PG8_SB(b, h) + boff + n * 2048 + k * 1024); } while (0)
; #define PG8_WAIT_V(n) asm volatile("s_waitcnt vmcnt(" #n ")" ::: "memory")
; template <class Epi, class Sched, bool ALIGN_EPI = false, bool SP2 = false>
; __device__ __forceinline__ void gemm_phase(PG8_LAS unsigned char* lds, const Gemm g, const Sched& S, const Epi& E) {
;     ...
;             const char* a1 = cA + (size_t)(t + 1) * kstep;
;             const char* a2 = last ? nA : cA + (size_t)(t + 2) * kstep; const char* b2 = last ? nB : cB + (size_t)(t + 2) * kstep;
;             const char* a3 = a2 + kstep; const char* b3 = b2 + kstep;
;             if (last && has_next) S.a_ready(nxt);
;             if constexpr (SP2) {
;             PG8_LDB(B0, 0, 0); PG8_LDB(B1, 0, 1); PG8_SCHED; PG8_LDA(At, 0, 0); PG8_STAGE(PG8_SA(1, 1), a1 + hstep, voffA);
;             PG8_WAIT_V(8); PG8_WAIT_L(0); PG8_BAR; PG8_MMA(0, 0, At, B0); PG8_MMA(0, 1, At, B1); PG8_BAR; PG8_SCHED;
;             PG8_LDA(At, 0, 1); PG8_STAGE(PG8_SB(0, 0), b2, voffB); PG8_STAGE(PG8_SB(0, 1), b2 + hstep, voffB); PG8_STAGE(PG8_SA(0, 0), a2, voffA);
;             PG8_WAIT_V(8); PG8_WAIT_L(0); PG8_BAR; PG8_MMA(1, 0, At, B0); PG8_MMA(1, 1, At, B1); PG8_BAR; PG8_SCHED;
;             PG8_LDB(B0, 1, 0); PG8_LDB(B1, 1, 1); PG8_SCHED; PG8_LDA(At, 1, 0); PG8_STAGE(PG8_SA(0, 1), a2 + hstep, voffA);
;             PG8_WAIT_V(8); PG8_WAIT_L(0); PG8_BAR; PG8_MMA(0, 0, At, B0); PG8_MMA(0, 1, At, B1); PG8_BAR; PG8_SCHED;
;             PG8_LDA(At, 1, 1); PG8_STAGE(PG8_SB(1, 0), b3, voffB); PG8_STAGE(PG8_SB(1, 1), b3 + hstep, voffB); PG8_STAGE(PG8_SA(1, 0), a3, voffA);
;             PG8_WAIT_V(8); PG8_WAIT_L(0); PG8_BAR; PG8_MMA(1, 0, At, B0); PG8_MMA(1, 1, At, B1); PG8_BAR; PG8_SCHED;
	s_add_u32 s58, s70, 0x8000
	s_addc_u32 s59, s71, 0
	s_mov_b32 m0, s89
	ds_read_b128 v[202:205], v165 offset:49152
	ds_read_b128 v[206:209], v165 offset:50176
	ds_read_b128 v[210:213], v165 offset:51200
	ds_read_b128 v[214:217], v165 offset:52224
	ds_read_b128 v[218:221], v165 offset:53248
	ds_read_b128 v[222:225], v165 offset:54272
	ds_read_b128 v[226:229], v165 offset:55296
	ds_read_b128 v[230:233], v165 offset:56320
	global_load_lds_dwordx4 v136, s[58:59]
	v_lshl_add_u64 v[176:177], s[58:59], 0, v[140:141]
	s_add_u32 s58, s70, 0xc000
	s_mov_b32 m0, s90
	s_addc_u32 s59, s71, 0
	global_load_lds_dwordx4 v[176:177], off
	s_mov_b32 m0, s91
	s_nop 0
	global_load_lds_dwordx4 v136, s[58:59]
	s_mov_b32 m0, s92
	s_nop 0
	global_load_lds_dwordx4 v140, s[58:59]
	s_mov_b32 m0, s75
	s_nop 0
	global_load_lds_dwordx4 v134, s[48:49]
	s_mov_b32 m0, s76
	s_nop 0
	global_load_lds_dwordx4 v138, s[48:49]
	s_waitcnt vmcnt(8)
	s_waitcnt lgkmcnt(0)
	s_barrier
	s_setprio 1
	s_waitcnt lgkmcnt(0)
	v_mfma_f32_16x16x32_bf16 v[126:129], v[130:133], v[202:205], v[126:129]
	v_mfma_f32_16x16x32_bf16 v[126:129], v[156:159], v[206:209], v[126:129]
	v_mfma_f32_16x16x32_bf16 v[102:105], v[130:133], v[210:213], v[102:105]
	v_mfma_f32_16x16x32_bf16 v[102:105], v[156:159], v[214:217], v[102:105]
	v_mfma_f32_16x16x32_bf16 v[62:65], v[130:133], v[218:221], v[62:65]
	v_mfma_f32_16x16x32_bf16 v[62:65], v[156:159], v[222:225], v[62:65]
	v_mfma_f32_16x16x32_bf16 v[22:25], v[130:133], v[226:229], v[22:25]
	v_mfma_f32_16x16x32_bf16 v[22:25], v[156:159], v[230:233], v[22:25]
	v_mfma_f32_16x16x32_bf16 v[18:21], v[168:171], v[226:229], v[18:21]
	v_mfma_f32_16x16x32_bf16 v[18:21], v[172:175], v[230:233], v[18:21]
	v_mfma_f32_16x16x32_bf16 v[58:61], v[168:171], v[218:221], v[58:61]
	v_mfma_f32_16x16x32_bf16 v[58:61], v[172:175], v[222:225], v[58:61]
	v_mfma_f32_16x16x32_bf16 v[98:101], v[168:171], v[210:213], v[98:101]
	v_mfma_f32_16x16x32_bf16 v[98:101], v[172:175], v[214:217], v[98:101]
	v_mfma_f32_16x16x32_bf16 v[122:125], v[168:171], v[202:205], v[122:125]
	v_mfma_f32_16x16x32_bf16 v[122:125], v[172:175], v[206:209], v[122:125]
	s_setprio 0
	s_setprio 1
	v_mfma_f32_16x16x32_bf16 v[118:121], v[180:183], v[202:205], v[118:121]
	v_mfma_f32_16x16x32_bf16 v[118:121], v[184:187], v[206:209], v[118:121]
	v_mfma_f32_16x16x32_bf16 v[78:81], v[180:183], v[210:213], v[78:81]
	v_mfma_f32_16x16x32_bf16 v[78:81], v[184:187], v[214:217], v[78:81]
	v_mfma_f32_16x16x32_bf16 v[46:49], v[180:183], v[218:221], v[46:49]
	v_mfma_f32_16x16x32_bf16 v[46:49], v[184:187], v[222:225], v[46:49]
	v_mfma_f32_16x16x32_bf16 v[6:9], v[180:183], v[226:229], v[6:9]
	v_mfma_f32_16x16x32_bf16 v[6:9], v[184:187], v[230:233], v[6:9]
	v_mfma_f32_16x16x32_bf16 v[2:5], v[188:191], v[226:229], v[2:5]
	v_mfma_f32_16x16x32_bf16 v[2:5], v[198:201], v[230:233], v[2:5]
	v_mfma_f32_16x16x32_bf16 v[42:45], v[188:191], v[218:221], v[42:45]
	v_mfma_f32_16x16x32_bf16 v[42:45], v[198:201], v[222:225], v[42:45]
	v_mfma_f32_16x16x32_bf16 v[74:77], v[188:191], v[210:213], v[74:77]
	v_mfma_f32_16x16x32_bf16 v[74:77], v[198:201], v[214:217], v[74:77]
	v_mfma_f32_16x16x32_bf16 v[114:117], v[188:191], v[202:205], v[114:117]
	v_mfma_f32_16x16x32_bf16 v[114:117], v[198:201], v[206:209], v[114:117]
	s_setprio 0
	s_barrier
	s_add_i32 s56, s56, 2
	s_add_u32 s50, s50, 0x10000
	s_addc_u32 s51, s51, 0
	s_add_u32 s26, s26, 0x10000
	s_addc_u32 s33, s33, 0
	s_cmp_lt_u32 s56, 62
	s_cbranch_scc1 .LBB0_684
	s_andn2_b64 vcc, exec, s[12:13]
	s_cbranch_vccnz .LBB0_687
	s_barrier

; #define PG8_STAGE(bufoff, gbase, voff) do { _Pragma("unroll") for (int _i = 0; _i < 2; ++_i) \
;         __builtin_amdgcn_global_load_lds((const unsigned*)((const char*)(gbase) + (voff)[_i]), (PG8_LAS unsigned*)(lds + (bufoff) + ldsw + _i * 8192), 16, 0, 0); } while (0)
; #define PG8_LDA(dst, b, h) do { _Pragma("unroll") for (int m = 0; m < 4; ++m) _Pragma("unroll") for (int k = 0; k < 2; ++k) dst[m][k] = *(const PG8_LAS bf16x8*)(lds + PG8_SA(b, h) + aoff + m * 2048 + k * 1024); } while (0)
; #define PG8_LDB(dst, b, h) do { _Pragma("unroll") for (int n = 0; n < 2; ++n) _Pragma("unroll") for (int k = 0; k < 2; ++k) dst[n][k] = *(const PG8_LAS bf16x8*)(lds + PG8_SB(b, h) + boff + n * 2048 + k * 1024); } while (0)
; #define PG8_WAIT_V(n) asm volatile("s_waitcnt vmcnt(" #n ")" ::: "memory")
; #define PG8_WAIT_L(n) asm volatile("s_waitcnt lgkmcnt(" #n ")" ::: "memory")
; #define PG8_BAR __builtin_amdgcn_s_barrier()
; #define PG8_SCHED __builtin_amdgcn_sched_barrier(0)
; template <class Epi, class Sched, bool ALIGN_EPI = false, bool SP2 = false>
; __device__ __forceinline__ void gemm_phase(PG8_LAS unsigned char* lds, const Gemm g, const Sched& S, const Epi& E) {
;     ...
;             const char* a1 = cA + (size_t)(t + 1) * kstep;
;             const char* a2 = last ? nA : cA + (size_t)(t + 2) * kstep; const char* b2 = last ? nB : cB + (size_t)(t + 2) * kstep;
;             const char* a3 = a2 + kstep; const char* b3 = b2 + kstep;
;             if (last && has_next) S.a_ready(nxt);
;             if constexpr (SP2) {
;             PG8_LDB(B0, 0, 0); PG8_LDB(B1, 0, 1); PG8_SCHED; PG8_LDA(At, 0, 0); PG8_STAGE(PG8_SA(1, 1), a1 + hstep, voffA);
;             PG8_WAIT_V(8); PG8_WAIT_L(0); PG8_BAR; PG8_MMA(0, 0, At, B0); PG8_MMA(0, 1, At, B1); PG8_BAR; PG8_SCHED;
;             PG8_LDA(At, 0, 1); PG8_STAGE(PG8_SB(0, 0), b2, voffB); PG8_STAGE(PG8_SB(0, 1), b2 + hstep, voffB); PG8_STAGE(PG8_SA(0, 0), a2, voffA);
;             PG8_WAIT_V(8); PG8_WAIT_L(0); PG8_BAR; PG8_MMA(1, 0, At, B0); PG8_MMA(1, 1, At, B1); PG8_BAR; PG8_SCHED;
;             PG8_LDB(B0, 1, 0); PG8_LDB(B1, 1, 1); PG8_SCHED; PG8_LDA(At, 1, 0); PG8_STAGE(PG8_SA(0, 1), a2 + hstep, voffA);
;             PG8_WAIT_V(8); PG8_WAIT_L(0); PG8_BAR; PG8_MMA(0, 0, At, B0); PG8_MMA(0, 1, At, B1); PG8_BAR; PG8_SCHED;
.LBB0_757:
	ds_read_b128 v[154:157], v149
	ds_read_b128 v[158:161], v149 offset:1024
	ds_read_b128 v[162:165], v149 offset:2048
	ds_read_b128 v[166:169], v149 offset:3072
	ds_read_b128 v[170:173], v150
	ds_read_b128 v[174:177], v150 offset:1024
	ds_read_b128 v[180:183], v150 offset:2048
	ds_read_b128 v[184:187], v150 offset:3072
	s_add_u32 s46, s44, 0x4000
	s_addc_u32 s47, s45, 0
	s_cmp_eq_u32 s70, 60
	s_cselect_b32 s50, s39, s46
	s_cselect_b32 s51, s17, s47
	s_cselect_b32 s48, s41, s68
	s_cselect_b32 s49, s15, s69
	s_add_u32 s46, s50, 0x8000
	s_addc_u32 s47, s51, 0
	s_sub_u32 s46, s44, 0x4000
	s_subb_u32 s47, s45, 0
	s_mov_b32 m0, s57
	s_nop 0
	global_load_lds_dwordx4 v130, s[46:47]
	s_mov_b32 m0, s58
	s_nop 0
	global_load_lds_dwordx4 v134, s[46:47]
	s_add_i32 m0, s26, 0xc000
	ds_read_b128 v[188:191], v151
	ds_read_b128 v[198:201], v151 offset:1024
	ds_read_b128 v[202:205], v151 offset:2048
	ds_read_b128 v[206:209], v151 offset:3072
	ds_read_b128 v[210:213], v151 offset:4096
	ds_read_b128 v[214:217], v151 offset:5120
	ds_read_b128 v[218:221], v151 offset:6144
	ds_read_b128 v[222:225], v151 offset:7168
	global_load_lds_dwordx4 v138, s[44:45]
	s_add_i32 m0, s26, 0xe000
	s_nop 0
	global_load_lds_dwordx4 v140, s[44:45]
	s_waitcnt vmcnt(8)
	s_waitcnt lgkmcnt(0)
	s_barrier
	s_setprio 1
	s_waitcnt lgkmcnt(0)
	v_mfma_f32_16x16x32_bf16 v[126:129], v[154:157], v[188:191], v[126:129]
	v_mfma_f32_16x16x32_bf16 v[126:129], v[158:161], v[198:201], v[126:129]
	v_mfma_f32_16x16x32_bf16 v[110:113], v[154:157], v[202:205], v[110:113]
	v_mfma_f32_16x16x32_bf16 v[110:113], v[158:161], v[206:209], v[110:113]
	v_mfma_f32_16x16x32_bf16 v[94:97], v[154:157], v[210:213], v[94:97]
	v_mfma_f32_16x16x32_bf16 v[94:97], v[158:161], v[214:217], v[94:97]
	v_mfma_f32_16x16x32_bf16 v[78:81], v[154:157], v[218:221], v[78:81]
	v_mfma_f32_16x16x32_bf16 v[78:81], v[158:161], v[222:225], v[78:81]
	v_mfma_f32_16x16x32_bf16 v[74:77], v[162:165], v[218:221], v[74:77]
	v_mfma_f32_16x16x32_bf16 v[74:77], v[166:169], v[222:225], v[74:77]
	v_mfma_f32_16x16x32_bf16 v[90:93], v[162:165], v[210:213], v[90:93]
	v_mfma_f32_16x16x32_bf16 v[90:93], v[166:169], v[214:217], v[90:93]
	v_mfma_f32_16x16x32_bf16 v[106:109], v[162:165], v[202:205], v[106:109]
	v_mfma_f32_16x16x32_bf16 v[106:109], v[166:169], v[206:209], v[106:109]
	v_mfma_f32_16x16x32_bf16 v[122:125], v[162:165], v[188:191], v[122:125]
	v_mfma_f32_16x16x32_bf16 v[122:125], v[166:169], v[198:201], v[122:125]
	s_setprio 0
	s_setprio 1
	v_mfma_f32_16x16x32_bf16 v[118:121], v[170:173], v[188:191], v[118:121]
	v_mfma_f32_16x16x32_bf16 v[118:121], v[174:177], v[198:201], v[118:121]
	v_mfma_f32_16x16x32_bf16 v[102:105], v[170:173], v[202:205], v[102:105]
	v_mfma_f32_16x16x32_bf16 v[102:105], v[174:177], v[206:209], v[102:105]
	v_mfma_f32_16x16x32_bf16 v[86:89], v[170:173], v[210:213], v[86:89]
	v_mfma_f32_16x16x32_bf16 v[86:89], v[174:177], v[214:217], v[86:89]
	v_mfma_f32_16x16x32_bf16 v[70:73], v[170:173], v[218:221], v[70:73]
	v_mfma_f32_16x16x32_bf16 v[70:73], v[174:177], v[222:225], v[70:73]
	v_mfma_f32_16x16x32_bf16 v[66:69], v[180:183], v[218:221], v[66:69]
	v_mfma_f32_16x16x32_bf16 v[66:69], v[184:187], v[222:225], v[66:69]
	v_mfma_f32_16x16x32_bf16 v[82:85], v[180:183], v[210:213], v[82:85]
	v_mfma_f32_16x16x32_bf16 v[82:85], v[184:187], v[214:217], v[82:85]
	v_mfma_f32_16x16x32_bf16 v[98:101], v[180:183], v[202:205], v[98:101]
	v_mfma_f32_16x16x32_bf16 v[98:101], v[184:187], v[206:209], v[98:101]
	v_mfma_f32_16x16x32_bf16 v[114:117], v[180:183], v[188:191], v[114:117]
	v_mfma_f32_16x16x32_bf16 v[114:117], v[184:187], v[198:201], v[114:117]
	s_setprio 0
	s_barrier
	s_add_i32 s71, s59, s3
	s_mov_b32 m0, s71
	ds_read_b128 v[188:191], v151 offset:16384
	ds_read_b128 v[198:201], v151 offset:17408
	ds_read_b128 v[202:205], v151 offset:18432
	ds_read_b128 v[206:209], v151 offset:19456
	ds_read_b128 v[210:213], v151 offset:20480
	ds_read_b128 v[214:217], v151 offset:21504
	ds_read_b128 v[218:221], v151 offset:22528
	ds_read_b128 v[222:225], v151 offset:23552
	global_load_lds_dwordx4 v132, s[48:49]
	s_add_i32 m0, s71, 0x2000
	s_add_u32 s72, s48, 0x4000
	s_addc_u32 s73, s49, 0
	s_add_i32 s71, s61, s3
	global_load_lds_dwordx4 v136, s[48:49]
	s_mov_b32 m0, s71
	s_nop 0
	global_load_lds_dwordx4 v132, s[72:73]
	s_add_i32 m0, s71, 0x2000
	s_nop 0
	global_load_lds_dwordx4 v136, s[72:73]
	s_waitcnt vmcnt(6)
	s_waitcnt lgkmcnt(0)
	s_barrier
	s_setprio 1
	s_waitcnt lgkmcnt(0)
	v_mfma_f32_16x16x32_bf16 v[62:65], v[154:157], v[188:191], v[62:65]
	v_mfma_f32_16x16x32_bf16 v[62:65], v[158:161], v[198:201], v[62:65]
	v_mfma_f32_16x16x32_bf16 v[46:49], v[154:157], v[202:205], v[46:49]
	v_mfma_f32_16x16x32_bf16 v[46:49], v[158:161], v[206:209], v[46:49]
	v_mfma_f32_16x16x32_bf16 v[30:33], v[154:157], v[210:213], v[30:33]
	v_mfma_f32_16x16x32_bf16 v[30:33], v[158:161], v[214:217], v[30:33]
	v_mfma_f32_16x16x32_bf16 v[14:17], v[154:157], v[218:221], v[14:17]
	v_mfma_f32_16x16x32_bf16 v[14:17], v[158:161], v[222:225], v[14:17]
	v_mfma_f32_16x16x32_bf16 v[10:13], v[162:165], v[218:221], v[10:13]
	v_mfma_f32_16x16x32_bf16 v[10:13], v[166:169], v[222:225], v[10:13]
	v_mfma_f32_16x16x32_bf16 v[26:29], v[162:165], v[210:213], v[26:29]
	v_mfma_f32_16x16x32_bf16 v[26:29], v[166:169], v[214:217], v[26:29]
	v_mfma_f32_16x16x32_bf16 v[42:45], v[162:165], v[202:205], v[42:45]
	v_mfma_f32_16x16x32_bf16 v[42:45], v[166:169], v[206:209], v[42:45]
	v_mfma_f32_16x16x32_bf16 v[58:61], v[162:165], v[188:191], v[58:61]
	v_mfma_f32_16x16x32_bf16 v[58:61], v[166:169], v[198:201], v[58:61]
	s_setprio 0
	s_setprio 1
	v_mfma_f32_16x16x32_bf16 v[54:57], v[170:173], v[188:191], v[54:57]
	v_mfma_f32_16x16x32_bf16 v[54:57], v[174:177], v[198:201], v[54:57]
	v_mfma_f32_16x16x32_bf16 v[38:41], v[170:173], v[202:205], v[38:41]
	v_mfma_f32_16x16x32_bf16 v[38:41], v[174:177], v[206:209], v[38:41]
	v_mfma_f32_16x16x32_bf16 v[22:25], v[170:173], v[210:213], v[22:25]
	v_mfma_f32_16x16x32_bf16 v[22:25], v[174:177], v[214:217], v[22:25]
	v_mfma_f32_16x16x32_bf16 v[6:9], v[170:173], v[218:221], v[6:9]
	v_mfma_f32_16x16x32_bf16 v[6:9], v[174:177], v[222:225], v[6:9]
	v_mfma_f32_16x16x32_bf16 v[2:5], v[180:183], v[218:221], v[2:5]
	v_mfma_f32_16x16x32_bf16 v[2:5], v[184:187], v[222:225], v[2:5]
	v_mfma_f32_16x16x32_bf16 v[18:21], v[180:183], v[210:213], v[18:21]
	v_mfma_f32_16x16x32_bf16 v[18:21], v[184:187], v[214:217], v[18:21]
	v_mfma_f32_16x16x32_bf16 v[34:37], v[180:183], v[202:205], v[34:37]
	v_mfma_f32_16x16x32_bf16 v[34:37], v[184:187], v[206:209], v[34:37]
	v_mfma_f32_16x16x32_bf16 v[50:53], v[180:183], v[188:191], v[50:53]
	v_mfma_f32_16x16x32_bf16 v[50:53], v[184:187], v[198:201], v[50:53]
	s_setprio 0
	s_barrier
; #define PG8_STAGE(bufoff, gbase, voff) do { _Pragma("unroll") for (int _i = 0; _i < 2; ++_i) \
;         __builtin_amdgcn_global_load_lds((const unsigned*)((const char*)(gbase) + (voff)[_i]), (PG8_LAS unsigned*)(lds + (bufoff) + ldsw + _i * 8192), 16, 0, 0); } while (0)
; #define PG8_LDA(dst, b, h) do { _Pragma("unroll") for (int m = 0; m < 4; ++m) _Pragma("unroll") for (int k = 0; k < 2; ++k) dst[m][k] = *(const PG8_LAS bf16x8*)(lds + PG8_SA(b, h) + aoff + m * 2048 + k * 1024); } while (0)
; #define PG8_LDB(dst, b, h) do { _Pragma("unroll") for (int n = 0; n < 2; ++n) _Pragma("unroll") for (int k = 0; k < 2; ++k) dst[n][k] = *(const PG8_LAS bf16x8*)(lds + PG8_SB(b, h) + boff + n * 2048 + k * 1024); } while (0)
; #define PG8_MMA(ai, bj, At, Bt) do { __builtin_amdgcn_s_setprio(1); _Pragma("unroll") for (int m = 0; m < 4; ++m) _Pragma("unroll") for (int n = 0; n < 2; ++n) _Pragma("unroll") for (int k = 0; k < 2; ++k) \
;         acc[ai][bj][m][n] = __builtin_amdgcn_mfma_f32_16x16x32_bf16(Bt[n][k], At[m][k], acc[ai][bj][m][n], 0, 0, 0); __builtin_amdgcn_s_setprio(0); } while (0)
; #define PG8_WAIT_V(n) asm volatile("s_waitcnt vmcnt(" #n ")" ::: "memory")
; #define PG8_WAIT_L(n) asm volatile("s_waitcnt lgkmcnt(" #n ")" ::: "memory")
; #define PG8_BAR __builtin_amdgcn_s_barrier()
; #define PG8_SCHED __builtin_amdgcn_sched_barrier(0)
; template <class Epi, class Sched, bool ALIGN_EPI = false, bool SP2 = false>
; __device__ __forceinline__ void gemm_phase(PG8_LAS unsigned char* lds, const Gemm g, const Sched& S, const Epi& E) {
;     ...
;             PG8_LDB(B0, 1, 0); PG8_LDB(B1, 1, 1); PG8_SCHED; PG8_LDA(At, 1, 0); PG8_STAGE(PG8_SA(0, 1), a2 + hstep, voffA);
;             PG8_WAIT_V(8); PG8_WAIT_L(0); PG8_BAR; PG8_MMA(0, 0, At, B0); PG8_MMA(0, 1, At, B1); PG8_BAR; PG8_SCHED;
;             PG8_LDA(At, 1, 1); PG8_STAGE(PG8_SB(1, 0), b3, voffB); PG8_STAGE(PG8_SB(1, 1), b3 + hstep, voffB); PG8_STAGE(PG8_SA(1, 0), a3, voffA);
;             PG8_WAIT_V(8); PG8_WAIT_L(0); PG8_BAR; PG8_MMA(1, 0, At, B0); PG8_MMA(1, 1, At, B1); PG8_BAR; PG8_SCHED;
;     ...
;         if constexpr (ALIGN_EPI) { if (wr == 0) PG8_BAR; }
	s_add_i32 s71, 0, 0x18000
	v_add_u32_e32 v146, s71, v1
	s_add_i32 s72, 0, 0x1c000
	ds_read_b128 v[154:157], v146
	ds_read_b128 v[158:161], v146 offset:1024
	ds_read_b128 v[162:165], v146 offset:2048
	ds_read_b128 v[166:169], v146 offset:3072
	v_add_u32_e32 v146, s72, v1
	ds_read_b128 v[170:173], v146
	ds_read_b128 v[174:177], v146 offset:1024
	ds_read_b128 v[180:183], v146 offset:2048
	ds_read_b128 v[184:187], v146 offset:3072
	s_mov_b32 m0, s26
	s_nop 0
	global_load_lds_dwordx4 v130, s[50:51]
	s_mov_b32 m0, s27
	s_nop 0
	global_load_lds_dwordx4 v134, s[50:51]
	s_add_u32 s50, s50, 0x4000
	s_addc_u32 s51, s51, 0
	s_mov_b32 m0, s28
	ds_read_b128 v[188:191], v151 offset:32768
	ds_read_b128 v[198:201], v151 offset:33792
	ds_read_b128 v[202:205], v151 offset:34816
	ds_read_b128 v[206:209], v151 offset:35840
	ds_read_b128 v[210:213], v151 offset:36864
	ds_read_b128 v[214:217], v151 offset:37888
	ds_read_b128 v[218:221], v151 offset:38912
	ds_read_b128 v[222:225], v151 offset:39936
	global_load_lds_dwordx4 v130, s[50:51]
	s_mov_b32 m0, s29
	s_nop 0
	global_load_lds_dwordx4 v134, s[50:51]
	s_waitcnt vmcnt(8)
	s_waitcnt lgkmcnt(0)
	s_barrier
	s_setprio 1
	s_waitcnt lgkmcnt(0)
	v_mfma_f32_16x16x32_bf16 v[126:129], v[154:157], v[188:191], v[126:129]
	v_mfma_f32_16x16x32_bf16 v[126:129], v[158:161], v[198:201], v[126:129]
	v_mfma_f32_16x16x32_bf16 v[110:113], v[154:157], v[202:205], v[110:113]
	v_mfma_f32_16x16x32_bf16 v[110:113], v[158:161], v[206:209], v[110:113]
	v_mfma_f32_16x16x32_bf16 v[94:97], v[154:157], v[210:213], v[94:97]
	v_mfma_f32_16x16x32_bf16 v[94:97], v[158:161], v[214:217], v[94:97]
	v_mfma_f32_16x16x32_bf16 v[78:81], v[154:157], v[218:221], v[78:81]
	v_mfma_f32_16x16x32_bf16 v[78:81], v[158:161], v[222:225], v[78:81]
	v_mfma_f32_16x16x32_bf16 v[74:77], v[162:165], v[218:221], v[74:77]
	v_mfma_f32_16x16x32_bf16 v[74:77], v[166:169], v[222:225], v[74:77]
	v_mfma_f32_16x16x32_bf16 v[90:93], v[162:165], v[210:213], v[90:93]
	v_mfma_f32_16x16x32_bf16 v[90:93], v[166:169], v[214:217], v[90:93]
	v_mfma_f32_16x16x32_bf16 v[106:109], v[162:165], v[202:205], v[106:109]
	v_mfma_f32_16x16x32_bf16 v[106:109], v[166:169], v[206:209], v[106:109]
	v_mfma_f32_16x16x32_bf16 v[122:125], v[162:165], v[188:191], v[122:125]
	v_mfma_f32_16x16x32_bf16 v[122:125], v[166:169], v[198:201], v[122:125]
	s_setprio 0
	s_setprio 1
	v_mfma_f32_16x16x32_bf16 v[118:121], v[170:173], v[188:191], v[118:121]
	v_mfma_f32_16x16x32_bf16 v[118:121], v[174:177], v[198:201], v[118:121]
	v_mfma_f32_16x16x32_bf16 v[102:105], v[170:173], v[202:205], v[102:105]
	v_mfma_f32_16x16x32_bf16 v[102:105], v[174:177], v[206:209], v[102:105]
	v_mfma_f32_16x16x32_bf16 v[86:89], v[170:173], v[210:213], v[86:89]
	v_mfma_f32_16x16x32_bf16 v[86:89], v[174:177], v[214:217], v[86:89]
	v_mfma_f32_16x16x32_bf16 v[70:73], v[170:173], v[218:221], v[70:73]
	v_mfma_f32_16x16x32_bf16 v[70:73], v[174:177], v[222:225], v[70:73]
	v_mfma_f32_16x16x32_bf16 v[66:69], v[180:183], v[218:221], v[66:69]
	v_mfma_f32_16x16x32_bf16 v[66:69], v[184:187], v[222:225], v[66:69]
	v_mfma_f32_16x16x32_bf16 v[82:85], v[180:183], v[210:213], v[82:85]
	v_mfma_f32_16x16x32_bf16 v[82:85], v[184:187], v[214:217], v[82:85]
	v_mfma_f32_16x16x32_bf16 v[98:101], v[180:183], v[202:205], v[98:101]
	v_mfma_f32_16x16x32_bf16 v[98:101], v[184:187], v[206:209], v[98:101]
	v_mfma_f32_16x16x32_bf16 v[114:117], v[180:183], v[188:191], v[114:117]
	v_mfma_f32_16x16x32_bf16 v[114:117], v[184:187], v[198:201], v[114:117]
	s_setprio 0
	s_barrier
	s_add_u32 s50, s48, 0x8000
	s_addc_u32 s51, s49, 0
	s_add_i32 s71, s71, s3
	s_mov_b32 m0, s71
	ds_read_b128 v[188:191], v151 offset:49152
	ds_read_b128 v[198:201], v151 offset:50176
	ds_read_b128 v[202:205], v151 offset:51200
	ds_read_b128 v[206:209], v151 offset:52224
	ds_read_b128 v[210:213], v151 offset:53248
	ds_read_b128 v[214:217], v151 offset:54272
	ds_read_b128 v[218:221], v151 offset:55296
	ds_read_b128 v[222:225], v151 offset:56320
	global_load_lds_dwordx4 v132, s[50:51]
	s_add_i32 m0, s71, 0x2000
	s_add_u32 s48, s48, 0xc000
	v_lshl_add_u64 v[146:147], s[50:51], 0, v[136:137]
	s_addc_u32 s49, s49, 0
	s_add_i32 s50, s72, s3
	global_load_lds_dwordx4 v[146:147], off
	s_mov_b32 m0, s50
	s_nop 0
	global_load_lds_dwordx4 v132, s[48:49]
	s_add_i32 m0, s50, 0x2000
	s_nop 0
	global_load_lds_dwordx4 v136, s[48:49]
	s_waitcnt vmcnt(6)
	s_waitcnt lgkmcnt(0)
	s_barrier
	s_setprio 1
	s_waitcnt lgkmcnt(0)
	v_mfma_f32_16x16x32_bf16 v[62:65], v[154:157], v[188:191], v[62:65]
	v_mfma_f32_16x16x32_bf16 v[62:65], v[158:161], v[198:201], v[62:65]
	v_mfma_f32_16x16x32_bf16 v[46:49], v[154:157], v[202:205], v[46:49]
	v_mfma_f32_16x16x32_bf16 v[46:49], v[158:161], v[206:209], v[46:49]
	v_mfma_f32_16x16x32_bf16 v[30:33], v[154:157], v[210:213], v[30:33]
	v_mfma_f32_16x16x32_bf16 v[30:33], v[158:161], v[214:217], v[30:33]
	v_mfma_f32_16x16x32_bf16 v[14:17], v[154:157], v[218:221], v[14:17]
	v_mfma_f32_16x16x32_bf16 v[14:17], v[158:161], v[222:225], v[14:17]
	v_mfma_f32_16x16x32_bf16 v[10:13], v[162:165], v[218:221], v[10:13]
	v_mfma_f32_16x16x32_bf16 v[10:13], v[166:169], v[222:225], v[10:13]
	v_mfma_f32_16x16x32_bf16 v[26:29], v[162:165], v[210:213], v[26:29]
	v_mfma_f32_16x16x32_bf16 v[26:29], v[166:169], v[214:217], v[26:29]
	v_mfma_f32_16x16x32_bf16 v[42:45], v[162:165], v[202:205], v[42:45]
	v_mfma_f32_16x16x32_bf16 v[42:45], v[166:169], v[206:209], v[42:45]
	v_mfma_f32_16x16x32_bf16 v[58:61], v[162:165], v[188:191], v[58:61]
	v_mfma_f32_16x16x32_bf16 v[58:61], v[166:169], v[198:201], v[58:61]
	s_setprio 0
	s_setprio 1
	v_mfma_f32_16x16x32_bf16 v[54:57], v[170:173], v[188:191], v[54:57]
	v_mfma_f32_16x16x32_bf16 v[54:57], v[174:177], v[198:201], v[54:57]
	v_mfma_f32_16x16x32_bf16 v[38:41], v[170:173], v[202:205], v[38:41]
	v_mfma_f32_16x16x32_bf16 v[38:41], v[174:177], v[206:209], v[38:41]
	v_mfma_f32_16x16x32_bf16 v[22:25], v[170:173], v[210:213], v[22:25]
	v_mfma_f32_16x16x32_bf16 v[22:25], v[174:177], v[214:217], v[22:25]
	v_mfma_f32_16x16x32_bf16 v[6:9], v[170:173], v[218:221], v[6:9]
	v_mfma_f32_16x16x32_bf16 v[6:9], v[174:177], v[222:225], v[6:9]
	v_mfma_f32_16x16x32_bf16 v[2:5], v[180:183], v[218:221], v[2:5]
	v_mfma_f32_16x16x32_bf16 v[2:5], v[184:187], v[222:225], v[2:5]
	v_mfma_f32_16x16x32_bf16 v[18:21], v[180:183], v[210:213], v[18:21]
	v_mfma_f32_16x16x32_bf16 v[18:21], v[184:187], v[214:217], v[18:21]
	v_mfma_f32_16x16x32_bf16 v[34:37], v[180:183], v[202:205], v[34:37]
	v_mfma_f32_16x16x32_bf16 v[34:37], v[184:187], v[206:209], v[34:37]
	v_mfma_f32_16x16x32_bf16 v[50:53], v[180:183], v[188:191], v[50:53]
	v_mfma_f32_16x16x32_bf16 v[50:53], v[184:187], v[198:201], v[50:53]
	s_setprio 0
	s_barrier
	s_add_i32 s70, s70, 2
	s_add_u32 s44, s44, 0x10000
	s_addc_u32 s45, s45, 0
	s_add_u32 s68, s68, 0x10000
	s_addc_u32 s69, s69, 0
	s_cmp_gt_u32 s70, 61
	s_cbranch_scc0 .LBB0_757
	s_and_b64 vcc, exec, s[12:13]
	s_cbranch_vccz .LBB0_760
	s_barrier

; #define PG8_STAGE(bufoff, gbase, voff) do { _Pragma("unroll") for (int _i = 0; _i < 2; ++_i) \
;         __builtin_amdgcn_global_load_lds((const unsigned*)((const char*)(gbase) + (voff)[_i]), (PG8_LAS unsigned*)(lds + (bufoff) + ldsw + _i * 8192), 16, 0, 0); } while (0)
; #define PG8_LDA(dst, b, h) do { _Pragma("unroll") for (int m = 0; m < 4; ++m) _Pragma("unroll") for (int k = 0; k < 2; ++k) dst[m][k] = *(const PG8_LAS bf16x8*)(lds + PG8_SA(b, h) + aoff + m * 2048 + k * 1024); } while (0)
; #define PG8_LDB(dst, b, h) do { _Pragma("unroll") for (int n = 0; n < 2; ++n) _Pragma("unroll") for (int k = 0; k < 2; ++k) dst[n][k] = *(const PG8_LAS bf16x8*)(lds + PG8_SB(b, h) + boff + n * 2048 + k * 1024); } while (0)
; #define PG8_WAIT_V(n) asm volatile("s_waitcnt vmcnt(" #n ")" ::: "memory")
; #define PG8_WAIT_L(n) asm volatile("s_waitcnt lgkmcnt(" #n ")" ::: "memory")
; #define PG8_BAR __builtin_amdgcn_s_barrier()
; #define PG8_SCHED __builtin_amdgcn_sched_barrier(0)
; template <class Epi, class Sched, bool ALIGN_EPI = false, bool SP2 = false>
; __device__ __forceinline__ void gemm_phase(PG8_LAS unsigned char* lds, const Gemm g, const Sched& S, const Epi& E) {
;     ...
;             const char* a1 = cA + (size_t)(t + 1) * kstep;
;             const char* a2 = last ? nA : cA + (size_t)(t + 2) * kstep; const char* b2 = last ? nB : cB + (size_t)(t + 2) * kstep;
;             const char* a3 = a2 + kstep; const char* b3 = b2 + kstep;
;             if (last && has_next) S.a_ready(nxt);
;             if constexpr (SP2) {
;             PG8_LDB(B0, 0, 0); PG8_LDB(B1, 0, 1); PG8_SCHED; PG8_LDA(At, 0, 0); PG8_STAGE(PG8_SA(1, 1), a1 + hstep, voffA);
;             PG8_WAIT_V(8); PG8_WAIT_L(0); PG8_BAR; PG8_MMA(0, 0, At, B0); PG8_MMA(0, 1, At, B1); PG8_BAR; PG8_SCHED;
;             PG8_LDA(At, 0, 1); PG8_STAGE(PG8_SB(0, 0), b2, voffB); PG8_STAGE(PG8_SB(0, 1), b2 + hstep, voffB); PG8_STAGE(PG8_SA(0, 0), a2, voffA);
;             PG8_WAIT_V(8); PG8_WAIT_L(0); PG8_BAR; PG8_MMA(1, 0, At, B0); PG8_MMA(1, 1, At, B1); PG8_BAR; PG8_SCHED;
;             PG8_LDB(B0, 1, 0); PG8_LDB(B1, 1, 1); PG8_SCHED; PG8_LDA(At, 1, 0); PG8_STAGE(PG8_SA(0, 1), a2 + hstep, voffA);
;             PG8_WAIT_V(8); PG8_WAIT_L(0); PG8_BAR; PG8_MMA(0, 0, At, B0); PG8_MMA(0, 1, At, B1); PG8_BAR; PG8_SCHED;
.LBB0_840:
	ds_read_b128 v[148:151], v153
	ds_read_b128 v[158:161], v153 offset:1024
	ds_read_b128 v[162:165], v153 offset:2048
	ds_read_b128 v[166:169], v153 offset:3072
	ds_read_b128 v[170:173], v154
	ds_read_b128 v[174:177], v154 offset:1024
	ds_read_b128 v[180:183], v154 offset:2048
	ds_read_b128 v[184:187], v154 offset:3072
	s_add_u32 s42, s40, 0x4000
	s_addc_u32 s43, s41, 0
	s_cmp_eq_u32 s69, 60
	s_cselect_b32 s46, s65, s42
	s_cselect_b32 s47, s23, s43
	s_cselect_b32 s44, s66, s67
	s_cselect_b32 s45, s17, s68
	s_add_u32 s42, s46, 0x8000
	s_addc_u32 s43, s47, 0
	s_sub_u32 s42, s40, 0x4000
	s_subb_u32 s43, s41, 0
	s_mov_b32 m0, s50
	s_nop 0
	global_load_lds_dwordx4 v130, s[42:43]
	s_mov_b32 m0, s51
	s_nop 0
	global_load_lds_dwordx4 v134, s[42:43]
	s_add_i32 m0, s28, 0xc000
	ds_read_b128 v[188:191], v155
	ds_read_b128 v[198:201], v155 offset:1024
	ds_read_b128 v[202:205], v155 offset:2048
	ds_read_b128 v[206:209], v155 offset:3072
	ds_read_b128 v[210:213], v155 offset:4096
	ds_read_b128 v[214:217], v155 offset:5120
	ds_read_b128 v[218:221], v155 offset:6144
	ds_read_b128 v[222:225], v155 offset:7168
	global_load_lds_dwordx4 v140, s[40:41]
	s_add_i32 m0, s28, 0xe000
	s_nop 0
	global_load_lds_dwordx4 v142, s[40:41]
	s_waitcnt vmcnt(8)
	s_waitcnt lgkmcnt(0)
	s_barrier
	s_setprio 1
	s_waitcnt lgkmcnt(0)
	v_mfma_f32_16x16x32_bf16 v[126:129], v[148:151], v[188:191], v[126:129]
	v_mfma_f32_16x16x32_bf16 v[126:129], v[158:161], v[198:201], v[126:129]
	v_mfma_f32_16x16x32_bf16 v[110:113], v[148:151], v[202:205], v[110:113]
	v_mfma_f32_16x16x32_bf16 v[110:113], v[158:161], v[206:209], v[110:113]
	v_mfma_f32_16x16x32_bf16 v[94:97], v[148:151], v[210:213], v[94:97]
	v_mfma_f32_16x16x32_bf16 v[94:97], v[158:161], v[214:217], v[94:97]
	v_mfma_f32_16x16x32_bf16 v[78:81], v[148:151], v[218:221], v[78:81]
	v_mfma_f32_16x16x32_bf16 v[78:81], v[158:161], v[222:225], v[78:81]
	v_mfma_f32_16x16x32_bf16 v[74:77], v[162:165], v[218:221], v[74:77]
	v_mfma_f32_16x16x32_bf16 v[74:77], v[166:169], v[222:225], v[74:77]
	v_mfma_f32_16x16x32_bf16 v[90:93], v[162:165], v[210:213], v[90:93]
	v_mfma_f32_16x16x32_bf16 v[90:93], v[166:169], v[214:217], v[90:93]
	v_mfma_f32_16x16x32_bf16 v[106:109], v[162:165], v[202:205], v[106:109]
	v_mfma_f32_16x16x32_bf16 v[106:109], v[166:169], v[206:209], v[106:109]
	v_mfma_f32_16x16x32_bf16 v[122:125], v[162:165], v[188:191], v[122:125]
	v_mfma_f32_16x16x32_bf16 v[122:125], v[166:169], v[198:201], v[122:125]
	s_setprio 0
	s_setprio 1
	v_mfma_f32_16x16x32_bf16 v[118:121], v[170:173], v[188:191], v[118:121]
	v_mfma_f32_16x16x32_bf16 v[118:121], v[174:177], v[198:201], v[118:121]
	v_mfma_f32_16x16x32_bf16 v[102:105], v[170:173], v[202:205], v[102:105]
	v_mfma_f32_16x16x32_bf16 v[102:105], v[174:177], v[206:209], v[102:105]
	v_mfma_f32_16x16x32_bf16 v[86:89], v[170:173], v[210:213], v[86:89]
	v_mfma_f32_16x16x32_bf16 v[86:89], v[174:177], v[214:217], v[86:89]
	v_mfma_f32_16x16x32_bf16 v[70:73], v[170:173], v[218:221], v[70:73]
	v_mfma_f32_16x16x32_bf16 v[70:73], v[174:177], v[222:225], v[70:73]
	v_mfma_f32_16x16x32_bf16 v[66:69], v[180:183], v[218:221], v[66:69]
	v_mfma_f32_16x16x32_bf16 v[66:69], v[184:187], v[222:225], v[66:69]
	v_mfma_f32_16x16x32_bf16 v[82:85], v[180:183], v[210:213], v[82:85]
	v_mfma_f32_16x16x32_bf16 v[82:85], v[184:187], v[214:217], v[82:85]
	v_mfma_f32_16x16x32_bf16 v[98:101], v[180:183], v[202:205], v[98:101]
	v_mfma_f32_16x16x32_bf16 v[98:101], v[184:187], v[206:209], v[98:101]
	v_mfma_f32_16x16x32_bf16 v[114:117], v[180:183], v[188:191], v[114:117]
	v_mfma_f32_16x16x32_bf16 v[114:117], v[184:187], v[198:201], v[114:117]
	s_setprio 0
	s_barrier
	s_add_i32 s70, s56, s3
	s_mov_b32 m0, s70
	ds_read_b128 v[188:191], v155 offset:16384
	ds_read_b128 v[198:201], v155 offset:17408
	ds_read_b128 v[202:205], v155 offset:18432
	ds_read_b128 v[206:209], v155 offset:19456
	ds_read_b128 v[210:213], v155 offset:20480
	ds_read_b128 v[214:217], v155 offset:21504
	ds_read_b128 v[218:221], v155 offset:22528
	ds_read_b128 v[222:225], v155 offset:23552
	global_load_lds_dwordx4 v132, s[44:45]
	s_add_i32 m0, s70, 0x2000
	s_add_u32 s70, s44, 0x4000
	s_addc_u32 s71, s45, 0
	s_add_i32 s72, s57, s3
	global_load_lds_dwordx4 v136, s[44:45]
	s_mov_b32 m0, s72
	s_nop 0
	global_load_lds_dwordx4 v132, s[70:71]
	s_add_i32 m0, s72, 0x2000
	s_nop 0
	global_load_lds_dwordx4 v136, s[70:71]
	s_waitcnt vmcnt(6)
	s_waitcnt lgkmcnt(0)
	s_barrier
	s_setprio 1
	s_waitcnt lgkmcnt(0)
	v_mfma_f32_16x16x32_bf16 v[62:65], v[148:151], v[188:191], v[62:65]
	v_mfma_f32_16x16x32_bf16 v[62:65], v[158:161], v[198:201], v[62:65]
	v_mfma_f32_16x16x32_bf16 v[46:49], v[148:151], v[202:205], v[46:49]
	v_mfma_f32_16x16x32_bf16 v[46:49], v[158:161], v[206:209], v[46:49]
	v_mfma_f32_16x16x32_bf16 v[30:33], v[148:151], v[210:213], v[30:33]
	v_mfma_f32_16x16x32_bf16 v[30:33], v[158:161], v[214:217], v[30:33]
	v_mfma_f32_16x16x32_bf16 v[14:17], v[148:151], v[218:221], v[14:17]
	v_mfma_f32_16x16x32_bf16 v[14:17], v[158:161], v[222:225], v[14:17]
	v_mfma_f32_16x16x32_bf16 v[10:13], v[162:165], v[218:221], v[10:13]
	v_mfma_f32_16x16x32_bf16 v[10:13], v[166:169], v[222:225], v[10:13]
	v_mfma_f32_16x16x32_bf16 v[26:29], v[162:165], v[210:213], v[26:29]
	v_mfma_f32_16x16x32_bf16 v[26:29], v[166:169], v[214:217], v[26:29]
	v_mfma_f32_16x16x32_bf16 v[42:45], v[162:165], v[202:205], v[42:45]
	v_mfma_f32_16x16x32_bf16 v[42:45], v[166:169], v[206:209], v[42:45]
	v_mfma_f32_16x16x32_bf16 v[58:61], v[162:165], v[188:191], v[58:61]
	v_mfma_f32_16x16x32_bf16 v[58:61], v[166:169], v[198:201], v[58:61]
	s_setprio 0
	s_setprio 1
	v_mfma_f32_16x16x32_bf16 v[54:57], v[170:173], v[188:191], v[54:57]
	v_mfma_f32_16x16x32_bf16 v[54:57], v[174:177], v[198:201], v[54:57]
	v_mfma_f32_16x16x32_bf16 v[38:41], v[170:173], v[202:205], v[38:41]
	v_mfma_f32_16x16x32_bf16 v[38:41], v[174:177], v[206:209], v[38:41]
	v_mfma_f32_16x16x32_bf16 v[22:25], v[170:173], v[210:213], v[22:25]
	v_mfma_f32_16x16x32_bf16 v[22:25], v[174:177], v[214:217], v[22:25]
	v_mfma_f32_16x16x32_bf16 v[6:9], v[170:173], v[218:221], v[6:9]
	v_mfma_f32_16x16x32_bf16 v[6:9], v[174:177], v[222:225], v[6:9]
	v_mfma_f32_16x16x32_bf16 v[2:5], v[180:183], v[218:221], v[2:5]
	v_mfma_f32_16x16x32_bf16 v[2:5], v[184:187], v[222:225], v[2:5]
	v_mfma_f32_16x16x32_bf16 v[18:21], v[180:183], v[210:213], v[18:21]
	v_mfma_f32_16x16x32_bf16 v[18:21], v[184:187], v[214:217], v[18:21]
	v_mfma_f32_16x16x32_bf16 v[34:37], v[180:183], v[202:205], v[34:37]
	v_mfma_f32_16x16x32_bf16 v[34:37], v[184:187], v[206:209], v[34:37]
	v_mfma_f32_16x16x32_bf16 v[50:53], v[180:183], v[188:191], v[50:53]
	v_mfma_f32_16x16x32_bf16 v[50:53], v[184:187], v[198:201], v[50:53]
	s_setprio 0
	s_barrier
; #define PG8_STAGE(bufoff, gbase, voff) do { _Pragma("unroll") for (int _i = 0; _i < 2; ++_i) \
;         __builtin_amdgcn_global_load_lds((const unsigned*)((const char*)(gbase) + (voff)[_i]), (PG8_LAS unsigned*)(lds + (bufoff) + ldsw + _i * 8192), 16, 0, 0); } while (0)
; #define PG8_LDA(dst, b, h) do { _Pragma("unroll") for (int m = 0; m < 4; ++m) _Pragma("unroll") for (int k = 0; k < 2; ++k) dst[m][k] = *(const PG8_LAS bf16x8*)(lds + PG8_SA(b, h) + aoff + m * 2048 + k * 1024); } while (0)
; #define PG8_LDB(dst, b, h) do { _Pragma("unroll") for (int n = 0; n < 2; ++n) _Pragma("unroll") for (int k = 0; k < 2; ++k) dst[n][k] = *(const PG8_LAS bf16x8*)(lds + PG8_SB(b, h) + boff + n * 2048 + k * 1024); } while (0)
; #define PG8_MMA(ai, bj, At, Bt) do { __builtin_amdgcn_s_setprio(1); _Pragma("unroll") for (int m = 0; m < 4; ++m) _Pragma("unroll") for (int n = 0; n < 2; ++n) _Pragma("unroll") for (int k = 0; k < 2; ++k) \
;         acc[ai][bj][m][n] = __builtin_amdgcn_mfma_f32_16x16x32_bf16(Bt[n][k], At[m][k], acc[ai][bj][m][n], 0, 0, 0); __builtin_amdgcn_s_setprio(0); } while (0)
; #define PG8_WAIT_V(n) asm volatile("s_waitcnt vmcnt(" #n ")" ::: "memory")
; #define PG8_WAIT_L(n) asm volatile("s_waitcnt lgkmcnt(" #n ")" ::: "memory")
; #define PG8_BAR __builtin_amdgcn_s_barrier()
; #define PG8_SCHED __builtin_amdgcn_sched_barrier(0)
; template <class Epi, class Sched, bool ALIGN_EPI = false, bool SP2 = false>
; __device__ __forceinline__ void gemm_phase(PG8_LAS unsigned char* lds, const Gemm g, const Sched& S, const Epi& E) {
;     ...
;             PG8_LDB(B0, 1, 0); PG8_LDB(B1, 1, 1); PG8_SCHED; PG8_LDA(At, 1, 0); PG8_STAGE(PG8_SA(0, 1), a2 + hstep, voffA);
;             PG8_WAIT_V(8); PG8_WAIT_L(0); PG8_BAR; PG8_MMA(0, 0, At, B0); PG8_MMA(0, 1, At, B1); PG8_BAR; PG8_SCHED;
;             PG8_LDA(At, 1, 1); PG8_STAGE(PG8_SB(1, 0), b3, voffB); PG8_STAGE(PG8_SB(1, 1), b3 + hstep, voffB); PG8_STAGE(PG8_SA(1, 0), a3, voffA);
;             PG8_WAIT_V(8); PG8_WAIT_L(0); PG8_BAR; PG8_MMA(1, 0, At, B0); PG8_MMA(1, 1, At, B1); PG8_BAR; PG8_SCHED;
;     ...
;         if constexpr (ALIGN_EPI) { if (wr == 0) PG8_BAR; }
	s_add_i32 s70, 0, 0x18000
	v_add_u32_e32 v138, s70, v1
	s_add_i32 s71, 0, 0x1c000
	ds_read_b128 v[148:151], v138
	ds_read_b128 v[158:161], v138 offset:1024
	ds_read_b128 v[162:165], v138 offset:2048
	ds_read_b128 v[166:169], v138 offset:3072
	v_add_u32_e32 v138, s71, v1
	ds_read_b128 v[170:173], v138
	ds_read_b128 v[174:177], v138 offset:1024
	ds_read_b128 v[180:183], v138 offset:2048
	ds_read_b128 v[184:187], v138 offset:3072
	s_mov_b32 m0, s28
	s_nop 0
	global_load_lds_dwordx4 v130, s[46:47]
	s_mov_b32 m0, s29
	s_nop 0
	global_load_lds_dwordx4 v134, s[46:47]
	s_add_u32 s46, s46, 0x4000
	s_addc_u32 s47, s47, 0
	s_mov_b32 m0, s30
	ds_read_b128 v[188:191], v155 offset:32768
	ds_read_b128 v[198:201], v155 offset:33792
	ds_read_b128 v[202:205], v155 offset:34816
	ds_read_b128 v[206:209], v155 offset:35840
	ds_read_b128 v[210:213], v155 offset:36864
	ds_read_b128 v[214:217], v155 offset:37888
	ds_read_b128 v[218:221], v155 offset:38912
	ds_read_b128 v[222:225], v155 offset:39936
	global_load_lds_dwordx4 v130, s[46:47]
	s_mov_b32 m0, s31
	s_nop 0
	global_load_lds_dwordx4 v134, s[46:47]
	s_waitcnt vmcnt(8)
	s_waitcnt lgkmcnt(0)
	s_barrier
	s_setprio 1
	s_waitcnt lgkmcnt(0)
	v_mfma_f32_16x16x32_bf16 v[126:129], v[148:151], v[188:191], v[126:129]
	v_mfma_f32_16x16x32_bf16 v[126:129], v[158:161], v[198:201], v[126:129]
	v_mfma_f32_16x16x32_bf16 v[110:113], v[148:151], v[202:205], v[110:113]
	v_mfma_f32_16x16x32_bf16 v[110:113], v[158:161], v[206:209], v[110:113]
	v_mfma_f32_16x16x32_bf16 v[94:97], v[148:151], v[210:213], v[94:97]
	v_mfma_f32_16x16x32_bf16 v[94:97], v[158:161], v[214:217], v[94:97]
	v_mfma_f32_16x16x32_bf16 v[78:81], v[148:151], v[218:221], v[78:81]
	v_mfma_f32_16x16x32_bf16 v[78:81], v[158:161], v[222:225], v[78:81]
	v_mfma_f32_16x16x32_bf16 v[74:77], v[162:165], v[218:221], v[74:77]
	v_mfma_f32_16x16x32_bf16 v[74:77], v[166:169], v[222:225], v[74:77]
	v_mfma_f32_16x16x32_bf16 v[90:93], v[162:165], v[210:213], v[90:93]
	v_mfma_f32_16x16x32_bf16 v[90:93], v[166:169], v[214:217], v[90:93]
	v_mfma_f32_16x16x32_bf16 v[106:109], v[162:165], v[202:205], v[106:109]
	v_mfma_f32_16x16x32_bf16 v[106:109], v[166:169], v[206:209], v[106:109]
	v_mfma_f32_16x16x32_bf16 v[122:125], v[162:165], v[188:191], v[122:125]
	v_mfma_f32_16x16x32_bf16 v[122:125], v[166:169], v[198:201], v[122:125]
	s_setprio 0
	s_setprio 1
	v_mfma_f32_16x16x32_bf16 v[118:121], v[170:173], v[188:191], v[118:121]
	v_mfma_f32_16x16x32_bf16 v[118:121], v[174:177], v[198:201], v[118:121]
	v_mfma_f32_16x16x32_bf16 v[102:105], v[170:173], v[202:205], v[102:105]
	v_mfma_f32_16x16x32_bf16 v[102:105], v[174:177], v[206:209], v[102:105]
	v_mfma_f32_16x16x32_bf16 v[86:89], v[170:173], v[210:213], v[86:89]
	v_mfma_f32_16x16x32_bf16 v[86:89], v[174:177], v[214:217], v[86:89]
	v_mfma_f32_16x16x32_bf16 v[70:73], v[170:173], v[218:221], v[70:73]
	v_mfma_f32_16x16x32_bf16 v[70:73], v[174:177], v[222:225], v[70:73]
	v_mfma_f32_16x16x32_bf16 v[66:69], v[180:183], v[218:221], v[66:69]
	v_mfma_f32_16x16x32_bf16 v[66:69], v[184:187], v[222:225], v[66:69]
	v_mfma_f32_16x16x32_bf16 v[82:85], v[180:183], v[210:213], v[82:85]
	v_mfma_f32_16x16x32_bf16 v[82:85], v[184:187], v[214:217], v[82:85]
	v_mfma_f32_16x16x32_bf16 v[98:101], v[180:183], v[202:205], v[98:101]
	v_mfma_f32_16x16x32_bf16 v[98:101], v[184:187], v[206:209], v[98:101]
	v_mfma_f32_16x16x32_bf16 v[114:117], v[180:183], v[188:191], v[114:117]
	v_mfma_f32_16x16x32_bf16 v[114:117], v[184:187], v[198:201], v[114:117]
	s_setprio 0
	s_barrier
	s_add_u32 s46, s44, 0x8000
	s_addc_u32 s47, s45, 0
	s_add_i32 s70, s70, s3
	s_mov_b32 m0, s70
	ds_read_b128 v[188:191], v155 offset:49152
	ds_read_b128 v[198:201], v155 offset:50176
	ds_read_b128 v[202:205], v155 offset:51200
	ds_read_b128 v[206:209], v155 offset:52224
	ds_read_b128 v[210:213], v155 offset:53248
	ds_read_b128 v[214:217], v155 offset:54272
	ds_read_b128 v[218:221], v155 offset:55296
	ds_read_b128 v[222:225], v155 offset:56320
	global_load_lds_dwordx4 v132, s[46:47]
	s_add_i32 m0, s70, 0x2000
	s_add_u32 s44, s44, 0xc000
	v_lshl_add_u64 v[226:227], s[46:47], 0, v[136:137]
	s_addc_u32 s45, s45, 0
	s_add_i32 s46, s71, s3
	global_load_lds_dwordx4 v[226:227], off
	s_mov_b32 m0, s46
	s_nop 0
	global_load_lds_dwordx4 v132, s[44:45]
	s_add_i32 m0, s46, 0x2000
	s_nop 0
	global_load_lds_dwordx4 v136, s[44:45]
	s_waitcnt vmcnt(6)
	s_waitcnt lgkmcnt(0)
	s_barrier
	s_setprio 1
	s_waitcnt lgkmcnt(0)
	v_mfma_f32_16x16x32_bf16 v[62:65], v[148:151], v[188:191], v[62:65]
	v_mfma_f32_16x16x32_bf16 v[62:65], v[158:161], v[198:201], v[62:65]
	v_mfma_f32_16x16x32_bf16 v[46:49], v[148:151], v[202:205], v[46:49]
	v_mfma_f32_16x16x32_bf16 v[46:49], v[158:161], v[206:209], v[46:49]
	v_mfma_f32_16x16x32_bf16 v[30:33], v[148:151], v[210:213], v[30:33]
	v_mfma_f32_16x16x32_bf16 v[30:33], v[158:161], v[214:217], v[30:33]
	v_mfma_f32_16x16x32_bf16 v[14:17], v[148:151], v[218:221], v[14:17]
	v_mfma_f32_16x16x32_bf16 v[14:17], v[158:161], v[222:225], v[14:17]
	v_mfma_f32_16x16x32_bf16 v[10:13], v[162:165], v[218:221], v[10:13]
	v_mfma_f32_16x16x32_bf16 v[10:13], v[166:169], v[222:225], v[10:13]
	v_mfma_f32_16x16x32_bf16 v[26:29], v[162:165], v[210:213], v[26:29]
	v_mfma_f32_16x16x32_bf16 v[26:29], v[166:169], v[214:217], v[26:29]
	v_mfma_f32_16x16x32_bf16 v[42:45], v[162:165], v[202:205], v[42:45]
	v_mfma_f32_16x16x32_bf16 v[42:45], v[166:169], v[206:209], v[42:45]
	v_mfma_f32_16x16x32_bf16 v[58:61], v[162:165], v[188:191], v[58:61]
	v_mfma_f32_16x16x32_bf16 v[58:61], v[166:169], v[198:201], v[58:61]
	s_setprio 0
	s_setprio 1
	v_mfma_f32_16x16x32_bf16 v[54:57], v[170:173], v[188:191], v[54:57]
	v_mfma_f32_16x16x32_bf16 v[54:57], v[174:177], v[198:201], v[54:57]
	v_mfma_f32_16x16x32_bf16 v[38:41], v[170:173], v[202:205], v[38:41]
	v_mfma_f32_16x16x32_bf16 v[38:41], v[174:177], v[206:209], v[38:41]
	v_mfma_f32_16x16x32_bf16 v[22:25], v[170:173], v[210:213], v[22:25]
	v_mfma_f32_16x16x32_bf16 v[22:25], v[174:177], v[214:217], v[22:25]
	v_mfma_f32_16x16x32_bf16 v[6:9], v[170:173], v[218:221], v[6:9]
	v_mfma_f32_16x16x32_bf16 v[6:9], v[174:177], v[222:225], v[6:9]
	v_mfma_f32_16x16x32_bf16 v[2:5], v[180:183], v[218:221], v[2:5]
	v_mfma_f32_16x16x32_bf16 v[2:5], v[184:187], v[222:225], v[2:5]
	v_mfma_f32_16x16x32_bf16 v[18:21], v[180:183], v[210:213], v[18:21]
	v_mfma_f32_16x16x32_bf16 v[18:21], v[184:187], v[214:217], v[18:21]
	v_mfma_f32_16x16x32_bf16 v[34:37], v[180:183], v[202:205], v[34:37]
	v_mfma_f32_16x16x32_bf16 v[34:37], v[184:187], v[206:209], v[34:37]
	v_mfma_f32_16x16x32_bf16 v[50:53], v[180:183], v[188:191], v[50:53]
	v_mfma_f32_16x16x32_bf16 v[50:53], v[184:187], v[198:201], v[50:53]
	s_setprio 0
	s_barrier
	s_add_i32 s69, s69, 2
	s_add_u32 s40, s40, 0x10000
	s_addc_u32 s41, s41, 0
	s_add_u32 s67, s67, 0x10000
	s_addc_u32 s68, s68, 0
	s_cmp_gt_u32 s69, 61
	s_cbranch_scc0 .LBB0_840
	s_and_b64 vcc, exec, s[14:15]
	s_cbranch_vccz .LBB0_843
	s_barrier

; #define PG8_STAGE(bufoff, gbase, voff) do { _Pragma("unroll") for (int _i = 0; _i < 2; ++_i) \
;         __builtin_amdgcn_global_load_lds((const unsigned*)((const char*)(gbase) + (voff)[_i]), (PG8_LAS unsigned*)(lds + (bufoff) + ldsw + _i * 8192), 16, 0, 0); } while (0)
; #define PG8_LDA(dst, b, h) do { _Pragma("unroll") for (int m = 0; m < 4; ++m) _Pragma("unroll") for (int k = 0; k < 2; ++k) dst[m][k] = *(const PG8_LAS bf16x8*)(lds + PG8_SA(b, h) + aoff + m * 2048 + k * 1024); } while (0)
; #define PG8_LDB(dst, b, h) do { _Pragma("unroll") for (int n = 0; n < 2; ++n) _Pragma("unroll") for (int k = 0; k < 2; ++k) dst[n][k] = *(const PG8_LAS bf16x8*)(lds + PG8_SB(b, h) + boff + n * 2048 + k * 1024); } while (0)
; #define PG8_WAIT_V(n) asm volatile("s_waitcnt vmcnt(" #n ")" ::: "memory")
; #define PG8_WAIT_L(n) asm volatile("s_waitcnt lgkmcnt(" #n ")" ::: "memory")
; #define PG8_BAR __builtin_amdgcn_s_barrier()
; #define PG8_SCHED __builtin_amdgcn_sched_barrier(0)
; template <class Epi, class Sched, bool ALIGN_EPI = false, bool SP2 = false>
; __device__ __forceinline__ void gemm_phase(PG8_LAS unsigned char* lds, const Gemm g, const Sched& S, const Epi& E) {
;     ...
;             const char* a1 = cA + (size_t)(t + 1) * kstep;
;             const char* a2 = last ? nA : cA + (size_t)(t + 2) * kstep; const char* b2 = last ? nB : cB + (size_t)(t + 2) * kstep;
;             const char* a3 = a2 + kstep; const char* b3 = b2 + kstep;
;             if (last && has_next) S.a_ready(nxt);
;             if constexpr (SP2) {
;             PG8_LDB(B0, 0, 0); PG8_LDB(B1, 0, 1); PG8_SCHED; PG8_LDA(At, 0, 0); PG8_STAGE(PG8_SA(1, 1), a1 + hstep, voffA);
;             PG8_WAIT_V(8); PG8_WAIT_L(0); PG8_BAR; PG8_MMA(0, 0, At, B0); PG8_MMA(0, 1, At, B1); PG8_BAR; PG8_SCHED;
;             PG8_LDA(At, 0, 1); PG8_STAGE(PG8_SB(0, 0), b2, voffB); PG8_STAGE(PG8_SB(0, 1), b2 + hstep, voffB); PG8_STAGE(PG8_SA(0, 0), a2, voffA);
;             PG8_WAIT_V(8); PG8_WAIT_L(0); PG8_BAR; PG8_MMA(1, 0, At, B0); PG8_MMA(1, 1, At, B1); PG8_BAR; PG8_SCHED;
;             PG8_LDB(B0, 1, 0); PG8_LDB(B1, 1, 1); PG8_SCHED; PG8_LDA(At, 1, 0); PG8_STAGE(PG8_SA(0, 1), a2 + hstep, voffA);
;             PG8_WAIT_V(8); PG8_WAIT_L(0); PG8_BAR; PG8_MMA(0, 0, At, B0); PG8_MMA(0, 1, At, B1); PG8_BAR; PG8_SCHED;
.LBB0_939:
	s_or_b32 s24, s59, 1
	s_lshl_b64 s[62:63], s[24:25], 15
	s_add_i32 s24, s59, 2
	ds_read_b128 v[156:159], v193
	ds_read_b128 v[160:163], v193 offset:1024
	ds_read_b128 v[196:199], v193 offset:2048
	ds_read_b128 v[200:203], v193 offset:3072
	ds_read_b128 v[204:207], v194
	ds_read_b128 v[208:211], v194 offset:1024
	ds_read_b128 v[212:215], v194 offset:2048
	ds_read_b128 v[216:219], v194 offset:3072
	s_lshl_b64 s[8:9], s[24:25], 15
	s_add_u32 s44, s6, s8
	s_addc_u32 s45, s7, s9
	s_cmpk_eq_i32 s59, 0xaa
	s_cselect_b32 s46, s58, s44
	s_cselect_b32 s47, s56, s45
	s_cselect_b32 s44, 0, s8
	s_cselect_b32 s45, 0, s9
	s_add_u32 s8, s46, 0x8000
	s_addc_u32 s9, s47, 0
	s_add_u32 s44, s14, s44
	s_addc_u32 s45, s15, s45
	s_add_u32 s62, s6, s62
	s_addc_u32 s63, s7, s63
	s_add_u32 s62, s62, 0x4000
	s_addc_u32 s63, s63, 0
	s_sub_u32 s8, s62, 0x4000
	s_subb_u32 s9, s63, 0
	s_mov_b32 m0, s51
	s_nop 0
	global_load_lds_dwordx4 v130, s[8:9]
	s_mov_b32 m0, s57
	s_nop 0
	global_load_lds_dwordx4 v134, s[8:9]
	s_add_i32 m0, s30, 0xc000
	ds_read_b128 v[220:223], v186
	ds_read_b128 v[224:227], v186 offset:1024
	ds_read_b128 v[228:231], v186 offset:2048
	ds_read_b128 v[232:235], v186 offset:3072
	ds_read_b128 v[236:239], v186 offset:4096
	ds_read_b128 v[240:243], v186 offset:5120
	ds_read_b128 v[244:247], v186 offset:6144
	ds_read_b128 v[248:251], v186 offset:7168
	global_load_lds_dwordx4 v130, s[62:63]
	s_add_i32 m0, s30, 0xe000
	s_nop 0
	global_load_lds_dwordx4 v134, s[62:63]
	s_waitcnt vmcnt(8)
	s_waitcnt lgkmcnt(0)
	s_barrier
	s_setprio 1
	s_waitcnt lgkmcnt(0)
	v_mfma_f32_16x16x32_bf16 v[126:129], v[156:159], v[220:223], v[126:129]
	v_mfma_f32_16x16x32_bf16 v[126:129], v[160:163], v[224:227], v[126:129]
	v_mfma_f32_16x16x32_bf16 v[110:113], v[156:159], v[228:231], v[110:113]
	v_mfma_f32_16x16x32_bf16 v[110:113], v[160:163], v[232:235], v[110:113]
	v_mfma_f32_16x16x32_bf16 v[94:97], v[156:159], v[236:239], v[94:97]
	v_mfma_f32_16x16x32_bf16 v[94:97], v[160:163], v[240:243], v[94:97]
	v_mfma_f32_16x16x32_bf16 v[78:81], v[156:159], v[244:247], v[78:81]
	v_mfma_f32_16x16x32_bf16 v[78:81], v[160:163], v[248:251], v[78:81]
	v_mfma_f32_16x16x32_bf16 v[74:77], v[196:199], v[244:247], v[74:77]
	v_mfma_f32_16x16x32_bf16 v[74:77], v[200:203], v[248:251], v[74:77]
	v_mfma_f32_16x16x32_bf16 v[90:93], v[196:199], v[236:239], v[90:93]
	v_mfma_f32_16x16x32_bf16 v[90:93], v[200:203], v[240:243], v[90:93]
	v_mfma_f32_16x16x32_bf16 v[106:109], v[196:199], v[228:231], v[106:109]
	v_mfma_f32_16x16x32_bf16 v[106:109], v[200:203], v[232:235], v[106:109]
	v_mfma_f32_16x16x32_bf16 v[122:125], v[196:199], v[220:223], v[122:125]
	v_mfma_f32_16x16x32_bf16 v[122:125], v[200:203], v[224:227], v[122:125]
	s_setprio 0
	s_setprio 1
	v_mfma_f32_16x16x32_bf16 v[118:121], v[204:207], v[220:223], v[118:121]
	v_mfma_f32_16x16x32_bf16 v[118:121], v[208:211], v[224:227], v[118:121]
	v_mfma_f32_16x16x32_bf16 v[102:105], v[204:207], v[228:231], v[102:105]
	v_mfma_f32_16x16x32_bf16 v[102:105], v[208:211], v[232:235], v[102:105]
	v_mfma_f32_16x16x32_bf16 v[86:89], v[204:207], v[236:239], v[86:89]
	v_mfma_f32_16x16x32_bf16 v[86:89], v[208:211], v[240:243], v[86:89]
	v_mfma_f32_16x16x32_bf16 v[70:73], v[204:207], v[244:247], v[70:73]
	v_mfma_f32_16x16x32_bf16 v[70:73], v[208:211], v[248:251], v[70:73]
	v_mfma_f32_16x16x32_bf16 v[66:69], v[212:215], v[244:247], v[66:69]
	v_mfma_f32_16x16x32_bf16 v[66:69], v[216:219], v[248:251], v[66:69]
	v_mfma_f32_16x16x32_bf16 v[82:85], v[212:215], v[236:239], v[82:85]
	v_mfma_f32_16x16x32_bf16 v[82:85], v[216:219], v[240:243], v[82:85]
	v_mfma_f32_16x16x32_bf16 v[98:101], v[212:215], v[228:231], v[98:101]
	v_mfma_f32_16x16x32_bf16 v[98:101], v[216:219], v[232:235], v[98:101]
	v_mfma_f32_16x16x32_bf16 v[114:117], v[212:215], v[220:223], v[114:117]
	v_mfma_f32_16x16x32_bf16 v[114:117], v[216:219], v[224:227], v[114:117]
	s_setprio 0
	s_barrier
	s_add_i32 s62, s67, s29
	s_mov_b32 m0, s62
	ds_read_b128 v[220:223], v186 offset:16384
	ds_read_b128 v[224:227], v186 offset:17408
	ds_read_b128 v[228:231], v186 offset:18432
	ds_read_b128 v[232:235], v186 offset:19456
	ds_read_b128 v[236:239], v186 offset:20480
	ds_read_b128 v[240:243], v186 offset:21504
	ds_read_b128 v[244:247], v186 offset:22528
	ds_read_b128 v[248:251], v186 offset:23552
	global_load_lds_dwordx4 v132, s[44:45]
	s_add_i32 m0, s62, 0x2000
	s_add_u32 s62, s44, 0x4000
	s_addc_u32 s63, s45, 0
	s_add_i32 s72, s68, s29
	global_load_lds_dwordx4 v136, s[44:45]
	s_mov_b32 m0, s72
	s_nop 0
	global_load_lds_dwordx4 v132, s[62:63]
	s_add_i32 m0, s72, 0x2000
	s_nop 0
	global_load_lds_dwordx4 v136, s[62:63]
	s_waitcnt vmcnt(6)
	s_waitcnt lgkmcnt(0)
	s_barrier
; #define PG8_STAGE(bufoff, gbase, voff) do { _Pragma("unroll") for (int _i = 0; _i < 2; ++_i) \
;         __builtin_amdgcn_global_load_lds((const unsigned*)((const char*)(gbase) + (voff)[_i]), (PG8_LAS unsigned*)(lds + (bufoff) + ldsw + _i * 8192), 16, 0, 0); } while (0)
; #define PG8_LDA(dst, b, h) do { _Pragma("unroll") for (int m = 0; m < 4; ++m) _Pragma("unroll") for (int k = 0; k < 2; ++k) dst[m][k] = *(const PG8_LAS bf16x8*)(lds + PG8_SA(b, h) + aoff + m * 2048 + k * 1024); } while (0)
; #define PG8_LDB(dst, b, h) do { _Pragma("unroll") for (int n = 0; n < 2; ++n) _Pragma("unroll") for (int k = 0; k < 2; ++k) dst[n][k] = *(const PG8_LAS bf16x8*)(lds + PG8_SB(b, h) + boff + n * 2048 + k * 1024); } while (0)
; #define PG8_MMA(ai, bj, At, Bt) do { __builtin_amdgcn_s_setprio(1); _Pragma("unroll") for (int m = 0; m < 4; ++m) _Pragma("unroll") for (int n = 0; n < 2; ++n) _Pragma("unroll") for (int k = 0; k < 2; ++k) \
;         acc[ai][bj][m][n] = __builtin_amdgcn_mfma_f32_16x16x32_bf16(Bt[n][k], At[m][k], acc[ai][bj][m][n], 0, 0, 0); __builtin_amdgcn_s_setprio(0); } while (0)
; #define PG8_WAIT_V(n) asm volatile("s_waitcnt vmcnt(" #n ")" ::: "memory")
; #define PG8_WAIT_L(n) asm volatile("s_waitcnt lgkmcnt(" #n ")" ::: "memory")
; #define PG8_BAR __builtin_amdgcn_s_barrier()
; #define PG8_SCHED __builtin_amdgcn_sched_barrier(0)
; template <class Epi, class Sched, bool ALIGN_EPI = false, bool SP2 = false>
; __device__ __forceinline__ void gemm_phase(PG8_LAS unsigned char* lds, const Gemm g, const Sched& S, const Epi& E) {
;     ...
;             PG8_WAIT_V(8); PG8_WAIT_L(0); PG8_BAR; PG8_MMA(1, 0, At, B0); PG8_MMA(1, 1, At, B1); PG8_BAR; PG8_SCHED;
;             PG8_LDB(B0, 1, 0); PG8_LDB(B1, 1, 1); PG8_SCHED; PG8_LDA(At, 1, 0); PG8_STAGE(PG8_SA(0, 1), a2 + hstep, voffA);
;             PG8_WAIT_V(8); PG8_WAIT_L(0); PG8_BAR; PG8_MMA(0, 0, At, B0); PG8_MMA(0, 1, At, B1); PG8_BAR; PG8_SCHED;
	s_setprio 1
	s_waitcnt lgkmcnt(0)
	v_mfma_f32_16x16x32_bf16 v[62:65], v[156:159], v[220:223], v[62:65]
	v_mfma_f32_16x16x32_bf16 v[62:65], v[160:163], v[224:227], v[62:65]
	v_mfma_f32_16x16x32_bf16 v[46:49], v[156:159], v[228:231], v[46:49]
	v_mfma_f32_16x16x32_bf16 v[46:49], v[160:163], v[232:235], v[46:49]
	v_mfma_f32_16x16x32_bf16 v[30:33], v[156:159], v[236:239], v[30:33]
	v_mfma_f32_16x16x32_bf16 v[30:33], v[160:163], v[240:243], v[30:33]
	v_mfma_f32_16x16x32_bf16 v[14:17], v[156:159], v[244:247], v[14:17]
	v_mfma_f32_16x16x32_bf16 v[14:17], v[160:163], v[248:251], v[14:17]
	v_mfma_f32_16x16x32_bf16 v[10:13], v[196:199], v[244:247], v[10:13]
	v_mfma_f32_16x16x32_bf16 v[10:13], v[200:203], v[248:251], v[10:13]
	v_mfma_f32_16x16x32_bf16 v[26:29], v[196:199], v[236:239], v[26:29]
	v_mfma_f32_16x16x32_bf16 v[26:29], v[200:203], v[240:243], v[26:29]
	v_mfma_f32_16x16x32_bf16 v[42:45], v[196:199], v[228:231], v[42:45]
	v_mfma_f32_16x16x32_bf16 v[42:45], v[200:203], v[232:235], v[42:45]
	v_mfma_f32_16x16x32_bf16 v[58:61], v[196:199], v[220:223], v[58:61]
	v_mfma_f32_16x16x32_bf16 v[58:61], v[200:203], v[224:227], v[58:61]
	s_setprio 0
	s_setprio 1
	v_mfma_f32_16x16x32_bf16 v[54:57], v[204:207], v[220:223], v[54:57]
	v_mfma_f32_16x16x32_bf16 v[54:57], v[208:211], v[224:227], v[54:57]
	v_mfma_f32_16x16x32_bf16 v[38:41], v[204:207], v[228:231], v[38:41]
	v_mfma_f32_16x16x32_bf16 v[38:41], v[208:211], v[232:235], v[38:41]
	v_mfma_f32_16x16x32_bf16 v[22:25], v[204:207], v[236:239], v[22:25]
	v_mfma_f32_16x16x32_bf16 v[22:25], v[208:211], v[240:243], v[22:25]
	v_mfma_f32_16x16x32_bf16 v[6:9], v[204:207], v[244:247], v[6:9]
	v_mfma_f32_16x16x32_bf16 v[6:9], v[208:211], v[248:251], v[6:9]
	v_mfma_f32_16x16x32_bf16 v[2:5], v[212:215], v[244:247], v[2:5]
	v_mfma_f32_16x16x32_bf16 v[2:5], v[216:219], v[248:251], v[2:5]
	v_mfma_f32_16x16x32_bf16 v[18:21], v[212:215], v[236:239], v[18:21]
	v_mfma_f32_16x16x32_bf16 v[18:21], v[216:219], v[240:243], v[18:21]
	v_mfma_f32_16x16x32_bf16 v[34:37], v[212:215], v[228:231], v[34:37]
	v_mfma_f32_16x16x32_bf16 v[34:37], v[216:219], v[232:235], v[34:37]
	v_mfma_f32_16x16x32_bf16 v[50:53], v[212:215], v[220:223], v[50:53]
	v_mfma_f32_16x16x32_bf16 v[50:53], v[216:219], v[224:227], v[50:53]
	s_setprio 0
	s_barrier
	s_add_i32 s62, 0, 0x18000
	v_add_u32_e32 v145, s62, v166
	s_add_i32 s63, 0, 0x1c000
	ds_read_b128 v[156:159], v145
	ds_read_b128 v[160:163], v145 offset:1024
	ds_read_b128 v[196:199], v145 offset:2048
	ds_read_b128 v[200:203], v145 offset:3072
	v_add_u32_e32 v145, s63, v166
	ds_read_b128 v[204:207], v145
	ds_read_b128 v[208:211], v145 offset:1024
	ds_read_b128 v[212:215], v145 offset:2048
	ds_read_b128 v[216:219], v145 offset:3072
	s_mov_b32 m0, s30
	s_nop 0
	global_load_lds_dwordx4 v130, s[46:47]
	s_mov_b32 m0, s31
	s_nop 0
	global_load_lds_dwordx4 v134, s[46:47]
	s_add_u32 s46, s46, 0x4000
	s_addc_u32 s47, s47, 0
	s_mov_b32 m0, s35
	ds_read_b128 v[220:223], v186 offset:32768
	ds_read_b128 v[224:227], v186 offset:33792
	ds_read_b128 v[228:231], v186 offset:34816
	ds_read_b128 v[232:235], v186 offset:35840
	ds_read_b128 v[236:239], v186 offset:36864
	ds_read_b128 v[240:243], v186 offset:37888
	ds_read_b128 v[244:247], v186 offset:38912
	ds_read_b128 v[248:251], v186 offset:39936
	global_load_lds_dwordx4 v130, s[46:47]
	s_mov_b32 m0, s48
	s_nop 0
	global_load_lds_dwordx4 v134, s[46:47]
	s_waitcnt vmcnt(8)
	s_waitcnt lgkmcnt(0)
	s_barrier
; #define PG8_STAGE(bufoff, gbase, voff) do { _Pragma("unroll") for (int _i = 0; _i < 2; ++_i) \
;         __builtin_amdgcn_global_load_lds((const unsigned*)((const char*)(gbase) + (voff)[_i]), (PG8_LAS unsigned*)(lds + (bufoff) + ldsw + _i * 8192), 16, 0, 0); } while (0)
; #define PG8_LDA(dst, b, h) do { _Pragma("unroll") for (int m = 0; m < 4; ++m) _Pragma("unroll") for (int k = 0; k < 2; ++k) dst[m][k] = *(const PG8_LAS bf16x8*)(lds + PG8_SA(b, h) + aoff + m * 2048 + k * 1024); } while (0)
; #define PG8_MMA(ai, bj, At, Bt) do { __builtin_amdgcn_s_setprio(1); _Pragma("unroll") for (int m = 0; m < 4; ++m) _Pragma("unroll") for (int n = 0; n < 2; ++n) _Pragma("unroll") for (int k = 0; k < 2; ++k) \
;         acc[ai][bj][m][n] = __builtin_amdgcn_mfma_f32_16x16x32_bf16(Bt[n][k], At[m][k], acc[ai][bj][m][n], 0, 0, 0); __builtin_amdgcn_s_setprio(0); } while (0)
; #define PG8_WAIT_V(n) asm volatile("s_waitcnt vmcnt(" #n ")" ::: "memory")
; #define PG8_WAIT_L(n) asm volatile("s_waitcnt lgkmcnt(" #n ")" ::: "memory")
; #define PG8_BAR __builtin_amdgcn_s_barrier()
; #define PG8_SCHED __builtin_amdgcn_sched_barrier(0)
; template <class Epi, class Sched, bool ALIGN_EPI = false, bool SP2 = false>
; __device__ __forceinline__ void gemm_phase(PG8_LAS unsigned char* lds, const Gemm g, const Sched& S, const Epi& E) {
;     ...
;             PG8_WAIT_V(8); PG8_WAIT_L(0); PG8_BAR; PG8_MMA(0, 0, At, B0); PG8_MMA(0, 1, At, B1); PG8_BAR; PG8_SCHED;
;             PG8_LDA(At, 1, 1); PG8_STAGE(PG8_SB(1, 0), b3, voffB); PG8_STAGE(PG8_SB(1, 1), b3 + hstep, voffB); PG8_STAGE(PG8_SA(1, 0), a3, voffA);
;             PG8_WAIT_V(8); PG8_WAIT_L(0); PG8_BAR; PG8_MMA(1, 0, At, B0); PG8_MMA(1, 1, At, B1); PG8_BAR; PG8_SCHED;
;     ...
;         if constexpr (ALIGN_EPI) { if (wr == 0) PG8_BAR; }
	s_setprio 1
	s_waitcnt lgkmcnt(0)
	v_mfma_f32_16x16x32_bf16 v[126:129], v[156:159], v[220:223], v[126:129]
	v_mfma_f32_16x16x32_bf16 v[126:129], v[160:163], v[224:227], v[126:129]
	v_mfma_f32_16x16x32_bf16 v[110:113], v[156:159], v[228:231], v[110:113]
	v_mfma_f32_16x16x32_bf16 v[110:113], v[160:163], v[232:235], v[110:113]
	v_mfma_f32_16x16x32_bf16 v[94:97], v[156:159], v[236:239], v[94:97]
	v_mfma_f32_16x16x32_bf16 v[94:97], v[160:163], v[240:243], v[94:97]
	v_mfma_f32_16x16x32_bf16 v[78:81], v[156:159], v[244:247], v[78:81]
	v_mfma_f32_16x16x32_bf16 v[78:81], v[160:163], v[248:251], v[78:81]
	v_mfma_f32_16x16x32_bf16 v[74:77], v[196:199], v[244:247], v[74:77]
	v_mfma_f32_16x16x32_bf16 v[74:77], v[200:203], v[248:251], v[74:77]
	v_mfma_f32_16x16x32_bf16 v[90:93], v[196:199], v[236:239], v[90:93]
	v_mfma_f32_16x16x32_bf16 v[90:93], v[200:203], v[240:243], v[90:93]
	v_mfma_f32_16x16x32_bf16 v[106:109], v[196:199], v[228:231], v[106:109]
	v_mfma_f32_16x16x32_bf16 v[106:109], v[200:203], v[232:235], v[106:109]
	v_mfma_f32_16x16x32_bf16 v[122:125], v[196:199], v[220:223], v[122:125]
	v_mfma_f32_16x16x32_bf16 v[122:125], v[200:203], v[224:227], v[122:125]
	s_setprio 0
	s_setprio 1
	v_mfma_f32_16x16x32_bf16 v[118:121], v[204:207], v[220:223], v[118:121]
	v_mfma_f32_16x16x32_bf16 v[118:121], v[208:211], v[224:227], v[118:121]
	v_mfma_f32_16x16x32_bf16 v[102:105], v[204:207], v[228:231], v[102:105]
	v_mfma_f32_16x16x32_bf16 v[102:105], v[208:211], v[232:235], v[102:105]
	v_mfma_f32_16x16x32_bf16 v[86:89], v[204:207], v[236:239], v[86:89]
	v_mfma_f32_16x16x32_bf16 v[86:89], v[208:211], v[240:243], v[86:89]
	v_mfma_f32_16x16x32_bf16 v[70:73], v[204:207], v[244:247], v[70:73]
	v_mfma_f32_16x16x32_bf16 v[70:73], v[208:211], v[248:251], v[70:73]
	v_mfma_f32_16x16x32_bf16 v[66:69], v[212:215], v[244:247], v[66:69]
	v_mfma_f32_16x16x32_bf16 v[66:69], v[216:219], v[248:251], v[66:69]
	v_mfma_f32_16x16x32_bf16 v[82:85], v[212:215], v[236:239], v[82:85]
	v_mfma_f32_16x16x32_bf16 v[82:85], v[216:219], v[240:243], v[82:85]
	v_mfma_f32_16x16x32_bf16 v[98:101], v[212:215], v[228:231], v[98:101]
	v_mfma_f32_16x16x32_bf16 v[98:101], v[216:219], v[232:235], v[98:101]
	v_mfma_f32_16x16x32_bf16 v[114:117], v[212:215], v[220:223], v[114:117]
	v_mfma_f32_16x16x32_bf16 v[114:117], v[216:219], v[224:227], v[114:117]
	s_setprio 0
	s_barrier
	s_add_u32 s46, s44, 0x8000
	s_addc_u32 s47, s45, 0
	s_add_i32 s62, s62, s29
	s_mov_b32 m0, s62
	ds_read_b128 v[220:223], v186 offset:49152
	ds_read_b128 v[224:227], v186 offset:50176
	ds_read_b128 v[228:231], v186 offset:51200
	ds_read_b128 v[232:235], v186 offset:52224
	ds_read_b128 v[236:239], v186 offset:53248
	ds_read_b128 v[240:243], v186 offset:54272
	ds_read_b128 v[244:247], v186 offset:55296
	ds_read_b128 v[248:251], v186 offset:56320
	global_load_lds_dwordx4 v132, s[46:47]
	s_add_i32 m0, s62, 0x2000
	s_add_u32 s44, s44, 0xc000
	v_lshl_add_u64 v[164:165], s[46:47], 0, v[136:137]
	s_addc_u32 s45, s45, 0
	s_add_i32 s46, s63, s29
	global_load_lds_dwordx4 v[164:165], off
	s_mov_b32 m0, s46
	s_nop 0
	global_load_lds_dwordx4 v132, s[44:45]
	s_add_i32 m0, s46, 0x2000
	s_nop 0
	global_load_lds_dwordx4 v136, s[44:45]
	s_waitcnt vmcnt(6)
	s_waitcnt lgkmcnt(0)
	s_barrier
	s_setprio 1
	s_waitcnt lgkmcnt(0)
	v_mfma_f32_16x16x32_bf16 v[62:65], v[156:159], v[220:223], v[62:65]
	v_mfma_f32_16x16x32_bf16 v[62:65], v[160:163], v[224:227], v[62:65]
	v_mfma_f32_16x16x32_bf16 v[46:49], v[156:159], v[228:231], v[46:49]
	v_mfma_f32_16x16x32_bf16 v[46:49], v[160:163], v[232:235], v[46:49]
	v_mfma_f32_16x16x32_bf16 v[30:33], v[156:159], v[236:239], v[30:33]
	v_mfma_f32_16x16x32_bf16 v[30:33], v[160:163], v[240:243], v[30:33]
	v_mfma_f32_16x16x32_bf16 v[14:17], v[156:159], v[244:247], v[14:17]
	v_mfma_f32_16x16x32_bf16 v[14:17], v[160:163], v[248:251], v[14:17]
	v_mfma_f32_16x16x32_bf16 v[10:13], v[196:199], v[244:247], v[10:13]
	v_mfma_f32_16x16x32_bf16 v[10:13], v[200:203], v[248:251], v[10:13]
	v_mfma_f32_16x16x32_bf16 v[26:29], v[196:199], v[236:239], v[26:29]
	v_mfma_f32_16x16x32_bf16 v[26:29], v[200:203], v[240:243], v[26:29]
	v_mfma_f32_16x16x32_bf16 v[42:45], v[196:199], v[228:231], v[42:45]
	v_mfma_f32_16x16x32_bf16 v[42:45], v[200:203], v[232:235], v[42:45]
	v_mfma_f32_16x16x32_bf16 v[58:61], v[196:199], v[220:223], v[58:61]
	v_mfma_f32_16x16x32_bf16 v[58:61], v[200:203], v[224:227], v[58:61]
	s_setprio 0
	s_setprio 1
	v_mfma_f32_16x16x32_bf16 v[54:57], v[204:207], v[220:223], v[54:57]
	v_mfma_f32_16x16x32_bf16 v[54:57], v[208:211], v[224:227], v[54:57]
	v_mfma_f32_16x16x32_bf16 v[38:41], v[204:207], v[228:231], v[38:41]
	v_mfma_f32_16x16x32_bf16 v[38:41], v[208:211], v[232:235], v[38:41]
	v_mfma_f32_16x16x32_bf16 v[22:25], v[204:207], v[236:239], v[22:25]
	v_mfma_f32_16x16x32_bf16 v[22:25], v[208:211], v[240:243], v[22:25]
	v_mfma_f32_16x16x32_bf16 v[6:9], v[204:207], v[244:247], v[6:9]
	v_mfma_f32_16x16x32_bf16 v[6:9], v[208:211], v[248:251], v[6:9]
	v_mfma_f32_16x16x32_bf16 v[2:5], v[212:215], v[244:247], v[2:5]
	v_mfma_f32_16x16x32_bf16 v[2:5], v[216:219], v[248:251], v[2:5]
	v_mfma_f32_16x16x32_bf16 v[18:21], v[212:215], v[236:239], v[18:21]
	v_mfma_f32_16x16x32_bf16 v[18:21], v[216:219], v[240:243], v[18:21]
	v_mfma_f32_16x16x32_bf16 v[34:37], v[212:215], v[228:231], v[34:37]
	v_mfma_f32_16x16x32_bf16 v[34:37], v[216:219], v[232:235], v[34:37]
	v_mfma_f32_16x16x32_bf16 v[50:53], v[212:215], v[220:223], v[50:53]
	v_mfma_f32_16x16x32_bf16 v[50:53], v[216:219], v[224:227], v[50:53]
	s_setprio 0
	s_barrier
	s_cmpk_gt_u32 s59, 0xa9
	s_mov_b32 s59, s24
	s_cbranch_scc0 .LBB0_939
	s_and_b64 vcc, exec, s[38:39]
	s_cbranch_vccz .LBB0_942
	s_barrier
